# GEMM K-loops: first trip peeled (accumulator zeroing removed via inline-0 SrcC) and first two vmcnt waits of later units relaxed past the epilogue stores; plus earlier scan/B2-epilogue edits; bit-iden
# speedup vs baseline: 1.0023x; 1.0023x over previous
.LBB0_163:
	s_or_b64 exec, exec, s[0:1]
	v_readlane_b32 s4, v254, 2
	v_readlane_b32 s6, v254, 4
	v_readlane_b32 s7, v254, 5
	s_add_u32 s0, s6, 0xd54000
	v_readlane_b32 s5, v254, 3
	v_writelane_b32 v254, s0, 19
	s_addc_u32 s0, s7, 0
	v_writelane_b32 v254, s0, 20
	s_add_u32 s0, s6, 0x1d54000
	s_addc_u32 s1, s7, 0
	v_writelane_b32 v254, s0, 21
	s_mov_b32 s93, 0
	v_writelane_b32 v255, 0, 49
	v_mov_b32_e32 v191, 0
	v_writelane_b32 v254, s1, 22
	s_add_u32 s0, s6, 0x14054000
	s_addc_u32 s1, s7, 0
	s_add_u32 s42, s6, 0x2b4000
	v_writelane_b32 v254, s0, 23
	s_addc_u32 s43, s7, 0
	v_mov_b32_e32 v228, 1
	v_writelane_b32 v254, s1, 24
	s_add_u32 s0, s6, 0x2b0000
	s_addc_u32 s1, s7, 0
	v_writelane_b32 v254, s0, 25
	v_mov_b32_e32 v229, 0x358637bd
	v_mov_b32_e32 v237, 0x3db504f3
	v_writelane_b32 v254, s1, 26
	s_add_u32 s0, s6, 0x2b2000
	s_addc_u32 s1, s7, 0
	v_writelane_b32 v254, s0, 27
	v_mov_b32_e32 v232, 0x41b17218
	v_mov_b32_e32 v233, 0x42800000
	v_writelane_b32 v254, s1, 28
	s_add_u32 s0, s6, 0x36054000
	s_addc_u32 s1, s7, 0
	v_writelane_b32 v254, s0, 29
	v_not_b32_e32 v234, 63
	v_mov_b32_e32 v235, 0x27200
	v_writelane_b32 v254, s1, 30
	s_add_u32 s0, s6, 0x61404000
	s_addc_u32 s1, s7, 0
	v_writelane_b32 v254, s0, 31
	v_mov_b32_e32 v236, 0x21800
	v_mov_b64_e32 v[192:193], 0x400
	v_writelane_b32 v254, s1, 32
	v_mov_b64_e32 v[194:195], 0x3ff
	v_readlane_b32 s3, v254, 11
	s_add_i32 s0, s3, 0xfffffbc0
	v_writelane_b32 v254, s0, 33
	s_add_u32 s0, s6, 0xa254000
	s_addc_u32 s1, s7, 0
	v_writelane_b32 v254, s0, 34
	v_mov_b64_e32 v[230:231], 0x2ff
	s_movk_i32 s54, 0xc0
	v_writelane_b32 v254, s1, 35
	s_add_u32 s0, s6, 0x7654000
	s_addc_u32 s1, s7, 0
	v_writelane_b32 v254, s0, 36
	s_movk_i32 s74, 0x80
	s_mov_b32 s80, 0x80000
	v_writelane_b32 v254, s1, 37
	s_add_u32 s0, s6, 0x6e54000
	s_addc_u32 s1, s7, 0
	v_writelane_b32 v254, s0, 38
	s_mov_b32 s96, 0x800000
	s_mov_b32 s41, 0x3f317217
	v_writelane_b32 v254, s1, 39
	s_add_u32 s0, s6, 0x6654000
	s_addc_u32 s1, s7, 0
	v_writelane_b32 v254, s0, 40
	s_mov_b32 s55, 0x7f800000
	s_mov_b64 s[58:59], 0x80
	v_writelane_b32 v254, s1, 41
	s_add_u32 s0, s6, 0x5e54000
	s_addc_u32 s1, s7, 0
	v_writelane_b32 v254, s0, 42
	s_mov_b64 s[50:51], 0x100
	s_mov_b32 s64, 0xbfb8aa3b
	v_writelane_b32 v254, s1, 43
	s_add_u32 s0, s6, 0x3e54000
	s_addc_u32 s1, s7, 0
	v_writelane_b32 v254, s0, 44
	s_waitcnt lgkmcnt(0)
	s_barrier
	v_writelane_b32 v254, s1, 45
	s_nop 0
	v_readlane_b32 s0, v254, 0
	v_readlane_b32 s1, v254, 1
	s_add_u32 s0, s0, 0xb0
	s_addc_u32 s1, s1, 0
	v_writelane_b32 v254, s0, 46
	s_nop 1
	v_writelane_b32 v254, s1, 47
	s_add_u32 s0, s6, 0x6f4000
	s_addc_u32 s1, s7, 0
	s_add_u32 s82, s6, 0x914000
	s_addc_u32 s83, s7, 0
	v_writelane_b32 v254, s0, 48
	s_add_u32 s84, s6, 0xb34000
	s_addc_u32 s85, s7, 0
	v_writelane_b32 v254, s1, 49
	s_and_b32 s0, s18, 0xffffffc0
	v_writelane_b32 v254, s0, 50
	s_lshl_b32 s0, s3, 13
	s_and_b32 s0, s0, 0x7fff8000
	s_add_i32 s0, s0, 0
	s_add_i32 s0, s0, 0x10000
	v_writelane_b32 v254, s0, 51
	s_lshr_b32 s0, s18, 7
	s_lshl_b32 s2, s0, 13
	s_add_i32 s49, s2, 0
	s_and_b32 s2, s18, 0xffffff80
	s_add_i32 s63, s2, 0
	s_lshl_b32 s2, s0, 9
	s_lshl_b32 s62, s0, 5
	s_add_i32 s2, s2, 0
	s_lshl_b32 s73, s0, 6
	s_lshl_b32 s0, s3, 9
	s_bfe_u32 s1, s18, 0x10006
	s_add_i32 s2, s2, 0x21000
	s_add_i32 s0, s0, 0
	v_writelane_b32 v254, s2, 52
	s_lshl_b32 s97, s1, 13
	s_add_i32 s0, s0, 0x26200
	s_lshl_b32 s65, s3, 12
	s_add_i32 s72, s97, 0
	v_writelane_b32 v254, s0, 53
	s_or_b32 s0, s1, 2
	s_or_b32 s70, s65, 0x400
	s_or_b32 s71, s65, 0x800
	s_or_b32 s76, s65, 0xc00
	s_and_b32 s48, s18, 0xc0
	s_add_i32 s63, s63, 0x20000
	s_add_i32 s72, s72, 0x22200
	s_lshl_b32 s45, s3, 8
	s_lshl_b32 s75, s1, 5
	s_or_b32 s94, s73, 16
	s_or_b32 s95, s73, 32
	s_or_b32 s78, s73, 48
	s_lshl_b32 s79, s0, 13
	s_lshl_b32 s44, s0, 5
	s_add_u32 s69, s6, 0x3e854000
	s_addc_u32 s77, s7, 0
	s_add_u32 s0, s6, 0x73624000
	v_writelane_b32 v254, s0, 54
	s_addc_u32 s0, s7, 0
	v_writelane_b32 v254, s0, 55
	s_add_u32 s0, s6, 0x61624000
	v_writelane_b32 v254, s0, 56
	s_addc_u32 s0, s7, 0
	s_add_u32 s86, s6, 0x47054000
	s_addc_u32 s87, s7, 0
	v_writelane_b32 v254, s0, 57
	s_add_u32 s0, s6, 0x14056000
	s_addc_u32 s1, s7, 0
	v_writelane_b32 v254, s0, 58
	s_nop 1
	v_writelane_b32 v254, s1, 59
	s_add_u32 s0, s6, 0x4f854000
	v_writelane_b32 v254, s0, 60
	s_addc_u32 s0, s7, 0
	v_writelane_b32 v254, s0, 61
	s_add_u32 s0, s6, 0x14057000
	s_addc_u32 s1, s7, 0
	v_writelane_b32 v254, s0, 62
	s_nop 1
	v_writelane_b32 v254, s1, 63
	s_add_u32 s0, s6, 0x5000
	s_addc_u32 s1, s7, 0
	v_writelane_b32 v255, s0, 0
	s_nop 1
	v_writelane_b32 v255, s1, 1
	s_add_u32 s0, s6, 0x5400
	v_writelane_b32 v255, s0, 2
	s_addc_u32 s0, s7, 0
	v_writelane_b32 v255, s0, 3
	s_add_u32 s0, s6, 0x58054000
	s_addc_u32 s1, s7, 0
	v_writelane_b32 v255, s0, 4
	s_nop 1
	v_writelane_b32 v255, s1, 5
	s_add_u32 s0, s6, 0x42c54000
	s_addc_u32 s1, s7, 0
	v_writelane_b32 v255, s0, 6
	s_nop 1
	v_writelane_b32 v255, s1, 7
	s_add_u32 s0, s6, 0x60854000
	s_addc_u32 s1, s7, 0
	v_writelane_b32 v255, s0, 8
	s_nop 1
	v_writelane_b32 v255, s1, 9
	s_add_i32 s0, s3, 0xfffffd00
	v_writelane_b32 v255, s0, 10
	s_add_u32 s0, s6, 0x4000
	v_writelane_b32 v255, s0, 11
	s_addc_u32 s0, s7, 0
	v_writelane_b32 v255, s0, 12
	s_add_u32 s0, s6, 0x4400
	v_writelane_b32 v255, s0, 13
	s_addc_u32 s0, s7, 0
	v_writelane_b32 v255, s0, 14
	s_sub_i32 s0, s3, 64
	v_writelane_b32 v255, s0, 15
	v_readlane_b32 s0, v254, 15
	v_readlane_b32 s1, v254, 16
	s_add_u32 s0, s0, 0x1e000
	s_addc_u32 s1, s1, 0
	v_writelane_b32 v255, s0, 16
	s_add_i32 s45, s45, 0
	s_nop 0
	v_writelane_b32 v255, s1, 17
	s_add_i32 s0, s3, 0x200
	v_writelane_b32 v255, s0, 18
	s_add_i32 s0, s3, 0xc0
	v_writelane_b32 v255, s0, 19
	s_add_i32 s0, 0, 0x22020
	v_writelane_b32 v255, s0, 20
	s_add_i32 s0, 0, 0x22024
	v_writelane_b32 v255, s0, 21
	s_mov_b32 s0, s93
	v_writelane_b32 v255, s0, 22
	s_nop 1
	v_writelane_b32 v255, s1, 23
	v_writelane_b32 v255, s38, 24
	s_nop 1
	v_writelane_b32 v255, s39, 25
	v_writelane_b32 v255, s42, 26
	s_nop 1
	v_writelane_b32 v255, s43, 27
	v_writelane_b32 v255, s69, 28
	v_writelane_b32 v255, s77, 29
	s_branch .LBB0_165

.LBB0_175:
	s_ashr_i32 s57, s56, 31
	s_lshl_b64 s[52:53], s[56:57], 20
	v_readlane_b32 s66, v254, 17
	v_readlane_b32 s67, v254, 18
	s_add_u32 s66, s66, s52
	s_addc_u32 s67, s67, s53
	s_and_b64 s[52:53], s[6:7], exec
	s_cselect_b32 s11, s67, s9
	s_cselect_b32 s13, s66, s8
	s_ashr_i32 s61, s60, 31
	s_lshl_b64 s[52:53], s[60:61], 20
	v_readlane_b32 s68, v254, 21
	v_readlane_b32 s69, v254, 22
	s_add_u32 s88, s68, s52
	s_addc_u32 s89, s69, s53
	s_and_b64 s[52:53], s[6:7], exec
	s_cselect_b32 s57, s89, s15
	s_cselect_b32 s61, s88, s14
	s_add_u32 s8, s8, 0x80080
	s_addc_u32 s9, s9, 0
	s_add_u32 s68, s14, 0x100
	s_addc_u32 s69, s15, 0
	s_mov_b32 s90, -2
	s_add_u32 s14, s8, 0xfff80080
	s_addc_u32 s15, s9, -1
	s_add_i32 s91, 0, 0x10000
	s_cmp_eq_u32 s90, 28
	s_cselect_b32 s53, s11, s15
	s_cselect_b32 s52, s13, s14
	v_add_u32_e32 v14, s91, v188
	s_cselect_b32 s15, s57, s69
	s_cselect_b32 s14, s61, s68
	s_add_i32 s96, 0, 0x14000
	ds_read_b128 v[6:9], v14
	ds_read_b128 v[10:13], v14 offset:1024
	ds_read_b128 v[140:143], v14 offset:2048
	ds_read_b128 v[144:147], v14 offset:3072
	v_add_u32_e32 v14, s96, v188
	ds_read_b128 v[148:151], v14
	ds_read_b128 v[152:155], v14 offset:1024
	ds_read_b128 v[180:183], v14 offset:2048
	ds_read_b128 v[208:211], v14 offset:3072
	v_lshl_add_u64 v[14:15], s[8:9], 0, v[176:177]
	s_add_i32 m0, s40, 0xc000
	ds_read_b128 v[212:215], v206
	ds_read_b128 v[216:219], v206 offset:1024
	ds_read_b128 v[220:223], v206 offset:2048
	ds_read_b128 v[224:227], v206 offset:3072
	ds_read_b128 v[238:241], v206 offset:4096
	ds_read_b128 v[242:245], v206 offset:5120
	ds_read_b128 v[246:249], v206 offset:6144
	ds_read_b128 v[250:253], v206 offset:7168
	global_load_lds_dwordx4 v[14:15], off
	v_lshl_add_u64 v[14:15], s[8:9], 0, v[178:179]
	s_add_i32 m0, s40, 0xe000
	s_nop 0
	global_load_lds_dwordx4 v[14:15], off
	s_waitcnt vmcnt(8)
	s_waitcnt lgkmcnt(0)
	s_barrier
	s_setprio 1
	s_waitcnt lgkmcnt(0)
	v_mfma_f32_16x16x32_bf16 v[136:139], v[6:9], v[212:215], 0
	v_mfma_f32_16x16x32_bf16 v[104:107], v[140:143], v[212:215], 0
	v_mfma_f32_16x16x32_bf16 v[132:135], v[6:9], v[220:223], 0
	v_mfma_f32_16x16x32_bf16 v[100:103], v[140:143], v[220:223], 0
	v_mfma_f32_16x16x32_bf16 v[128:131], v[6:9], v[238:241], 0
	v_mfma_f32_16x16x32_bf16 v[96:99], v[140:143], v[238:241], 0
	v_mfma_f32_16x16x32_bf16 v[124:127], v[6:9], v[246:249], 0
	v_mfma_f32_16x16x32_bf16 v[92:95], v[140:143], v[246:249], 0
	v_mfma_f32_16x16x32_bf16 v[136:139], v[10:13], v[216:219], v[136:139]
	v_mfma_f32_16x16x32_bf16 v[104:107], v[144:147], v[216:219], v[104:107]
	v_mfma_f32_16x16x32_bf16 v[132:135], v[10:13], v[224:227], v[132:135]
	v_mfma_f32_16x16x32_bf16 v[100:103], v[144:147], v[224:227], v[100:103]
	v_mfma_f32_16x16x32_bf16 v[128:131], v[10:13], v[242:245], v[128:131]
	v_mfma_f32_16x16x32_bf16 v[96:99], v[144:147], v[242:245], v[96:99]
	v_mfma_f32_16x16x32_bf16 v[124:127], v[10:13], v[250:253], v[124:127]
	v_mfma_f32_16x16x32_bf16 v[92:95], v[144:147], v[250:253], v[92:95]
	s_setprio 0
	s_setprio 1
	v_mfma_f32_16x16x32_bf16 v[72:75], v[148:151], v[212:215], 0
	v_mfma_f32_16x16x32_bf16 v[40:43], v[180:183], v[212:215], 0
	v_mfma_f32_16x16x32_bf16 v[68:71], v[148:151], v[220:223], 0
	v_mfma_f32_16x16x32_bf16 v[36:39], v[180:183], v[220:223], 0
	v_mfma_f32_16x16x32_bf16 v[64:67], v[148:151], v[238:241], 0
	v_mfma_f32_16x16x32_bf16 v[32:35], v[180:183], v[238:241], 0
	v_mfma_f32_16x16x32_bf16 v[60:63], v[148:151], v[246:249], 0
	v_mfma_f32_16x16x32_bf16 v[28:31], v[180:183], v[246:249], 0
	v_mfma_f32_16x16x32_bf16 v[72:75], v[152:155], v[216:219], v[72:75]
	v_mfma_f32_16x16x32_bf16 v[40:43], v[208:211], v[216:219], v[40:43]
	v_mfma_f32_16x16x32_bf16 v[68:71], v[152:155], v[224:227], v[68:71]
	v_mfma_f32_16x16x32_bf16 v[36:39], v[208:211], v[224:227], v[36:39]
	v_mfma_f32_16x16x32_bf16 v[64:67], v[152:155], v[242:245], v[64:67]
	v_mfma_f32_16x16x32_bf16 v[32:35], v[208:211], v[242:245], v[32:35]
	v_mfma_f32_16x16x32_bf16 v[60:63], v[152:155], v[250:253], v[60:63]
	v_mfma_f32_16x16x32_bf16 v[28:31], v[208:211], v[250:253], v[28:31]
	s_setprio 0
	s_barrier
	s_add_i32 s91, s91, s33
	v_lshl_add_u64 v[156:157], s[14:15], 0, v[160:161]
	s_mov_b32 m0, s91
	ds_read_b128 v[212:215], v206 offset:16384
	ds_read_b128 v[216:219], v206 offset:17408
	ds_read_b128 v[220:223], v206 offset:18432
	ds_read_b128 v[224:227], v206 offset:19456
	ds_read_b128 v[238:241], v206 offset:20480
	ds_read_b128 v[242:245], v206 offset:21504
	ds_read_b128 v[246:249], v206 offset:22528
	ds_read_b128 v[250:253], v206 offset:23552
	global_load_lds_dwordx4 v[156:157], off
	s_add_i32 m0, s91, 0x2000
	s_add_u32 vcc_lo, s14, 0x80000
	v_lshl_add_u64 v[184:185], s[14:15], 0, v[164:165]
	s_addc_u32 vcc_hi, s15, 0
	s_add_i32 s91, s96, s33
	global_load_lds_dwordx4 v[184:185], off
	v_lshl_add_u64 v[14:15], vcc, 0, v[160:161]
	s_mov_b32 m0, s91
	v_lshl_add_u64 v[196:197], s[52:53], 0, v[158:159]
	global_load_lds_dwordx4 v[14:15], off
	v_lshl_add_u64 v[14:15], vcc, 0, v[164:165]
	s_add_i32 m0, s91, 0x2000
	v_lshl_add_u64 v[198:199], s[52:53], 0, v[162:163]
	global_load_lds_dwordx4 v[14:15], off
	s_mov_b32 m0, s40
	s_nop 0
	global_load_lds_dwordx4 v[196:197], off
	s_mov_b32 m0, s41
	s_nop 0
	global_load_lds_dwordx4 v[198:199], off
	s_waitcnt vmcnt(8)
	s_waitcnt lgkmcnt(0)
	s_barrier
	s_setprio 1
	s_waitcnt lgkmcnt(0)
	v_mfma_f32_16x16x32_bf16 v[120:123], v[6:9], v[212:215], 0
	v_mfma_f32_16x16x32_bf16 v[88:91], v[140:143], v[212:215], 0
	v_mfma_f32_16x16x32_bf16 v[116:119], v[6:9], v[220:223], 0
	v_mfma_f32_16x16x32_bf16 v[84:87], v[140:143], v[220:223], 0
	v_mfma_f32_16x16x32_bf16 v[112:115], v[6:9], v[238:241], 0
	v_mfma_f32_16x16x32_bf16 v[80:83], v[140:143], v[238:241], 0
	v_mfma_f32_16x16x32_bf16 v[6:9], v[6:9], v[246:249], 0
	v_mfma_f32_16x16x32_bf16 v[120:123], v[10:13], v[216:219], v[120:123]
	v_mfma_f32_16x16x32_bf16 v[88:91], v[144:147], v[216:219], v[88:91]
	v_mfma_f32_16x16x32_bf16 v[116:119], v[10:13], v[224:227], v[116:119]
	v_mfma_f32_16x16x32_bf16 v[84:87], v[144:147], v[224:227], v[84:87]
	v_mfma_f32_16x16x32_bf16 v[112:115], v[10:13], v[242:245], v[112:115]
	v_mfma_f32_16x16x32_bf16 v[80:83], v[144:147], v[242:245], v[80:83]
	v_mfma_f32_16x16x32_bf16 v[6:9], v[10:13], v[250:253], v[6:9]
	v_mfma_f32_16x16x32_bf16 v[10:13], v[140:143], v[246:249], 0
	v_mfma_f32_16x16x32_bf16 v[10:13], v[144:147], v[250:253], v[10:13]
	s_setprio 0
	s_setprio 1
	v_mfma_f32_16x16x32_bf16 v[56:59], v[148:151], v[212:215], 0
	v_mfma_f32_16x16x32_bf16 v[24:27], v[180:183], v[212:215], 0
	v_mfma_f32_16x16x32_bf16 v[52:55], v[148:151], v[220:223], 0
	v_mfma_f32_16x16x32_bf16 v[20:23], v[180:183], v[220:223], 0
	v_mfma_f32_16x16x32_bf16 v[48:51], v[148:151], v[238:241], 0
	v_mfma_f32_16x16x32_bf16 v[14:17], v[180:183], v[238:241], 0
	v_mfma_f32_16x16x32_bf16 v[44:47], v[148:151], v[246:249], 0
	v_mfma_f32_16x16x32_bf16 v[2:5], v[180:183], v[246:249], 0
	v_mfma_f32_16x16x32_bf16 v[56:59], v[152:155], v[216:219], v[56:59]
	v_mfma_f32_16x16x32_bf16 v[24:27], v[208:211], v[216:219], v[24:27]
	v_mfma_f32_16x16x32_bf16 v[52:55], v[152:155], v[224:227], v[52:55]
	v_mfma_f32_16x16x32_bf16 v[20:23], v[208:211], v[224:227], v[20:23]
	v_mfma_f32_16x16x32_bf16 v[48:51], v[152:155], v[242:245], v[48:51]
	v_mfma_f32_16x16x32_bf16 v[14:17], v[208:211], v[242:245], v[14:17]
	v_mfma_f32_16x16x32_bf16 v[44:47], v[152:155], v[250:253], v[44:47]
	v_mfma_f32_16x16x32_bf16 v[2:5], v[208:211], v[250:253], v[2:5]
	s_setprio 0
	s_barrier
	s_add_i32 s91, 0, 0x18000
	v_add_u32_e32 v18, s91, v188
	s_add_i32 s96, 0, 0x1c000
	ds_read_b128 v[76:79], v18
	ds_read_b128 v[108:111], v18 offset:1024
	ds_read_b128 v[140:143], v18 offset:2048
	ds_read_b128 v[144:147], v18 offset:3072
	v_add_u32_e32 v18, s96, v188
	ds_read_b128 v[148:151], v18
	ds_read_b128 v[152:155], v18 offset:1024
	ds_read_b128 v[180:183], v18 offset:2048
	ds_read_b128 v[208:211], v18 offset:3072
	s_add_u32 s52, s52, 0x80000
	s_addc_u32 s53, s53, 0
	s_mov_b32 m0, s42
	v_lshl_add_u64 v[18:19], s[52:53], 0, v[158:159]
	ds_read_b128 v[212:215], v206 offset:32768
	ds_read_b128 v[216:219], v206 offset:33792
	ds_read_b128 v[220:223], v206 offset:34816
	ds_read_b128 v[224:227], v206 offset:35840
	ds_read_b128 v[238:241], v206 offset:36864
	ds_read_b128 v[242:245], v206 offset:37888
	ds_read_b128 v[246:249], v206 offset:38912
	ds_read_b128 v[250:253], v206 offset:39936
	global_load_lds_dwordx4 v[18:19], off
	v_lshl_add_u64 v[18:19], s[52:53], 0, v[162:163]
	s_mov_b32 m0, s43
	s_nop 0
	global_load_lds_dwordx4 v[18:19], off
	s_waitcnt vmcnt(8)
	s_waitcnt lgkmcnt(0)
	s_barrier
	s_setprio 1
	s_waitcnt lgkmcnt(0)
	v_mfma_f32_16x16x32_bf16 v[136:139], v[76:79], v[212:215], v[136:139]
	v_mfma_f32_16x16x32_bf16 v[104:107], v[140:143], v[212:215], v[104:107]
	v_mfma_f32_16x16x32_bf16 v[132:135], v[76:79], v[220:223], v[132:135]
	v_mfma_f32_16x16x32_bf16 v[100:103], v[140:143], v[220:223], v[100:103]
	v_mfma_f32_16x16x32_bf16 v[128:131], v[76:79], v[238:241], v[128:131]
	v_mfma_f32_16x16x32_bf16 v[96:99], v[140:143], v[238:241], v[96:99]
	v_mfma_f32_16x16x32_bf16 v[124:127], v[76:79], v[246:249], v[124:127]
	v_mfma_f32_16x16x32_bf16 v[92:95], v[140:143], v[246:249], v[92:95]
	v_mfma_f32_16x16x32_bf16 v[136:139], v[108:111], v[216:219], v[136:139]
	v_mfma_f32_16x16x32_bf16 v[104:107], v[144:147], v[216:219], v[104:107]
	v_mfma_f32_16x16x32_bf16 v[132:135], v[108:111], v[224:227], v[132:135]
	v_mfma_f32_16x16x32_bf16 v[100:103], v[144:147], v[224:227], v[100:103]
	v_mfma_f32_16x16x32_bf16 v[128:131], v[108:111], v[242:245], v[128:131]
	v_mfma_f32_16x16x32_bf16 v[96:99], v[144:147], v[242:245], v[96:99]
	v_mfma_f32_16x16x32_bf16 v[124:127], v[108:111], v[250:253], v[124:127]
	v_mfma_f32_16x16x32_bf16 v[92:95], v[144:147], v[250:253], v[92:95]
	s_setprio 0
	s_setprio 1
	v_mfma_f32_16x16x32_bf16 v[72:75], v[148:151], v[212:215], v[72:75]
	v_mfma_f32_16x16x32_bf16 v[40:43], v[180:183], v[212:215], v[40:43]
	v_mfma_f32_16x16x32_bf16 v[68:71], v[148:151], v[220:223], v[68:71]
	v_mfma_f32_16x16x32_bf16 v[36:39], v[180:183], v[220:223], v[36:39]
	v_mfma_f32_16x16x32_bf16 v[64:67], v[148:151], v[238:241], v[64:67]
	v_mfma_f32_16x16x32_bf16 v[32:35], v[180:183], v[238:241], v[32:35]
	v_mfma_f32_16x16x32_bf16 v[60:63], v[148:151], v[246:249], v[60:63]
	v_mfma_f32_16x16x32_bf16 v[28:31], v[180:183], v[246:249], v[28:31]
	v_mfma_f32_16x16x32_bf16 v[72:75], v[152:155], v[216:219], v[72:75]
	v_mfma_f32_16x16x32_bf16 v[40:43], v[208:211], v[216:219], v[40:43]
	v_mfma_f32_16x16x32_bf16 v[68:71], v[152:155], v[224:227], v[68:71]
	v_mfma_f32_16x16x32_bf16 v[36:39], v[208:211], v[224:227], v[36:39]
	v_mfma_f32_16x16x32_bf16 v[64:67], v[152:155], v[242:245], v[64:67]
	v_mfma_f32_16x16x32_bf16 v[32:35], v[208:211], v[242:245], v[32:35]
	v_mfma_f32_16x16x32_bf16 v[60:63], v[152:155], v[250:253], v[60:63]
	v_mfma_f32_16x16x32_bf16 v[28:31], v[208:211], v[250:253], v[28:31]
	s_setprio 0
	s_barrier
	s_add_i32 s52, s91, s33
	v_lshl_add_u64 v[18:19], v[156:157], 0, s[58:59]
	s_mov_b32 m0, s52
	ds_read_b128 v[212:215], v206 offset:49152
	ds_read_b128 v[216:219], v206 offset:50176
	ds_read_b128 v[220:223], v206 offset:51200
	ds_read_b128 v[224:227], v206 offset:52224
	ds_read_b128 v[238:241], v206 offset:53248
	ds_read_b128 v[242:245], v206 offset:54272
	ds_read_b128 v[246:249], v206 offset:55296
	ds_read_b128 v[250:253], v206 offset:56320
	global_load_lds_dwordx4 v[18:19], off
	s_add_i32 m0, s52, 0x2000
	s_add_u32 s14, s14, 0x80080
	v_lshl_add_u64 v[18:19], v[184:185], 0, s[58:59]
	s_addc_u32 s15, s15, 0
	s_add_i32 s52, s96, s33
	global_load_lds_dwordx4 v[18:19], off
	v_lshl_add_u64 v[18:19], s[14:15], 0, v[160:161]
	s_mov_b32 m0, s52
	s_nop 0
	global_load_lds_dwordx4 v[18:19], off
	v_lshl_add_u64 v[18:19], s[14:15], 0, v[164:165]
	s_add_i32 m0, s52, 0x2000
	s_nop 0
	global_load_lds_dwordx4 v[18:19], off
	v_lshl_add_u64 v[18:19], v[196:197], 0, s[58:59]
	s_mov_b32 m0, s55
	s_nop 0
	global_load_lds_dwordx4 v[18:19], off
	v_lshl_add_u64 v[18:19], v[198:199], 0, s[58:59]
	s_mov_b32 m0, s77
	s_nop 0
	global_load_lds_dwordx4 v[18:19], off
	s_waitcnt vmcnt(8)
	s_waitcnt lgkmcnt(0)
	s_barrier
	s_setprio 1
	s_waitcnt lgkmcnt(0)
	v_mfma_f32_16x16x32_bf16 v[120:123], v[76:79], v[212:215], v[120:123]
	v_mfma_f32_16x16x32_bf16 v[116:119], v[76:79], v[220:223], v[116:119]
	v_mfma_f32_16x16x32_bf16 v[112:115], v[76:79], v[238:241], v[112:115]
	v_mfma_f32_16x16x32_bf16 v[6:9], v[76:79], v[246:249], v[6:9]
	v_mfma_f32_16x16x32_bf16 v[120:123], v[108:111], v[216:219], v[120:123]
	v_mfma_f32_16x16x32_bf16 v[88:91], v[140:143], v[212:215], v[88:91]
	v_mfma_f32_16x16x32_bf16 v[116:119], v[108:111], v[224:227], v[116:119]
	v_mfma_f32_16x16x32_bf16 v[84:87], v[140:143], v[220:223], v[84:87]
	v_mfma_f32_16x16x32_bf16 v[112:115], v[108:111], v[242:245], v[112:115]
	v_mfma_f32_16x16x32_bf16 v[80:83], v[140:143], v[238:241], v[80:83]
	v_mfma_f32_16x16x32_bf16 v[108:111], v[108:111], v[250:253], v[6:9]
	v_mfma_f32_16x16x32_bf16 v[6:9], v[140:143], v[246:249], v[10:13]
	v_mfma_f32_16x16x32_bf16 v[88:91], v[144:147], v[216:219], v[88:91]
	v_mfma_f32_16x16x32_bf16 v[84:87], v[144:147], v[224:227], v[84:87]
	v_mfma_f32_16x16x32_bf16 v[80:83], v[144:147], v[242:245], v[80:83]
	v_mfma_f32_16x16x32_bf16 v[76:79], v[144:147], v[250:253], v[6:9]
	s_setprio 0
	s_setprio 1
	v_mfma_f32_16x16x32_bf16 v[6:9], v[148:151], v[212:215], v[56:59]
	v_mfma_f32_16x16x32_bf16 v[56:59], v[152:155], v[216:219], v[6:9]
	v_mfma_f32_16x16x32_bf16 v[6:9], v[180:183], v[212:215], v[24:27]
	v_mfma_f32_16x16x32_bf16 v[24:27], v[208:211], v[216:219], v[6:9]
	v_mfma_f32_16x16x32_bf16 v[6:9], v[148:151], v[220:223], v[52:55]
	v_mfma_f32_16x16x32_bf16 v[52:55], v[152:155], v[224:227], v[6:9]
	v_mfma_f32_16x16x32_bf16 v[6:9], v[180:183], v[220:223], v[20:23]
	v_mfma_f32_16x16x32_bf16 v[20:23], v[208:211], v[224:227], v[6:9]
	v_mfma_f32_16x16x32_bf16 v[6:9], v[148:151], v[238:241], v[48:51]
	v_mfma_f32_16x16x32_bf16 v[48:51], v[152:155], v[242:245], v[6:9]
	v_mfma_f32_16x16x32_bf16 v[6:9], v[180:183], v[238:241], v[14:17]
	v_mfma_f32_16x16x32_bf16 v[16:19], v[208:211], v[242:245], v[6:9]
	v_mfma_f32_16x16x32_bf16 v[6:9], v[148:151], v[246:249], v[44:47]
	v_mfma_f32_16x16x32_bf16 v[2:5], v[180:183], v[246:249], v[2:5]
	v_mfma_f32_16x16x32_bf16 v[44:47], v[152:155], v[250:253], v[6:9]
	v_mfma_f32_16x16x32_bf16 v[2:5], v[208:211], v[250:253], v[2:5]
	s_setprio 0
	s_barrier
	s_add_i32 s90, s90, 2
	s_add_u32 s8, s8, 0x100
	s_addc_u32 s9, s9, 0
	s_add_u32 s68, s68, 0x100
	s_addc_u32 s69, s69, 0
	s_cmp_gt_u32 s90, 29
	s_cbranch_scc1 .Lpeel_done_0

.Lpeel_done_0:
	s_and_b64 vcc, exec, s[16:17]
	s_cbranch_vccz .LBB0_179
	s_barrier

.LBB0_671:
	s_ashr_i32 s11, s10, 31
	s_lshl_b64 s[12:13], s[10:11], 20
	v_readlane_b32 s14, v254, 17
	v_readlane_b32 s15, v254, 18
	s_add_u32 s12, s14, s12
	s_addc_u32 s13, s15, s13
	s_and_b64 s[14:15], s[4:5], exec
	s_cselect_b32 s11, s13, s23
	s_cselect_b32 s18, s12, s22
	s_ashr_i32 s9, s8, 31
	s_lshl_b64 s[14:15], s[8:9], 20
	v_readlane_b32 s26, v254, 44
	v_readlane_b32 s27, v254, 45
	s_add_u32 s14, s26, s14
	s_addc_u32 s15, s27, s15
	s_and_b64 s[26:27], s[4:5], exec
	s_cselect_b32 s9, s15, s25
	s_cselect_b32 s19, s14, s24
	s_add_u32 s22, s22, 0x80080
	s_addc_u32 s23, s23, 0
	s_add_u32 s21, s24, 0x100
	s_addc_u32 s33, s25, 0
	s_mov_b32 s40, -2
	v_readlane_b32 s41, v255, 49
	s_nop 3
	s_cmp_eq_u32 s41, 2
	v_writelane_b32 v255, 2, 49
	s_cbranch_scc0 .Ltrip0_strict_1
	s_add_u32 s24, s22, 0xfff80080
	s_addc_u32 s25, s23, -1
	s_add_i32 s41, 0, 0x10000
	s_cmp_eq_u32 s40, 28
	s_cselect_b32 s27, s11, s25
	s_cselect_b32 s26, s18, s24
	s_cselect_b32 s25, s9, s33
	s_cselect_b32 s24, s19, s21
	s_add_i32 s46, 0, 0x14000
	v_add_u32_e32 v142, s41, v214
	v_add_u32_e32 v158, s46, v214
	ds_read_b128 v[130:133], v142
	ds_read_b128 v[134:137], v142 offset:1024
	ds_read_b128 v[138:141], v142 offset:2048
	ds_read_b128 v[142:145], v142 offset:3072
	ds_read_b128 v[146:149], v158
	ds_read_b128 v[150:153], v158 offset:1024
	ds_read_b128 v[154:157], v158 offset:2048
	ds_read_b128 v[158:161], v158 offset:3072
	v_lshl_add_u64 v[212:213], s[22:23], 0, v[182:183]
	s_add_i32 m0, s17, 0xc000
	ds_read_b128 v[162:165], v216
	ds_read_b128 v[166:169], v216 offset:1024
	ds_read_b128 v[170:173], v216 offset:2048
	ds_read_b128 v[186:189], v216 offset:3072
	ds_read_b128 v[196:199], v216 offset:4096
	ds_read_b128 v[200:203], v216 offset:5120
	ds_read_b128 v[204:207], v216 offset:6144
	ds_read_b128 v[208:211], v216 offset:7168
	global_load_lds_dwordx4 v[212:213], off
	v_lshl_add_u64 v[212:213], s[22:23], 0, v[184:185]
	s_add_i32 m0, s17, 0xe000
	s_nop 0
	global_load_lds_dwordx4 v[212:213], off
	s_waitcnt vmcnt(24)
	s_waitcnt lgkmcnt(0)
	s_barrier
	s_setprio 1
	s_waitcnt lgkmcnt(0)
	v_mfma_f32_16x16x32_bf16 v[126:129], v[130:133], v[162:165], 0
	v_mfma_f32_16x16x32_bf16 v[122:125], v[138:141], v[162:165], 0
	v_mfma_f32_16x16x32_bf16 v[110:113], v[130:133], v[170:173], 0
	v_mfma_f32_16x16x32_bf16 v[106:109], v[138:141], v[170:173], 0
	v_mfma_f32_16x16x32_bf16 v[94:97], v[130:133], v[196:199], 0
	v_mfma_f32_16x16x32_bf16 v[90:93], v[138:141], v[196:199], 0
	v_mfma_f32_16x16x32_bf16 v[78:81], v[130:133], v[204:207], 0
	v_mfma_f32_16x16x32_bf16 v[74:77], v[138:141], v[204:207], 0
	v_mfma_f32_16x16x32_bf16 v[126:129], v[134:137], v[166:169], v[126:129]
	v_mfma_f32_16x16x32_bf16 v[122:125], v[142:145], v[166:169], v[122:125]
	v_mfma_f32_16x16x32_bf16 v[110:113], v[134:137], v[186:189], v[110:113]
	v_mfma_f32_16x16x32_bf16 v[106:109], v[142:145], v[186:189], v[106:109]
	v_mfma_f32_16x16x32_bf16 v[94:97], v[134:137], v[200:203], v[94:97]
	v_mfma_f32_16x16x32_bf16 v[90:93], v[142:145], v[200:203], v[90:93]
	v_mfma_f32_16x16x32_bf16 v[78:81], v[134:137], v[208:211], v[78:81]
	v_mfma_f32_16x16x32_bf16 v[74:77], v[142:145], v[208:211], v[74:77]
	s_setprio 0
	s_setprio 1
	v_mfma_f32_16x16x32_bf16 v[118:121], v[146:149], v[162:165], 0
	v_mfma_f32_16x16x32_bf16 v[114:117], v[154:157], v[162:165], 0
	v_mfma_f32_16x16x32_bf16 v[102:105], v[146:149], v[170:173], 0
	v_mfma_f32_16x16x32_bf16 v[98:101], v[154:157], v[170:173], 0
	v_mfma_f32_16x16x32_bf16 v[86:89], v[146:149], v[196:199], 0
	v_mfma_f32_16x16x32_bf16 v[82:85], v[154:157], v[196:199], 0
	v_mfma_f32_16x16x32_bf16 v[70:73], v[146:149], v[204:207], 0
	v_mfma_f32_16x16x32_bf16 v[66:69], v[154:157], v[204:207], 0
	v_mfma_f32_16x16x32_bf16 v[118:121], v[150:153], v[166:169], v[118:121]
	v_mfma_f32_16x16x32_bf16 v[114:117], v[158:161], v[166:169], v[114:117]
	v_mfma_f32_16x16x32_bf16 v[102:105], v[150:153], v[186:189], v[102:105]
	v_mfma_f32_16x16x32_bf16 v[98:101], v[158:161], v[186:189], v[98:101]
	v_mfma_f32_16x16x32_bf16 v[86:89], v[150:153], v[200:203], v[86:89]
	v_mfma_f32_16x16x32_bf16 v[82:85], v[158:161], v[200:203], v[82:85]
	v_mfma_f32_16x16x32_bf16 v[70:73], v[150:153], v[208:211], v[70:73]
	v_mfma_f32_16x16x32_bf16 v[66:69], v[158:161], v[208:211], v[66:69]
	s_setprio 0
	s_barrier
	s_add_i32 s41, s41, s29
	v_lshl_add_u64 v[212:213], s[24:25], 0, v[178:179]
	s_mov_b32 m0, s41
	ds_read_b128 v[162:165], v216 offset:16384
	ds_read_b128 v[166:169], v216 offset:17408
	ds_read_b128 v[170:173], v216 offset:18432
	ds_read_b128 v[186:189], v216 offset:19456
	ds_read_b128 v[196:199], v216 offset:20480
	ds_read_b128 v[200:203], v216 offset:21504
	ds_read_b128 v[204:207], v216 offset:22528
	ds_read_b128 v[208:211], v216 offset:23552
	global_load_lds_dwordx4 v[212:213], off
	s_add_i32 m0, s41, 0x2000
	s_add_u32 s42, s24, 0x80000
	v_lshl_add_u64 v[218:219], s[24:25], 0, v[174:175]
	s_addc_u32 s43, s25, 0
	s_add_i32 s41, s46, s29
	global_load_lds_dwordx4 v[218:219], off
	v_lshl_add_u64 v[220:221], s[42:43], 0, v[178:179]
	s_mov_b32 m0, s41
	v_lshl_add_u64 v[222:223], s[26:27], 0, v[176:177]
	global_load_lds_dwordx4 v[220:221], off
	v_lshl_add_u64 v[220:221], s[42:43], 0, v[174:175]
	s_add_i32 m0, s41, 0x2000
	s_nop 0
	global_load_lds_dwordx4 v[220:221], off
	v_lshl_add_u64 v[220:221], s[26:27], 0, v[180:181]
	s_mov_b32 m0, s17
	s_nop 0
	global_load_lds_dwordx4 v[220:221], off
	s_mov_b32 m0, s31
	s_nop 0
	global_load_lds_dwordx4 v[222:223], off
	s_waitcnt vmcnt(24)
	s_waitcnt lgkmcnt(0)
	s_barrier
	s_setprio 1
	s_waitcnt lgkmcnt(0)
	v_mfma_f32_16x16x32_bf16 v[62:65], v[130:133], v[162:165], 0
	v_mfma_f32_16x16x32_bf16 v[58:61], v[138:141], v[162:165], 0
	v_mfma_f32_16x16x32_bf16 v[46:49], v[130:133], v[170:173], 0
	v_mfma_f32_16x16x32_bf16 v[42:45], v[138:141], v[170:173], 0
	v_mfma_f32_16x16x32_bf16 v[30:33], v[130:133], v[196:199], 0
	v_mfma_f32_16x16x32_bf16 v[26:29], v[138:141], v[196:199], 0
	v_mfma_f32_16x16x32_bf16 v[14:17], v[130:133], v[204:207], 0
	v_mfma_f32_16x16x32_bf16 v[10:13], v[138:141], v[204:207], 0
	v_mfma_f32_16x16x32_bf16 v[62:65], v[134:137], v[166:169], v[62:65]
	v_mfma_f32_16x16x32_bf16 v[58:61], v[142:145], v[166:169], v[58:61]
	v_mfma_f32_16x16x32_bf16 v[46:49], v[134:137], v[186:189], v[46:49]
	v_mfma_f32_16x16x32_bf16 v[42:45], v[142:145], v[186:189], v[42:45]
	v_mfma_f32_16x16x32_bf16 v[30:33], v[134:137], v[200:203], v[30:33]
	v_mfma_f32_16x16x32_bf16 v[26:29], v[142:145], v[200:203], v[26:29]
	v_mfma_f32_16x16x32_bf16 v[14:17], v[134:137], v[208:211], v[14:17]
	v_mfma_f32_16x16x32_bf16 v[10:13], v[142:145], v[208:211], v[10:13]
	s_setprio 0
	s_setprio 1
	v_mfma_f32_16x16x32_bf16 v[54:57], v[146:149], v[162:165], 0
	v_mfma_f32_16x16x32_bf16 v[50:53], v[154:157], v[162:165], 0
	v_mfma_f32_16x16x32_bf16 v[38:41], v[146:149], v[170:173], 0
	v_mfma_f32_16x16x32_bf16 v[34:37], v[154:157], v[170:173], 0
	v_mfma_f32_16x16x32_bf16 v[22:25], v[146:149], v[196:199], 0
	v_mfma_f32_16x16x32_bf16 v[18:21], v[154:157], v[196:199], 0
	v_mfma_f32_16x16x32_bf16 v[6:9], v[146:149], v[204:207], 0
	v_mfma_f32_16x16x32_bf16 v[2:5], v[154:157], v[204:207], 0
	v_mfma_f32_16x16x32_bf16 v[54:57], v[150:153], v[166:169], v[54:57]
	v_mfma_f32_16x16x32_bf16 v[50:53], v[158:161], v[166:169], v[50:53]
	v_mfma_f32_16x16x32_bf16 v[38:41], v[150:153], v[186:189], v[38:41]
	v_mfma_f32_16x16x32_bf16 v[34:37], v[158:161], v[186:189], v[34:37]
	v_mfma_f32_16x16x32_bf16 v[22:25], v[150:153], v[200:203], v[22:25]
	v_mfma_f32_16x16x32_bf16 v[18:21], v[158:161], v[200:203], v[18:21]
	v_mfma_f32_16x16x32_bf16 v[6:9], v[150:153], v[208:211], v[6:9]
	v_mfma_f32_16x16x32_bf16 v[2:5], v[158:161], v[208:211], v[2:5]
	s_setprio 0
	s_barrier
	s_add_i32 s41, 0, 0x18000
	s_add_i32 s42, 0, 0x1c000
	v_add_u32_e32 v142, s41, v214
	v_add_u32_e32 v158, s42, v214
	ds_read_b128 v[130:133], v142
	ds_read_b128 v[134:137], v142 offset:1024
	ds_read_b128 v[138:141], v142 offset:2048
	ds_read_b128 v[142:145], v142 offset:3072
	ds_read_b128 v[146:149], v158
	ds_read_b128 v[150:153], v158 offset:1024
	ds_read_b128 v[154:157], v158 offset:2048
	ds_read_b128 v[158:161], v158 offset:3072
	s_add_u32 s26, s26, 0x80000
	s_addc_u32 s27, s27, 0
	s_mov_b32 m0, s34
	v_lshl_add_u64 v[224:225], s[26:27], 0, v[180:181]
	ds_read_b128 v[162:165], v216 offset:32768
	ds_read_b128 v[166:169], v216 offset:33792
	ds_read_b128 v[170:173], v216 offset:34816
	ds_read_b128 v[186:189], v216 offset:35840
	ds_read_b128 v[196:199], v216 offset:36864
	ds_read_b128 v[200:203], v216 offset:37888
	ds_read_b128 v[204:207], v216 offset:38912
	ds_read_b128 v[208:211], v216 offset:39936
	global_load_lds_dwordx4 v[224:225], off
	v_lshl_add_u64 v[224:225], s[26:27], 0, v[176:177]
	s_mov_b32 m0, s35
	s_nop 0
	global_load_lds_dwordx4 v[224:225], off
	s_waitcnt vmcnt(8)
	s_waitcnt lgkmcnt(0)
	s_barrier
	s_setprio 1
	s_waitcnt lgkmcnt(0)
	v_mfma_f32_16x16x32_bf16 v[126:129], v[130:133], v[162:165], v[126:129]
	v_mfma_f32_16x16x32_bf16 v[122:125], v[138:141], v[162:165], v[122:125]
	v_mfma_f32_16x16x32_bf16 v[110:113], v[130:133], v[170:173], v[110:113]
	v_mfma_f32_16x16x32_bf16 v[106:109], v[138:141], v[170:173], v[106:109]
	v_mfma_f32_16x16x32_bf16 v[94:97], v[130:133], v[196:199], v[94:97]
	v_mfma_f32_16x16x32_bf16 v[90:93], v[138:141], v[196:199], v[90:93]
	v_mfma_f32_16x16x32_bf16 v[78:81], v[130:133], v[204:207], v[78:81]
	v_mfma_f32_16x16x32_bf16 v[74:77], v[138:141], v[204:207], v[74:77]
	v_mfma_f32_16x16x32_bf16 v[126:129], v[134:137], v[166:169], v[126:129]
	v_mfma_f32_16x16x32_bf16 v[122:125], v[142:145], v[166:169], v[122:125]
	v_mfma_f32_16x16x32_bf16 v[110:113], v[134:137], v[186:189], v[110:113]
	v_mfma_f32_16x16x32_bf16 v[106:109], v[142:145], v[186:189], v[106:109]
	v_mfma_f32_16x16x32_bf16 v[94:97], v[134:137], v[200:203], v[94:97]
	v_mfma_f32_16x16x32_bf16 v[90:93], v[142:145], v[200:203], v[90:93]
	v_mfma_f32_16x16x32_bf16 v[78:81], v[134:137], v[208:211], v[78:81]
	v_mfma_f32_16x16x32_bf16 v[74:77], v[142:145], v[208:211], v[74:77]
	s_setprio 0
	s_setprio 1
	v_mfma_f32_16x16x32_bf16 v[118:121], v[146:149], v[162:165], v[118:121]
	v_mfma_f32_16x16x32_bf16 v[114:117], v[154:157], v[162:165], v[114:117]
	v_mfma_f32_16x16x32_bf16 v[102:105], v[146:149], v[170:173], v[102:105]
	v_mfma_f32_16x16x32_bf16 v[98:101], v[154:157], v[170:173], v[98:101]
	v_mfma_f32_16x16x32_bf16 v[86:89], v[146:149], v[196:199], v[86:89]
	v_mfma_f32_16x16x32_bf16 v[82:85], v[154:157], v[196:199], v[82:85]
	v_mfma_f32_16x16x32_bf16 v[70:73], v[146:149], v[204:207], v[70:73]
	v_mfma_f32_16x16x32_bf16 v[66:69], v[154:157], v[204:207], v[66:69]
	v_mfma_f32_16x16x32_bf16 v[118:121], v[150:153], v[166:169], v[118:121]
	v_mfma_f32_16x16x32_bf16 v[114:117], v[158:161], v[166:169], v[114:117]
	v_mfma_f32_16x16x32_bf16 v[102:105], v[150:153], v[186:189], v[102:105]
	v_mfma_f32_16x16x32_bf16 v[98:101], v[158:161], v[186:189], v[98:101]
	v_mfma_f32_16x16x32_bf16 v[86:89], v[150:153], v[200:203], v[86:89]
	v_mfma_f32_16x16x32_bf16 v[82:85], v[158:161], v[200:203], v[82:85]
	v_mfma_f32_16x16x32_bf16 v[70:73], v[150:153], v[208:211], v[70:73]
	v_mfma_f32_16x16x32_bf16 v[66:69], v[158:161], v[208:211], v[66:69]
	s_setprio 0
	s_barrier
	s_add_i32 s26, s41, s29
	v_lshl_add_u64 v[212:213], v[212:213], 0, s[58:59]
	s_mov_b32 m0, s26
	ds_read_b128 v[162:165], v216 offset:49152
	ds_read_b128 v[166:169], v216 offset:50176
	ds_read_b128 v[170:173], v216 offset:51200
	ds_read_b128 v[186:189], v216 offset:52224
	ds_read_b128 v[196:199], v216 offset:53248
	ds_read_b128 v[200:203], v216 offset:54272
	ds_read_b128 v[204:207], v216 offset:55296
	ds_read_b128 v[208:211], v216 offset:56320
	global_load_lds_dwordx4 v[212:213], off
	s_add_i32 m0, s26, 0x2000
	s_add_u32 s24, s24, 0x80080
	v_lshl_add_u64 v[212:213], v[218:219], 0, s[58:59]
	s_addc_u32 s25, s25, 0
	s_add_i32 s26, s42, s29
	global_load_lds_dwordx4 v[212:213], off
	v_lshl_add_u64 v[212:213], s[24:25], 0, v[178:179]
	s_mov_b32 m0, s26
	s_nop 0
	global_load_lds_dwordx4 v[212:213], off
	v_lshl_add_u64 v[212:213], s[24:25], 0, v[174:175]
	s_add_i32 m0, s26, 0x2000
	s_nop 0
	global_load_lds_dwordx4 v[212:213], off
	v_lshl_add_u64 v[212:213], v[220:221], 0, s[58:59]
	s_mov_b32 m0, s38
	s_nop 0
	global_load_lds_dwordx4 v[212:213], off
	v_lshl_add_u64 v[212:213], v[222:223], 0, s[58:59]
	s_mov_b32 m0, s39
	s_nop 0
	global_load_lds_dwordx4 v[212:213], off
	s_waitcnt vmcnt(8)
	s_waitcnt lgkmcnt(0)
	s_barrier
	s_setprio 1
	s_waitcnt lgkmcnt(0)
	v_mfma_f32_16x16x32_bf16 v[62:65], v[130:133], v[162:165], v[62:65]
	v_mfma_f32_16x16x32_bf16 v[58:61], v[138:141], v[162:165], v[58:61]
	v_mfma_f32_16x16x32_bf16 v[46:49], v[130:133], v[170:173], v[46:49]
	v_mfma_f32_16x16x32_bf16 v[42:45], v[138:141], v[170:173], v[42:45]
	v_mfma_f32_16x16x32_bf16 v[30:33], v[130:133], v[196:199], v[30:33]
	v_mfma_f32_16x16x32_bf16 v[26:29], v[138:141], v[196:199], v[26:29]
	v_mfma_f32_16x16x32_bf16 v[14:17], v[130:133], v[204:207], v[14:17]
	v_mfma_f32_16x16x32_bf16 v[10:13], v[138:141], v[204:207], v[10:13]
	v_mfma_f32_16x16x32_bf16 v[62:65], v[134:137], v[166:169], v[62:65]
	v_mfma_f32_16x16x32_bf16 v[58:61], v[142:145], v[166:169], v[58:61]
	v_mfma_f32_16x16x32_bf16 v[46:49], v[134:137], v[186:189], v[46:49]
	v_mfma_f32_16x16x32_bf16 v[42:45], v[142:145], v[186:189], v[42:45]
	v_mfma_f32_16x16x32_bf16 v[30:33], v[134:137], v[200:203], v[30:33]
	v_mfma_f32_16x16x32_bf16 v[26:29], v[142:145], v[200:203], v[26:29]
	v_mfma_f32_16x16x32_bf16 v[14:17], v[134:137], v[208:211], v[14:17]
	v_mfma_f32_16x16x32_bf16 v[10:13], v[142:145], v[208:211], v[10:13]
	s_setprio 0
	s_setprio 1
	v_mfma_f32_16x16x32_bf16 v[54:57], v[146:149], v[162:165], v[54:57]
	v_mfma_f32_16x16x32_bf16 v[50:53], v[154:157], v[162:165], v[50:53]
	v_mfma_f32_16x16x32_bf16 v[38:41], v[146:149], v[170:173], v[38:41]
	v_mfma_f32_16x16x32_bf16 v[34:37], v[154:157], v[170:173], v[34:37]
	v_mfma_f32_16x16x32_bf16 v[22:25], v[146:149], v[196:199], v[22:25]
	v_mfma_f32_16x16x32_bf16 v[18:21], v[154:157], v[196:199], v[18:21]
	v_mfma_f32_16x16x32_bf16 v[6:9], v[146:149], v[204:207], v[6:9]
	v_mfma_f32_16x16x32_bf16 v[2:5], v[154:157], v[204:207], v[2:5]
	v_mfma_f32_16x16x32_bf16 v[54:57], v[150:153], v[166:169], v[54:57]
	v_mfma_f32_16x16x32_bf16 v[50:53], v[158:161], v[166:169], v[50:53]
	v_mfma_f32_16x16x32_bf16 v[38:41], v[150:153], v[186:189], v[38:41]
	v_mfma_f32_16x16x32_bf16 v[34:37], v[158:161], v[186:189], v[34:37]
	v_mfma_f32_16x16x32_bf16 v[22:25], v[150:153], v[200:203], v[22:25]
	v_mfma_f32_16x16x32_bf16 v[18:21], v[158:161], v[200:203], v[18:21]
	v_mfma_f32_16x16x32_bf16 v[6:9], v[150:153], v[208:211], v[6:9]
	v_mfma_f32_16x16x32_bf16 v[2:5], v[158:161], v[208:211], v[2:5]
	s_setprio 0
	s_barrier
	s_add_i32 s40, s40, 2
	s_add_u32 s22, s22, 0x100
	s_addc_u32 s23, s23, 0
	s_add_u32 s21, s21, 0x100
	s_addc_u32 s33, s33, 0
	s_cmp_gt_u32 s40, 29
	s_cbranch_scc1 .Lpeel_done_1
	s_branch .LBB0_672
.Ltrip0_strict_1:
	s_add_u32 s24, s22, 0xfff80080
	s_addc_u32 s25, s23, -1
	s_add_i32 s41, 0, 0x10000
	s_cmp_eq_u32 s40, 28
	s_cselect_b32 s27, s11, s25
	s_cselect_b32 s26, s18, s24
	s_cselect_b32 s25, s9, s33
	s_cselect_b32 s24, s19, s21
	s_add_i32 s46, 0, 0x14000
	v_add_u32_e32 v142, s41, v214
	v_add_u32_e32 v158, s46, v214
	ds_read_b128 v[130:133], v142
	ds_read_b128 v[134:137], v142 offset:1024
	ds_read_b128 v[138:141], v142 offset:2048
	ds_read_b128 v[142:145], v142 offset:3072
	ds_read_b128 v[146:149], v158
	ds_read_b128 v[150:153], v158 offset:1024
	ds_read_b128 v[154:157], v158 offset:2048
	ds_read_b128 v[158:161], v158 offset:3072
	v_lshl_add_u64 v[212:213], s[22:23], 0, v[182:183]
	s_add_i32 m0, s17, 0xc000
	ds_read_b128 v[162:165], v216
	ds_read_b128 v[166:169], v216 offset:1024
	ds_read_b128 v[170:173], v216 offset:2048
	ds_read_b128 v[186:189], v216 offset:3072
	ds_read_b128 v[196:199], v216 offset:4096
	ds_read_b128 v[200:203], v216 offset:5120
	ds_read_b128 v[204:207], v216 offset:6144
	ds_read_b128 v[208:211], v216 offset:7168
	global_load_lds_dwordx4 v[212:213], off
	v_lshl_add_u64 v[212:213], s[22:23], 0, v[184:185]
	s_add_i32 m0, s17, 0xe000
	s_nop 0
	global_load_lds_dwordx4 v[212:213], off
	s_waitcnt vmcnt(8)
	s_waitcnt lgkmcnt(0)
	s_barrier
	s_setprio 1
	s_waitcnt lgkmcnt(0)
	v_mfma_f32_16x16x32_bf16 v[126:129], v[130:133], v[162:165], 0
	v_mfma_f32_16x16x32_bf16 v[122:125], v[138:141], v[162:165], 0
	v_mfma_f32_16x16x32_bf16 v[110:113], v[130:133], v[170:173], 0
	v_mfma_f32_16x16x32_bf16 v[106:109], v[138:141], v[170:173], 0
	v_mfma_f32_16x16x32_bf16 v[94:97], v[130:133], v[196:199], 0
	v_mfma_f32_16x16x32_bf16 v[90:93], v[138:141], v[196:199], 0
	v_mfma_f32_16x16x32_bf16 v[78:81], v[130:133], v[204:207], 0
	v_mfma_f32_16x16x32_bf16 v[74:77], v[138:141], v[204:207], 0
	v_mfma_f32_16x16x32_bf16 v[126:129], v[134:137], v[166:169], v[126:129]
	v_mfma_f32_16x16x32_bf16 v[122:125], v[142:145], v[166:169], v[122:125]
	v_mfma_f32_16x16x32_bf16 v[110:113], v[134:137], v[186:189], v[110:113]
	v_mfma_f32_16x16x32_bf16 v[106:109], v[142:145], v[186:189], v[106:109]
	v_mfma_f32_16x16x32_bf16 v[94:97], v[134:137], v[200:203], v[94:97]
	v_mfma_f32_16x16x32_bf16 v[90:93], v[142:145], v[200:203], v[90:93]
	v_mfma_f32_16x16x32_bf16 v[78:81], v[134:137], v[208:211], v[78:81]
	v_mfma_f32_16x16x32_bf16 v[74:77], v[142:145], v[208:211], v[74:77]
	s_setprio 0
	s_setprio 1
	v_mfma_f32_16x16x32_bf16 v[118:121], v[146:149], v[162:165], 0
	v_mfma_f32_16x16x32_bf16 v[114:117], v[154:157], v[162:165], 0
	v_mfma_f32_16x16x32_bf16 v[102:105], v[146:149], v[170:173], 0
	v_mfma_f32_16x16x32_bf16 v[98:101], v[154:157], v[170:173], 0
	v_mfma_f32_16x16x32_bf16 v[86:89], v[146:149], v[196:199], 0
	v_mfma_f32_16x16x32_bf16 v[82:85], v[154:157], v[196:199], 0
	v_mfma_f32_16x16x32_bf16 v[70:73], v[146:149], v[204:207], 0
	v_mfma_f32_16x16x32_bf16 v[66:69], v[154:157], v[204:207], 0
	v_mfma_f32_16x16x32_bf16 v[118:121], v[150:153], v[166:169], v[118:121]
	v_mfma_f32_16x16x32_bf16 v[114:117], v[158:161], v[166:169], v[114:117]
	v_mfma_f32_16x16x32_bf16 v[102:105], v[150:153], v[186:189], v[102:105]
	v_mfma_f32_16x16x32_bf16 v[98:101], v[158:161], v[186:189], v[98:101]
	v_mfma_f32_16x16x32_bf16 v[86:89], v[150:153], v[200:203], v[86:89]
	v_mfma_f32_16x16x32_bf16 v[82:85], v[158:161], v[200:203], v[82:85]
	v_mfma_f32_16x16x32_bf16 v[70:73], v[150:153], v[208:211], v[70:73]
	v_mfma_f32_16x16x32_bf16 v[66:69], v[158:161], v[208:211], v[66:69]
	s_setprio 0
	s_barrier
	s_add_i32 s41, s41, s29
	v_lshl_add_u64 v[212:213], s[24:25], 0, v[178:179]
	s_mov_b32 m0, s41
	ds_read_b128 v[162:165], v216 offset:16384
	ds_read_b128 v[166:169], v216 offset:17408
	ds_read_b128 v[170:173], v216 offset:18432
	ds_read_b128 v[186:189], v216 offset:19456
	ds_read_b128 v[196:199], v216 offset:20480
	ds_read_b128 v[200:203], v216 offset:21504
	ds_read_b128 v[204:207], v216 offset:22528
	ds_read_b128 v[208:211], v216 offset:23552
	global_load_lds_dwordx4 v[212:213], off
	s_add_i32 m0, s41, 0x2000
	s_add_u32 s42, s24, 0x80000
	v_lshl_add_u64 v[218:219], s[24:25], 0, v[174:175]
	s_addc_u32 s43, s25, 0
	s_add_i32 s41, s46, s29
	global_load_lds_dwordx4 v[218:219], off
	v_lshl_add_u64 v[220:221], s[42:43], 0, v[178:179]
	s_mov_b32 m0, s41
	v_lshl_add_u64 v[222:223], s[26:27], 0, v[176:177]
	global_load_lds_dwordx4 v[220:221], off
	v_lshl_add_u64 v[220:221], s[42:43], 0, v[174:175]
	s_add_i32 m0, s41, 0x2000
	s_nop 0
	global_load_lds_dwordx4 v[220:221], off
	v_lshl_add_u64 v[220:221], s[26:27], 0, v[180:181]
	s_mov_b32 m0, s17
	s_nop 0
	global_load_lds_dwordx4 v[220:221], off
	s_mov_b32 m0, s31
	s_nop 0
	global_load_lds_dwordx4 v[222:223], off
	s_waitcnt vmcnt(8)
	s_waitcnt lgkmcnt(0)
	s_barrier
	s_setprio 1
	s_waitcnt lgkmcnt(0)
	v_mfma_f32_16x16x32_bf16 v[62:65], v[130:133], v[162:165], 0
	v_mfma_f32_16x16x32_bf16 v[58:61], v[138:141], v[162:165], 0
	v_mfma_f32_16x16x32_bf16 v[46:49], v[130:133], v[170:173], 0
	v_mfma_f32_16x16x32_bf16 v[42:45], v[138:141], v[170:173], 0
	v_mfma_f32_16x16x32_bf16 v[30:33], v[130:133], v[196:199], 0
	v_mfma_f32_16x16x32_bf16 v[26:29], v[138:141], v[196:199], 0
	v_mfma_f32_16x16x32_bf16 v[14:17], v[130:133], v[204:207], 0
	v_mfma_f32_16x16x32_bf16 v[10:13], v[138:141], v[204:207], 0
	v_mfma_f32_16x16x32_bf16 v[62:65], v[134:137], v[166:169], v[62:65]
	v_mfma_f32_16x16x32_bf16 v[58:61], v[142:145], v[166:169], v[58:61]
	v_mfma_f32_16x16x32_bf16 v[46:49], v[134:137], v[186:189], v[46:49]
	v_mfma_f32_16x16x32_bf16 v[42:45], v[142:145], v[186:189], v[42:45]
	v_mfma_f32_16x16x32_bf16 v[30:33], v[134:137], v[200:203], v[30:33]
	v_mfma_f32_16x16x32_bf16 v[26:29], v[142:145], v[200:203], v[26:29]
	v_mfma_f32_16x16x32_bf16 v[14:17], v[134:137], v[208:211], v[14:17]
	v_mfma_f32_16x16x32_bf16 v[10:13], v[142:145], v[208:211], v[10:13]
	s_setprio 0
	s_setprio 1
	v_mfma_f32_16x16x32_bf16 v[54:57], v[146:149], v[162:165], 0
	v_mfma_f32_16x16x32_bf16 v[50:53], v[154:157], v[162:165], 0
	v_mfma_f32_16x16x32_bf16 v[38:41], v[146:149], v[170:173], 0
	v_mfma_f32_16x16x32_bf16 v[34:37], v[154:157], v[170:173], 0
	v_mfma_f32_16x16x32_bf16 v[22:25], v[146:149], v[196:199], 0
	v_mfma_f32_16x16x32_bf16 v[18:21], v[154:157], v[196:199], 0
	v_mfma_f32_16x16x32_bf16 v[6:9], v[146:149], v[204:207], 0
	v_mfma_f32_16x16x32_bf16 v[2:5], v[154:157], v[204:207], 0
	v_mfma_f32_16x16x32_bf16 v[54:57], v[150:153], v[166:169], v[54:57]
	v_mfma_f32_16x16x32_bf16 v[50:53], v[158:161], v[166:169], v[50:53]
	v_mfma_f32_16x16x32_bf16 v[38:41], v[150:153], v[186:189], v[38:41]
	v_mfma_f32_16x16x32_bf16 v[34:37], v[158:161], v[186:189], v[34:37]
	v_mfma_f32_16x16x32_bf16 v[22:25], v[150:153], v[200:203], v[22:25]
	v_mfma_f32_16x16x32_bf16 v[18:21], v[158:161], v[200:203], v[18:21]
	v_mfma_f32_16x16x32_bf16 v[6:9], v[150:153], v[208:211], v[6:9]
	v_mfma_f32_16x16x32_bf16 v[2:5], v[158:161], v[208:211], v[2:5]
	s_setprio 0
	s_barrier
	s_add_i32 s41, 0, 0x18000
	s_add_i32 s42, 0, 0x1c000
	v_add_u32_e32 v142, s41, v214
	v_add_u32_e32 v158, s42, v214
	ds_read_b128 v[130:133], v142
	ds_read_b128 v[134:137], v142 offset:1024
	ds_read_b128 v[138:141], v142 offset:2048
	ds_read_b128 v[142:145], v142 offset:3072
	ds_read_b128 v[146:149], v158
	ds_read_b128 v[150:153], v158 offset:1024
	ds_read_b128 v[154:157], v158 offset:2048
	ds_read_b128 v[158:161], v158 offset:3072
	s_add_u32 s26, s26, 0x80000
	s_addc_u32 s27, s27, 0
	s_mov_b32 m0, s34
	v_lshl_add_u64 v[224:225], s[26:27], 0, v[180:181]
	ds_read_b128 v[162:165], v216 offset:32768
	ds_read_b128 v[166:169], v216 offset:33792
	ds_read_b128 v[170:173], v216 offset:34816
	ds_read_b128 v[186:189], v216 offset:35840
	ds_read_b128 v[196:199], v216 offset:36864
	ds_read_b128 v[200:203], v216 offset:37888
	ds_read_b128 v[204:207], v216 offset:38912
	ds_read_b128 v[208:211], v216 offset:39936
	global_load_lds_dwordx4 v[224:225], off
	v_lshl_add_u64 v[224:225], s[26:27], 0, v[176:177]
	s_mov_b32 m0, s35
	s_nop 0
	global_load_lds_dwordx4 v[224:225], off
	s_waitcnt vmcnt(8)
	s_waitcnt lgkmcnt(0)
	s_barrier
	s_setprio 1
	s_waitcnt lgkmcnt(0)
	v_mfma_f32_16x16x32_bf16 v[126:129], v[130:133], v[162:165], v[126:129]
	v_mfma_f32_16x16x32_bf16 v[122:125], v[138:141], v[162:165], v[122:125]
	v_mfma_f32_16x16x32_bf16 v[110:113], v[130:133], v[170:173], v[110:113]
	v_mfma_f32_16x16x32_bf16 v[106:109], v[138:141], v[170:173], v[106:109]
	v_mfma_f32_16x16x32_bf16 v[94:97], v[130:133], v[196:199], v[94:97]
	v_mfma_f32_16x16x32_bf16 v[90:93], v[138:141], v[196:199], v[90:93]
	v_mfma_f32_16x16x32_bf16 v[78:81], v[130:133], v[204:207], v[78:81]
	v_mfma_f32_16x16x32_bf16 v[74:77], v[138:141], v[204:207], v[74:77]
	v_mfma_f32_16x16x32_bf16 v[126:129], v[134:137], v[166:169], v[126:129]
	v_mfma_f32_16x16x32_bf16 v[122:125], v[142:145], v[166:169], v[122:125]
	v_mfma_f32_16x16x32_bf16 v[110:113], v[134:137], v[186:189], v[110:113]
	v_mfma_f32_16x16x32_bf16 v[106:109], v[142:145], v[186:189], v[106:109]
	v_mfma_f32_16x16x32_bf16 v[94:97], v[134:137], v[200:203], v[94:97]
	v_mfma_f32_16x16x32_bf16 v[90:93], v[142:145], v[200:203], v[90:93]
	v_mfma_f32_16x16x32_bf16 v[78:81], v[134:137], v[208:211], v[78:81]
	v_mfma_f32_16x16x32_bf16 v[74:77], v[142:145], v[208:211], v[74:77]
	s_setprio 0
	s_setprio 1
	v_mfma_f32_16x16x32_bf16 v[118:121], v[146:149], v[162:165], v[118:121]
	v_mfma_f32_16x16x32_bf16 v[114:117], v[154:157], v[162:165], v[114:117]
	v_mfma_f32_16x16x32_bf16 v[102:105], v[146:149], v[170:173], v[102:105]
	v_mfma_f32_16x16x32_bf16 v[98:101], v[154:157], v[170:173], v[98:101]
	v_mfma_f32_16x16x32_bf16 v[86:89], v[146:149], v[196:199], v[86:89]
	v_mfma_f32_16x16x32_bf16 v[82:85], v[154:157], v[196:199], v[82:85]
	v_mfma_f32_16x16x32_bf16 v[70:73], v[146:149], v[204:207], v[70:73]
	v_mfma_f32_16x16x32_bf16 v[66:69], v[154:157], v[204:207], v[66:69]
	v_mfma_f32_16x16x32_bf16 v[118:121], v[150:153], v[166:169], v[118:121]
	v_mfma_f32_16x16x32_bf16 v[114:117], v[158:161], v[166:169], v[114:117]
	v_mfma_f32_16x16x32_bf16 v[102:105], v[150:153], v[186:189], v[102:105]
	v_mfma_f32_16x16x32_bf16 v[98:101], v[158:161], v[186:189], v[98:101]
	v_mfma_f32_16x16x32_bf16 v[86:89], v[150:153], v[200:203], v[86:89]
	v_mfma_f32_16x16x32_bf16 v[82:85], v[158:161], v[200:203], v[82:85]
	v_mfma_f32_16x16x32_bf16 v[70:73], v[150:153], v[208:211], v[70:73]
	v_mfma_f32_16x16x32_bf16 v[66:69], v[158:161], v[208:211], v[66:69]
	s_setprio 0
	s_barrier
	s_add_i32 s26, s41, s29
	v_lshl_add_u64 v[212:213], v[212:213], 0, s[58:59]
	s_mov_b32 m0, s26
	ds_read_b128 v[162:165], v216 offset:49152
	ds_read_b128 v[166:169], v216 offset:50176
	ds_read_b128 v[170:173], v216 offset:51200
	ds_read_b128 v[186:189], v216 offset:52224
	ds_read_b128 v[196:199], v216 offset:53248
	ds_read_b128 v[200:203], v216 offset:54272
	ds_read_b128 v[204:207], v216 offset:55296
	ds_read_b128 v[208:211], v216 offset:56320
	global_load_lds_dwordx4 v[212:213], off
	s_add_i32 m0, s26, 0x2000
	s_add_u32 s24, s24, 0x80080
	v_lshl_add_u64 v[212:213], v[218:219], 0, s[58:59]
	s_addc_u32 s25, s25, 0
	s_add_i32 s26, s42, s29
	global_load_lds_dwordx4 v[212:213], off
	v_lshl_add_u64 v[212:213], s[24:25], 0, v[178:179]
	s_mov_b32 m0, s26
	s_nop 0
	global_load_lds_dwordx4 v[212:213], off
	v_lshl_add_u64 v[212:213], s[24:25], 0, v[174:175]
	s_add_i32 m0, s26, 0x2000
	s_nop 0
	global_load_lds_dwordx4 v[212:213], off
	v_lshl_add_u64 v[212:213], v[220:221], 0, s[58:59]
	s_mov_b32 m0, s38
	s_nop 0
	global_load_lds_dwordx4 v[212:213], off
	v_lshl_add_u64 v[212:213], v[222:223], 0, s[58:59]
	s_mov_b32 m0, s39
	s_nop 0
	global_load_lds_dwordx4 v[212:213], off
	s_waitcnt vmcnt(8)
	s_waitcnt lgkmcnt(0)
	s_barrier
	s_setprio 1
	s_waitcnt lgkmcnt(0)
	v_mfma_f32_16x16x32_bf16 v[62:65], v[130:133], v[162:165], v[62:65]
	v_mfma_f32_16x16x32_bf16 v[58:61], v[138:141], v[162:165], v[58:61]
	v_mfma_f32_16x16x32_bf16 v[46:49], v[130:133], v[170:173], v[46:49]
	v_mfma_f32_16x16x32_bf16 v[42:45], v[138:141], v[170:173], v[42:45]
	v_mfma_f32_16x16x32_bf16 v[30:33], v[130:133], v[196:199], v[30:33]
	v_mfma_f32_16x16x32_bf16 v[26:29], v[138:141], v[196:199], v[26:29]
	v_mfma_f32_16x16x32_bf16 v[14:17], v[130:133], v[204:207], v[14:17]
	v_mfma_f32_16x16x32_bf16 v[10:13], v[138:141], v[204:207], v[10:13]
	v_mfma_f32_16x16x32_bf16 v[62:65], v[134:137], v[166:169], v[62:65]
	v_mfma_f32_16x16x32_bf16 v[58:61], v[142:145], v[166:169], v[58:61]
	v_mfma_f32_16x16x32_bf16 v[46:49], v[134:137], v[186:189], v[46:49]
	v_mfma_f32_16x16x32_bf16 v[42:45], v[142:145], v[186:189], v[42:45]
	v_mfma_f32_16x16x32_bf16 v[30:33], v[134:137], v[200:203], v[30:33]
	v_mfma_f32_16x16x32_bf16 v[26:29], v[142:145], v[200:203], v[26:29]
	v_mfma_f32_16x16x32_bf16 v[14:17], v[134:137], v[208:211], v[14:17]
	v_mfma_f32_16x16x32_bf16 v[10:13], v[142:145], v[208:211], v[10:13]
	s_setprio 0
	s_setprio 1
	v_mfma_f32_16x16x32_bf16 v[54:57], v[146:149], v[162:165], v[54:57]
	v_mfma_f32_16x16x32_bf16 v[50:53], v[154:157], v[162:165], v[50:53]
	v_mfma_f32_16x16x32_bf16 v[38:41], v[146:149], v[170:173], v[38:41]
	v_mfma_f32_16x16x32_bf16 v[34:37], v[154:157], v[170:173], v[34:37]
	v_mfma_f32_16x16x32_bf16 v[22:25], v[146:149], v[196:199], v[22:25]
	v_mfma_f32_16x16x32_bf16 v[18:21], v[154:157], v[196:199], v[18:21]
	v_mfma_f32_16x16x32_bf16 v[6:9], v[146:149], v[204:207], v[6:9]
	v_mfma_f32_16x16x32_bf16 v[2:5], v[154:157], v[204:207], v[2:5]
	v_mfma_f32_16x16x32_bf16 v[54:57], v[150:153], v[166:169], v[54:57]
	v_mfma_f32_16x16x32_bf16 v[50:53], v[158:161], v[166:169], v[50:53]
	v_mfma_f32_16x16x32_bf16 v[38:41], v[150:153], v[186:189], v[38:41]
	v_mfma_f32_16x16x32_bf16 v[34:37], v[158:161], v[186:189], v[34:37]
	v_mfma_f32_16x16x32_bf16 v[22:25], v[150:153], v[200:203], v[22:25]
	v_mfma_f32_16x16x32_bf16 v[18:21], v[158:161], v[200:203], v[18:21]
	v_mfma_f32_16x16x32_bf16 v[6:9], v[150:153], v[208:211], v[6:9]
	v_mfma_f32_16x16x32_bf16 v[2:5], v[158:161], v[208:211], v[2:5]
	s_setprio 0
	s_barrier
	s_add_i32 s40, s40, 2
	s_add_u32 s22, s22, 0x100
	s_addc_u32 s23, s23, 0
	s_add_u32 s21, s21, 0x100
	s_addc_u32 s33, s33, 0
	s_cmp_gt_u32 s40, 29
	s_cbranch_scc1 .Lpeel_done_1

.Lpeel_done_1:
	s_and_b64 vcc, exec, s[6:7]
	s_cbranch_vccz .LBB0_675
	s_barrier

.LBB0_747:
	s_ashr_i32 s9, s8, 31
	s_lshl_b64 s[10:11], s[8:9], 20
	s_add_u32 s10, s69, s10
	s_addc_u32 s11, s77, s11
	s_and_b64 s[12:13], s[4:5], exec
	s_cselect_b32 s9, s11, s17
	s_cselect_b32 s31, s10, s16
	s_ashr_i32 s7, s6, 31
	s_lshl_b64 s[12:13], s[6:7], 20
	v_readlane_b32 s22, v254, 42
	v_readlane_b32 s23, v254, 43
	s_add_u32 s12, s22, s12
	s_addc_u32 s13, s23, s13
	s_and_b64 s[22:23], s[4:5], exec
	s_cselect_b32 s7, s13, s21
	s_cselect_b32 s33, s12, s20
	s_add_u32 s16, s16, 0x80080
	s_addc_u32 s17, s17, 0
	s_add_u32 s34, s20, 0x100
	s_addc_u32 s35, s21, 0
	s_mov_b32 s36, -2
	v_readlane_b32 s37, v255, 49
	s_nop 3
	s_cmp_eq_u32 s37, 3
	v_writelane_b32 v255, 3, 49
	s_cbranch_scc0 .Ltrip0_strict_2
	s_add_u32 s20, s16, 0xfff80080
	s_addc_u32 s21, s17, -1
	s_add_i32 s37, 0, 0x10000
	s_cmp_eq_u32 s36, 28
	s_cselect_b32 s23, s9, s21
	s_cselect_b32 s22, s31, s20
	s_cselect_b32 s21, s7, s35
	s_cselect_b32 s20, s33, s34
	s_add_i32 s40, 0, 0x14000
	v_add_u32_e32 v142, s37, v238
	v_add_u32_e32 v158, s40, v238
	ds_read_b128 v[130:133], v142
	ds_read_b128 v[134:137], v142 offset:1024
	ds_read_b128 v[138:141], v142 offset:2048
	ds_read_b128 v[142:145], v142 offset:3072
	ds_read_b128 v[146:149], v158
	ds_read_b128 v[150:153], v158 offset:1024
	ds_read_b128 v[154:157], v158 offset:2048
	ds_read_b128 v[158:161], v158 offset:3072
	v_lshl_add_u64 v[210:211], s[16:17], 0, v[206:207]
	s_add_i32 m0, s25, 0xc000
	ds_read_b128 v[162:165], v240
	ds_read_b128 v[166:169], v240 offset:1024
	ds_read_b128 v[170:173], v240 offset:2048
	ds_read_b128 v[174:177], v240 offset:3072
	ds_read_b128 v[178:181], v240 offset:4096
	ds_read_b128 v[182:185], v240 offset:5120
	ds_read_b128 v[186:189], v240 offset:6144
	ds_read_b128 v[196:199], v240 offset:7168
	global_load_lds_dwordx4 v[210:211], off
	v_lshl_add_u64 v[210:211], s[16:17], 0, v[208:209]
	s_add_i32 m0, s25, 0xe000
	s_nop 0
	global_load_lds_dwordx4 v[210:211], off
	s_waitcnt vmcnt(24)
	s_waitcnt lgkmcnt(0)
	s_barrier
	s_setprio 1
	s_waitcnt lgkmcnt(0)
	v_mfma_f32_16x16x32_bf16 v[126:129], v[130:133], v[162:165], 0
	v_mfma_f32_16x16x32_bf16 v[122:125], v[138:141], v[162:165], 0
	v_mfma_f32_16x16x32_bf16 v[110:113], v[130:133], v[170:173], 0
	v_mfma_f32_16x16x32_bf16 v[106:109], v[138:141], v[170:173], 0
	v_mfma_f32_16x16x32_bf16 v[98:101], v[130:133], v[178:181], 0
	v_mfma_f32_16x16x32_bf16 v[90:93], v[138:141], v[178:181], 0
	v_mfma_f32_16x16x32_bf16 v[82:85], v[130:133], v[186:189], 0
	v_mfma_f32_16x16x32_bf16 v[74:77], v[138:141], v[186:189], 0
	v_mfma_f32_16x16x32_bf16 v[126:129], v[134:137], v[166:169], v[126:129]
	v_mfma_f32_16x16x32_bf16 v[122:125], v[142:145], v[166:169], v[122:125]
	v_mfma_f32_16x16x32_bf16 v[110:113], v[134:137], v[174:177], v[110:113]
	v_mfma_f32_16x16x32_bf16 v[106:109], v[142:145], v[174:177], v[106:109]
	v_mfma_f32_16x16x32_bf16 v[98:101], v[134:137], v[182:185], v[98:101]
	v_mfma_f32_16x16x32_bf16 v[90:93], v[142:145], v[182:185], v[90:93]
	v_mfma_f32_16x16x32_bf16 v[82:85], v[134:137], v[196:199], v[82:85]
	v_mfma_f32_16x16x32_bf16 v[74:77], v[142:145], v[196:199], v[74:77]
	s_setprio 0
	s_setprio 1
	v_mfma_f32_16x16x32_bf16 v[118:121], v[146:149], v[162:165], 0
	v_mfma_f32_16x16x32_bf16 v[114:117], v[154:157], v[162:165], 0
	v_mfma_f32_16x16x32_bf16 v[102:105], v[146:149], v[170:173], 0
	v_mfma_f32_16x16x32_bf16 v[94:97], v[154:157], v[170:173], 0
	v_mfma_f32_16x16x32_bf16 v[86:89], v[146:149], v[178:181], 0
	v_mfma_f32_16x16x32_bf16 v[78:81], v[154:157], v[178:181], 0
	v_mfma_f32_16x16x32_bf16 v[70:73], v[146:149], v[186:189], 0
	v_mfma_f32_16x16x32_bf16 v[66:69], v[154:157], v[186:189], 0
	v_mfma_f32_16x16x32_bf16 v[118:121], v[150:153], v[166:169], v[118:121]
	v_mfma_f32_16x16x32_bf16 v[114:117], v[158:161], v[166:169], v[114:117]
	v_mfma_f32_16x16x32_bf16 v[102:105], v[150:153], v[174:177], v[102:105]
	v_mfma_f32_16x16x32_bf16 v[94:97], v[158:161], v[174:177], v[94:97]
	v_mfma_f32_16x16x32_bf16 v[86:89], v[150:153], v[182:185], v[86:89]
	v_mfma_f32_16x16x32_bf16 v[78:81], v[158:161], v[182:185], v[78:81]
	v_mfma_f32_16x16x32_bf16 v[70:73], v[150:153], v[196:199], v[70:73]
	v_mfma_f32_16x16x32_bf16 v[66:69], v[158:161], v[196:199], v[66:69]
	s_setprio 0
	s_barrier
	s_add_i32 s37, s37, s24
	v_lshl_add_u64 v[210:211], s[20:21], 0, v[190:191]
	s_mov_b32 m0, s37
	ds_read_b128 v[162:165], v240 offset:16384
	ds_read_b128 v[166:169], v240 offset:17408
	ds_read_b128 v[170:173], v240 offset:18432
	ds_read_b128 v[174:177], v240 offset:19456
	ds_read_b128 v[178:181], v240 offset:20480
	ds_read_b128 v[182:185], v240 offset:21504
	ds_read_b128 v[186:189], v240 offset:22528
	ds_read_b128 v[196:199], v240 offset:23552
	global_load_lds_dwordx4 v[210:211], off
	s_add_i32 m0, s37, 0x2000
	s_add_u32 s38, s20, 0x80000
	v_lshl_add_u64 v[212:213], s[20:21], 0, v[204:205]
	s_addc_u32 s39, s21, 0
	s_add_i32 s37, s40, s24
	global_load_lds_dwordx4 v[212:213], off
	v_lshl_add_u64 v[214:215], s[38:39], 0, v[190:191]
	s_mov_b32 m0, s37
	v_lshl_add_u64 v[216:217], s[22:23], 0, v[202:203]
	global_load_lds_dwordx4 v[214:215], off
	v_lshl_add_u64 v[214:215], s[38:39], 0, v[204:205]
	s_add_i32 m0, s37, 0x2000
	s_nop 0
	global_load_lds_dwordx4 v[214:215], off
	v_lshl_add_u64 v[214:215], s[22:23], 0, v[200:201]
	s_mov_b32 m0, s25
	s_nop 0
	global_load_lds_dwordx4 v[214:215], off
	s_mov_b32 m0, s26
	s_nop 0
	global_load_lds_dwordx4 v[216:217], off
	s_waitcnt vmcnt(24)
	s_waitcnt lgkmcnt(0)
	s_barrier
	s_setprio 1
	s_waitcnt lgkmcnt(0)
	v_mfma_f32_16x16x32_bf16 v[62:65], v[130:133], v[162:165], 0
	v_mfma_f32_16x16x32_bf16 v[58:61], v[138:141], v[162:165], 0
	v_mfma_f32_16x16x32_bf16 v[50:53], v[130:133], v[170:173], 0
	v_mfma_f32_16x16x32_bf16 v[42:45], v[138:141], v[170:173], 0
	v_mfma_f32_16x16x32_bf16 v[34:37], v[130:133], v[178:181], 0
	v_mfma_f32_16x16x32_bf16 v[26:29], v[138:141], v[178:181], 0
	v_mfma_f32_16x16x32_bf16 v[18:21], v[130:133], v[186:189], 0
	v_mfma_f32_16x16x32_bf16 v[10:13], v[138:141], v[186:189], 0
	v_mfma_f32_16x16x32_bf16 v[62:65], v[134:137], v[166:169], v[62:65]
	v_mfma_f32_16x16x32_bf16 v[58:61], v[142:145], v[166:169], v[58:61]
	v_mfma_f32_16x16x32_bf16 v[50:53], v[134:137], v[174:177], v[50:53]
	v_mfma_f32_16x16x32_bf16 v[42:45], v[142:145], v[174:177], v[42:45]
	v_mfma_f32_16x16x32_bf16 v[34:37], v[134:137], v[182:185], v[34:37]
	v_mfma_f32_16x16x32_bf16 v[26:29], v[142:145], v[182:185], v[26:29]
	v_mfma_f32_16x16x32_bf16 v[18:21], v[134:137], v[196:199], v[18:21]
	v_mfma_f32_16x16x32_bf16 v[10:13], v[142:145], v[196:199], v[10:13]
	s_setprio 0
	s_setprio 1
	v_mfma_f32_16x16x32_bf16 v[54:57], v[146:149], v[162:165], 0
	v_mfma_f32_16x16x32_bf16 v[46:49], v[154:157], v[162:165], 0
	v_mfma_f32_16x16x32_bf16 v[38:41], v[146:149], v[170:173], 0
	v_mfma_f32_16x16x32_bf16 v[30:33], v[154:157], v[170:173], 0
	v_mfma_f32_16x16x32_bf16 v[22:25], v[146:149], v[178:181], 0
	v_mfma_f32_16x16x32_bf16 v[14:17], v[154:157], v[178:181], 0
	v_mfma_f32_16x16x32_bf16 v[6:9], v[146:149], v[186:189], 0
	v_mfma_f32_16x16x32_bf16 v[2:5], v[154:157], v[186:189], 0
	v_mfma_f32_16x16x32_bf16 v[54:57], v[150:153], v[166:169], v[54:57]
	v_mfma_f32_16x16x32_bf16 v[46:49], v[158:161], v[166:169], v[46:49]
	v_mfma_f32_16x16x32_bf16 v[38:41], v[150:153], v[174:177], v[38:41]
	v_mfma_f32_16x16x32_bf16 v[30:33], v[158:161], v[174:177], v[30:33]
	v_mfma_f32_16x16x32_bf16 v[22:25], v[150:153], v[182:185], v[22:25]
	v_mfma_f32_16x16x32_bf16 v[14:17], v[158:161], v[182:185], v[14:17]
	v_mfma_f32_16x16x32_bf16 v[6:9], v[150:153], v[196:199], v[6:9]
	v_mfma_f32_16x16x32_bf16 v[2:5], v[158:161], v[196:199], v[2:5]
	s_setprio 0
	s_barrier
	s_add_i32 s37, 0, 0x18000
	s_add_i32 s38, 0, 0x1c000
	v_add_u32_e32 v142, s37, v238
	v_add_u32_e32 v158, s38, v238
	ds_read_b128 v[130:133], v142
	ds_read_b128 v[134:137], v142 offset:1024
	ds_read_b128 v[138:141], v142 offset:2048
	ds_read_b128 v[142:145], v142 offset:3072
	ds_read_b128 v[146:149], v158
	ds_read_b128 v[150:153], v158 offset:1024
	ds_read_b128 v[154:157], v158 offset:2048
	ds_read_b128 v[158:161], v158 offset:3072
	s_add_u32 s22, s22, 0x80000
	s_addc_u32 s23, s23, 0
	s_mov_b32 m0, s27
	v_lshl_add_u64 v[218:219], s[22:23], 0, v[200:201]
	ds_read_b128 v[162:165], v240 offset:32768
	ds_read_b128 v[166:169], v240 offset:33792
	ds_read_b128 v[170:173], v240 offset:34816
	ds_read_b128 v[174:177], v240 offset:35840
	ds_read_b128 v[178:181], v240 offset:36864
	ds_read_b128 v[182:185], v240 offset:37888
	ds_read_b128 v[186:189], v240 offset:38912
	ds_read_b128 v[196:199], v240 offset:39936
	global_load_lds_dwordx4 v[218:219], off
	v_lshl_add_u64 v[218:219], s[22:23], 0, v[202:203]
	s_mov_b32 m0, s28
	s_nop 0
	global_load_lds_dwordx4 v[218:219], off
	s_waitcnt vmcnt(8)
	s_waitcnt lgkmcnt(0)
	s_barrier
	s_setprio 1
	s_waitcnt lgkmcnt(0)
	v_mfma_f32_16x16x32_bf16 v[126:129], v[130:133], v[162:165], v[126:129]
	v_mfma_f32_16x16x32_bf16 v[122:125], v[138:141], v[162:165], v[122:125]
	v_mfma_f32_16x16x32_bf16 v[110:113], v[130:133], v[170:173], v[110:113]
	v_mfma_f32_16x16x32_bf16 v[106:109], v[138:141], v[170:173], v[106:109]
	v_mfma_f32_16x16x32_bf16 v[98:101], v[130:133], v[178:181], v[98:101]
	v_mfma_f32_16x16x32_bf16 v[90:93], v[138:141], v[178:181], v[90:93]
	v_mfma_f32_16x16x32_bf16 v[82:85], v[130:133], v[186:189], v[82:85]
	v_mfma_f32_16x16x32_bf16 v[74:77], v[138:141], v[186:189], v[74:77]
	v_mfma_f32_16x16x32_bf16 v[126:129], v[134:137], v[166:169], v[126:129]
	v_mfma_f32_16x16x32_bf16 v[122:125], v[142:145], v[166:169], v[122:125]
	v_mfma_f32_16x16x32_bf16 v[110:113], v[134:137], v[174:177], v[110:113]
	v_mfma_f32_16x16x32_bf16 v[106:109], v[142:145], v[174:177], v[106:109]
	v_mfma_f32_16x16x32_bf16 v[98:101], v[134:137], v[182:185], v[98:101]
	v_mfma_f32_16x16x32_bf16 v[90:93], v[142:145], v[182:185], v[90:93]
	v_mfma_f32_16x16x32_bf16 v[82:85], v[134:137], v[196:199], v[82:85]
	v_mfma_f32_16x16x32_bf16 v[74:77], v[142:145], v[196:199], v[74:77]
	s_setprio 0
	s_setprio 1
	v_mfma_f32_16x16x32_bf16 v[118:121], v[146:149], v[162:165], v[118:121]
	v_mfma_f32_16x16x32_bf16 v[114:117], v[154:157], v[162:165], v[114:117]
	v_mfma_f32_16x16x32_bf16 v[102:105], v[146:149], v[170:173], v[102:105]
	v_mfma_f32_16x16x32_bf16 v[94:97], v[154:157], v[170:173], v[94:97]
	v_mfma_f32_16x16x32_bf16 v[86:89], v[146:149], v[178:181], v[86:89]
	v_mfma_f32_16x16x32_bf16 v[78:81], v[154:157], v[178:181], v[78:81]
	v_mfma_f32_16x16x32_bf16 v[70:73], v[146:149], v[186:189], v[70:73]
	v_mfma_f32_16x16x32_bf16 v[66:69], v[154:157], v[186:189], v[66:69]
	v_mfma_f32_16x16x32_bf16 v[118:121], v[150:153], v[166:169], v[118:121]
	v_mfma_f32_16x16x32_bf16 v[114:117], v[158:161], v[166:169], v[114:117]
	v_mfma_f32_16x16x32_bf16 v[102:105], v[150:153], v[174:177], v[102:105]
	v_mfma_f32_16x16x32_bf16 v[94:97], v[158:161], v[174:177], v[94:97]
	v_mfma_f32_16x16x32_bf16 v[86:89], v[150:153], v[182:185], v[86:89]
	v_mfma_f32_16x16x32_bf16 v[78:81], v[158:161], v[182:185], v[78:81]
	v_mfma_f32_16x16x32_bf16 v[70:73], v[150:153], v[196:199], v[70:73]
	v_mfma_f32_16x16x32_bf16 v[66:69], v[158:161], v[196:199], v[66:69]
	s_setprio 0
	s_barrier
	s_add_i32 s22, s37, s24
	v_lshl_add_u64 v[210:211], v[210:211], 0, s[58:59]
	s_mov_b32 m0, s22
	ds_read_b128 v[162:165], v240 offset:49152
	ds_read_b128 v[166:169], v240 offset:50176
	ds_read_b128 v[170:173], v240 offset:51200
	ds_read_b128 v[174:177], v240 offset:52224
	ds_read_b128 v[178:181], v240 offset:53248
	ds_read_b128 v[182:185], v240 offset:54272
	ds_read_b128 v[186:189], v240 offset:55296
	ds_read_b128 v[196:199], v240 offset:56320
	global_load_lds_dwordx4 v[210:211], off
	s_add_i32 m0, s22, 0x2000
	s_add_u32 s20, s20, 0x80080
	v_lshl_add_u64 v[210:211], v[212:213], 0, s[58:59]
	s_addc_u32 s21, s21, 0
	s_add_i32 s22, s38, s24
	global_load_lds_dwordx4 v[210:211], off
	v_lshl_add_u64 v[210:211], s[20:21], 0, v[190:191]
	s_mov_b32 m0, s22
	s_nop 0
	global_load_lds_dwordx4 v[210:211], off
	v_lshl_add_u64 v[210:211], s[20:21], 0, v[204:205]
	s_add_i32 m0, s22, 0x2000
	s_nop 0
	global_load_lds_dwordx4 v[210:211], off
	v_lshl_add_u64 v[210:211], v[214:215], 0, s[58:59]
	s_mov_b32 m0, s29
	s_nop 0
	global_load_lds_dwordx4 v[210:211], off
	v_lshl_add_u64 v[210:211], v[216:217], 0, s[58:59]
	s_mov_b32 m0, s30
	s_nop 0
	global_load_lds_dwordx4 v[210:211], off
	s_waitcnt vmcnt(8)
	s_waitcnt lgkmcnt(0)
	s_barrier
	s_setprio 1
	s_waitcnt lgkmcnt(0)
	v_mfma_f32_16x16x32_bf16 v[62:65], v[130:133], v[162:165], v[62:65]
	v_mfma_f32_16x16x32_bf16 v[58:61], v[138:141], v[162:165], v[58:61]
	v_mfma_f32_16x16x32_bf16 v[50:53], v[130:133], v[170:173], v[50:53]
	v_mfma_f32_16x16x32_bf16 v[42:45], v[138:141], v[170:173], v[42:45]
	v_mfma_f32_16x16x32_bf16 v[34:37], v[130:133], v[178:181], v[34:37]
	v_mfma_f32_16x16x32_bf16 v[26:29], v[138:141], v[178:181], v[26:29]
	v_mfma_f32_16x16x32_bf16 v[18:21], v[130:133], v[186:189], v[18:21]
	v_mfma_f32_16x16x32_bf16 v[10:13], v[138:141], v[186:189], v[10:13]
	v_mfma_f32_16x16x32_bf16 v[62:65], v[134:137], v[166:169], v[62:65]
	v_mfma_f32_16x16x32_bf16 v[58:61], v[142:145], v[166:169], v[58:61]
	v_mfma_f32_16x16x32_bf16 v[50:53], v[134:137], v[174:177], v[50:53]
	v_mfma_f32_16x16x32_bf16 v[42:45], v[142:145], v[174:177], v[42:45]
	v_mfma_f32_16x16x32_bf16 v[34:37], v[134:137], v[182:185], v[34:37]
	v_mfma_f32_16x16x32_bf16 v[26:29], v[142:145], v[182:185], v[26:29]
	v_mfma_f32_16x16x32_bf16 v[18:21], v[134:137], v[196:199], v[18:21]
	v_mfma_f32_16x16x32_bf16 v[10:13], v[142:145], v[196:199], v[10:13]
	s_setprio 0
	s_setprio 1
	v_mfma_f32_16x16x32_bf16 v[54:57], v[146:149], v[162:165], v[54:57]
	v_mfma_f32_16x16x32_bf16 v[46:49], v[154:157], v[162:165], v[46:49]
	v_mfma_f32_16x16x32_bf16 v[38:41], v[146:149], v[170:173], v[38:41]
	v_mfma_f32_16x16x32_bf16 v[30:33], v[154:157], v[170:173], v[30:33]
	v_mfma_f32_16x16x32_bf16 v[22:25], v[146:149], v[178:181], v[22:25]
	v_mfma_f32_16x16x32_bf16 v[14:17], v[154:157], v[178:181], v[14:17]
	v_mfma_f32_16x16x32_bf16 v[6:9], v[146:149], v[186:189], v[6:9]
	v_mfma_f32_16x16x32_bf16 v[2:5], v[154:157], v[186:189], v[2:5]
	v_mfma_f32_16x16x32_bf16 v[54:57], v[150:153], v[166:169], v[54:57]
	v_mfma_f32_16x16x32_bf16 v[46:49], v[158:161], v[166:169], v[46:49]
	v_mfma_f32_16x16x32_bf16 v[38:41], v[150:153], v[174:177], v[38:41]
	v_mfma_f32_16x16x32_bf16 v[30:33], v[158:161], v[174:177], v[30:33]
	v_mfma_f32_16x16x32_bf16 v[22:25], v[150:153], v[182:185], v[22:25]
	v_mfma_f32_16x16x32_bf16 v[14:17], v[158:161], v[182:185], v[14:17]
	v_mfma_f32_16x16x32_bf16 v[6:9], v[150:153], v[196:199], v[6:9]
	v_mfma_f32_16x16x32_bf16 v[2:5], v[158:161], v[196:199], v[2:5]
	s_setprio 0
	s_barrier
	s_add_i32 s36, s36, 2
	s_add_u32 s16, s16, 0x100
	s_addc_u32 s17, s17, 0
	s_add_u32 s34, s34, 0x100
	s_addc_u32 s35, s35, 0
	s_cmp_gt_u32 s36, 29
	s_cbranch_scc1 .Lpeel_done_2
	s_branch .LBB0_748
.Ltrip0_strict_2:
	s_add_u32 s20, s16, 0xfff80080
	s_addc_u32 s21, s17, -1
	s_add_i32 s37, 0, 0x10000
	s_cmp_eq_u32 s36, 28
	s_cselect_b32 s23, s9, s21
	s_cselect_b32 s22, s31, s20
	s_cselect_b32 s21, s7, s35
	s_cselect_b32 s20, s33, s34
	s_add_i32 s40, 0, 0x14000
	v_add_u32_e32 v142, s37, v238
	v_add_u32_e32 v158, s40, v238
	ds_read_b128 v[130:133], v142
	ds_read_b128 v[134:137], v142 offset:1024
	ds_read_b128 v[138:141], v142 offset:2048
	ds_read_b128 v[142:145], v142 offset:3072
	ds_read_b128 v[146:149], v158
	ds_read_b128 v[150:153], v158 offset:1024
	ds_read_b128 v[154:157], v158 offset:2048
	ds_read_b128 v[158:161], v158 offset:3072
	v_lshl_add_u64 v[210:211], s[16:17], 0, v[206:207]
	s_add_i32 m0, s25, 0xc000
	ds_read_b128 v[162:165], v240
	ds_read_b128 v[166:169], v240 offset:1024
	ds_read_b128 v[170:173], v240 offset:2048
	ds_read_b128 v[174:177], v240 offset:3072
	ds_read_b128 v[178:181], v240 offset:4096
	ds_read_b128 v[182:185], v240 offset:5120
	ds_read_b128 v[186:189], v240 offset:6144
	ds_read_b128 v[196:199], v240 offset:7168
	global_load_lds_dwordx4 v[210:211], off
	v_lshl_add_u64 v[210:211], s[16:17], 0, v[208:209]
	s_add_i32 m0, s25, 0xe000
	s_nop 0
	global_load_lds_dwordx4 v[210:211], off
	s_waitcnt vmcnt(8)
	s_waitcnt lgkmcnt(0)
	s_barrier
	s_setprio 1
	s_waitcnt lgkmcnt(0)
	v_mfma_f32_16x16x32_bf16 v[126:129], v[130:133], v[162:165], 0
	v_mfma_f32_16x16x32_bf16 v[122:125], v[138:141], v[162:165], 0
	v_mfma_f32_16x16x32_bf16 v[110:113], v[130:133], v[170:173], 0
	v_mfma_f32_16x16x32_bf16 v[106:109], v[138:141], v[170:173], 0
	v_mfma_f32_16x16x32_bf16 v[98:101], v[130:133], v[178:181], 0
	v_mfma_f32_16x16x32_bf16 v[90:93], v[138:141], v[178:181], 0
	v_mfma_f32_16x16x32_bf16 v[82:85], v[130:133], v[186:189], 0
	v_mfma_f32_16x16x32_bf16 v[74:77], v[138:141], v[186:189], 0
	v_mfma_f32_16x16x32_bf16 v[126:129], v[134:137], v[166:169], v[126:129]
	v_mfma_f32_16x16x32_bf16 v[122:125], v[142:145], v[166:169], v[122:125]
	v_mfma_f32_16x16x32_bf16 v[110:113], v[134:137], v[174:177], v[110:113]
	v_mfma_f32_16x16x32_bf16 v[106:109], v[142:145], v[174:177], v[106:109]
	v_mfma_f32_16x16x32_bf16 v[98:101], v[134:137], v[182:185], v[98:101]
	v_mfma_f32_16x16x32_bf16 v[90:93], v[142:145], v[182:185], v[90:93]
	v_mfma_f32_16x16x32_bf16 v[82:85], v[134:137], v[196:199], v[82:85]
	v_mfma_f32_16x16x32_bf16 v[74:77], v[142:145], v[196:199], v[74:77]
	s_setprio 0
	s_setprio 1
	v_mfma_f32_16x16x32_bf16 v[118:121], v[146:149], v[162:165], 0
	v_mfma_f32_16x16x32_bf16 v[114:117], v[154:157], v[162:165], 0
	v_mfma_f32_16x16x32_bf16 v[102:105], v[146:149], v[170:173], 0
	v_mfma_f32_16x16x32_bf16 v[94:97], v[154:157], v[170:173], 0
	v_mfma_f32_16x16x32_bf16 v[86:89], v[146:149], v[178:181], 0
	v_mfma_f32_16x16x32_bf16 v[78:81], v[154:157], v[178:181], 0
	v_mfma_f32_16x16x32_bf16 v[70:73], v[146:149], v[186:189], 0
	v_mfma_f32_16x16x32_bf16 v[66:69], v[154:157], v[186:189], 0
	v_mfma_f32_16x16x32_bf16 v[118:121], v[150:153], v[166:169], v[118:121]
	v_mfma_f32_16x16x32_bf16 v[114:117], v[158:161], v[166:169], v[114:117]
	v_mfma_f32_16x16x32_bf16 v[102:105], v[150:153], v[174:177], v[102:105]
	v_mfma_f32_16x16x32_bf16 v[94:97], v[158:161], v[174:177], v[94:97]
	v_mfma_f32_16x16x32_bf16 v[86:89], v[150:153], v[182:185], v[86:89]
	v_mfma_f32_16x16x32_bf16 v[78:81], v[158:161], v[182:185], v[78:81]
	v_mfma_f32_16x16x32_bf16 v[70:73], v[150:153], v[196:199], v[70:73]
	v_mfma_f32_16x16x32_bf16 v[66:69], v[158:161], v[196:199], v[66:69]
	s_setprio 0
	s_barrier
	s_add_i32 s37, s37, s24
	v_lshl_add_u64 v[210:211], s[20:21], 0, v[190:191]
	s_mov_b32 m0, s37
	ds_read_b128 v[162:165], v240 offset:16384
	ds_read_b128 v[166:169], v240 offset:17408
	ds_read_b128 v[170:173], v240 offset:18432
	ds_read_b128 v[174:177], v240 offset:19456
	ds_read_b128 v[178:181], v240 offset:20480
	ds_read_b128 v[182:185], v240 offset:21504
	ds_read_b128 v[186:189], v240 offset:22528
	ds_read_b128 v[196:199], v240 offset:23552
	global_load_lds_dwordx4 v[210:211], off
	s_add_i32 m0, s37, 0x2000
	s_add_u32 s38, s20, 0x80000
	v_lshl_add_u64 v[212:213], s[20:21], 0, v[204:205]
	s_addc_u32 s39, s21, 0
	s_add_i32 s37, s40, s24
	global_load_lds_dwordx4 v[212:213], off
	v_lshl_add_u64 v[214:215], s[38:39], 0, v[190:191]
	s_mov_b32 m0, s37
	v_lshl_add_u64 v[216:217], s[22:23], 0, v[202:203]
	global_load_lds_dwordx4 v[214:215], off
	v_lshl_add_u64 v[214:215], s[38:39], 0, v[204:205]
	s_add_i32 m0, s37, 0x2000
	s_nop 0
	global_load_lds_dwordx4 v[214:215], off
	v_lshl_add_u64 v[214:215], s[22:23], 0, v[200:201]
	s_mov_b32 m0, s25
	s_nop 0
	global_load_lds_dwordx4 v[214:215], off
	s_mov_b32 m0, s26
	s_nop 0
	global_load_lds_dwordx4 v[216:217], off
	s_waitcnt vmcnt(8)
	s_waitcnt lgkmcnt(0)
	s_barrier
	s_setprio 1
	s_waitcnt lgkmcnt(0)
	v_mfma_f32_16x16x32_bf16 v[62:65], v[130:133], v[162:165], 0
	v_mfma_f32_16x16x32_bf16 v[58:61], v[138:141], v[162:165], 0
	v_mfma_f32_16x16x32_bf16 v[50:53], v[130:133], v[170:173], 0
	v_mfma_f32_16x16x32_bf16 v[42:45], v[138:141], v[170:173], 0
	v_mfma_f32_16x16x32_bf16 v[34:37], v[130:133], v[178:181], 0
	v_mfma_f32_16x16x32_bf16 v[26:29], v[138:141], v[178:181], 0
	v_mfma_f32_16x16x32_bf16 v[18:21], v[130:133], v[186:189], 0
	v_mfma_f32_16x16x32_bf16 v[10:13], v[138:141], v[186:189], 0
	v_mfma_f32_16x16x32_bf16 v[62:65], v[134:137], v[166:169], v[62:65]
	v_mfma_f32_16x16x32_bf16 v[58:61], v[142:145], v[166:169], v[58:61]
	v_mfma_f32_16x16x32_bf16 v[50:53], v[134:137], v[174:177], v[50:53]
	v_mfma_f32_16x16x32_bf16 v[42:45], v[142:145], v[174:177], v[42:45]
	v_mfma_f32_16x16x32_bf16 v[34:37], v[134:137], v[182:185], v[34:37]
	v_mfma_f32_16x16x32_bf16 v[26:29], v[142:145], v[182:185], v[26:29]
	v_mfma_f32_16x16x32_bf16 v[18:21], v[134:137], v[196:199], v[18:21]
	v_mfma_f32_16x16x32_bf16 v[10:13], v[142:145], v[196:199], v[10:13]
	s_setprio 0
	s_setprio 1
	v_mfma_f32_16x16x32_bf16 v[54:57], v[146:149], v[162:165], 0
	v_mfma_f32_16x16x32_bf16 v[46:49], v[154:157], v[162:165], 0
	v_mfma_f32_16x16x32_bf16 v[38:41], v[146:149], v[170:173], 0
	v_mfma_f32_16x16x32_bf16 v[30:33], v[154:157], v[170:173], 0
	v_mfma_f32_16x16x32_bf16 v[22:25], v[146:149], v[178:181], 0
	v_mfma_f32_16x16x32_bf16 v[14:17], v[154:157], v[178:181], 0
	v_mfma_f32_16x16x32_bf16 v[6:9], v[146:149], v[186:189], 0
	v_mfma_f32_16x16x32_bf16 v[2:5], v[154:157], v[186:189], 0
	v_mfma_f32_16x16x32_bf16 v[54:57], v[150:153], v[166:169], v[54:57]
	v_mfma_f32_16x16x32_bf16 v[46:49], v[158:161], v[166:169], v[46:49]
	v_mfma_f32_16x16x32_bf16 v[38:41], v[150:153], v[174:177], v[38:41]
	v_mfma_f32_16x16x32_bf16 v[30:33], v[158:161], v[174:177], v[30:33]
	v_mfma_f32_16x16x32_bf16 v[22:25], v[150:153], v[182:185], v[22:25]
	v_mfma_f32_16x16x32_bf16 v[14:17], v[158:161], v[182:185], v[14:17]
	v_mfma_f32_16x16x32_bf16 v[6:9], v[150:153], v[196:199], v[6:9]
	v_mfma_f32_16x16x32_bf16 v[2:5], v[158:161], v[196:199], v[2:5]
	s_setprio 0
	s_barrier
	s_add_i32 s37, 0, 0x18000
	s_add_i32 s38, 0, 0x1c000
	v_add_u32_e32 v142, s37, v238
	v_add_u32_e32 v158, s38, v238
	ds_read_b128 v[130:133], v142
	ds_read_b128 v[134:137], v142 offset:1024
	ds_read_b128 v[138:141], v142 offset:2048
	ds_read_b128 v[142:145], v142 offset:3072
	ds_read_b128 v[146:149], v158
	ds_read_b128 v[150:153], v158 offset:1024
	ds_read_b128 v[154:157], v158 offset:2048
	ds_read_b128 v[158:161], v158 offset:3072
	s_add_u32 s22, s22, 0x80000
	s_addc_u32 s23, s23, 0
	s_mov_b32 m0, s27
	v_lshl_add_u64 v[218:219], s[22:23], 0, v[200:201]
	ds_read_b128 v[162:165], v240 offset:32768
	ds_read_b128 v[166:169], v240 offset:33792
	ds_read_b128 v[170:173], v240 offset:34816
	ds_read_b128 v[174:177], v240 offset:35840
	ds_read_b128 v[178:181], v240 offset:36864
	ds_read_b128 v[182:185], v240 offset:37888
	ds_read_b128 v[186:189], v240 offset:38912
	ds_read_b128 v[196:199], v240 offset:39936
	global_load_lds_dwordx4 v[218:219], off
	v_lshl_add_u64 v[218:219], s[22:23], 0, v[202:203]
	s_mov_b32 m0, s28
	s_nop 0
	global_load_lds_dwordx4 v[218:219], off
	s_waitcnt vmcnt(8)
	s_waitcnt lgkmcnt(0)
	s_barrier
	s_setprio 1
	s_waitcnt lgkmcnt(0)
	v_mfma_f32_16x16x32_bf16 v[126:129], v[130:133], v[162:165], v[126:129]
	v_mfma_f32_16x16x32_bf16 v[122:125], v[138:141], v[162:165], v[122:125]
	v_mfma_f32_16x16x32_bf16 v[110:113], v[130:133], v[170:173], v[110:113]
	v_mfma_f32_16x16x32_bf16 v[106:109], v[138:141], v[170:173], v[106:109]
	v_mfma_f32_16x16x32_bf16 v[98:101], v[130:133], v[178:181], v[98:101]
	v_mfma_f32_16x16x32_bf16 v[90:93], v[138:141], v[178:181], v[90:93]
	v_mfma_f32_16x16x32_bf16 v[82:85], v[130:133], v[186:189], v[82:85]
	v_mfma_f32_16x16x32_bf16 v[74:77], v[138:141], v[186:189], v[74:77]
	v_mfma_f32_16x16x32_bf16 v[126:129], v[134:137], v[166:169], v[126:129]
	v_mfma_f32_16x16x32_bf16 v[122:125], v[142:145], v[166:169], v[122:125]
	v_mfma_f32_16x16x32_bf16 v[110:113], v[134:137], v[174:177], v[110:113]
	v_mfma_f32_16x16x32_bf16 v[106:109], v[142:145], v[174:177], v[106:109]
	v_mfma_f32_16x16x32_bf16 v[98:101], v[134:137], v[182:185], v[98:101]
	v_mfma_f32_16x16x32_bf16 v[90:93], v[142:145], v[182:185], v[90:93]
	v_mfma_f32_16x16x32_bf16 v[82:85], v[134:137], v[196:199], v[82:85]
	v_mfma_f32_16x16x32_bf16 v[74:77], v[142:145], v[196:199], v[74:77]
	s_setprio 0
	s_setprio 1
	v_mfma_f32_16x16x32_bf16 v[118:121], v[146:149], v[162:165], v[118:121]
	v_mfma_f32_16x16x32_bf16 v[114:117], v[154:157], v[162:165], v[114:117]
	v_mfma_f32_16x16x32_bf16 v[102:105], v[146:149], v[170:173], v[102:105]
	v_mfma_f32_16x16x32_bf16 v[94:97], v[154:157], v[170:173], v[94:97]
	v_mfma_f32_16x16x32_bf16 v[86:89], v[146:149], v[178:181], v[86:89]
	v_mfma_f32_16x16x32_bf16 v[78:81], v[154:157], v[178:181], v[78:81]
	v_mfma_f32_16x16x32_bf16 v[70:73], v[146:149], v[186:189], v[70:73]
	v_mfma_f32_16x16x32_bf16 v[66:69], v[154:157], v[186:189], v[66:69]
	v_mfma_f32_16x16x32_bf16 v[118:121], v[150:153], v[166:169], v[118:121]
	v_mfma_f32_16x16x32_bf16 v[114:117], v[158:161], v[166:169], v[114:117]
	v_mfma_f32_16x16x32_bf16 v[102:105], v[150:153], v[174:177], v[102:105]
	v_mfma_f32_16x16x32_bf16 v[94:97], v[158:161], v[174:177], v[94:97]
	v_mfma_f32_16x16x32_bf16 v[86:89], v[150:153], v[182:185], v[86:89]
	v_mfma_f32_16x16x32_bf16 v[78:81], v[158:161], v[182:185], v[78:81]
	v_mfma_f32_16x16x32_bf16 v[70:73], v[150:153], v[196:199], v[70:73]
	v_mfma_f32_16x16x32_bf16 v[66:69], v[158:161], v[196:199], v[66:69]
	s_setprio 0
	s_barrier
	s_add_i32 s22, s37, s24
	v_lshl_add_u64 v[210:211], v[210:211], 0, s[58:59]
	s_mov_b32 m0, s22
	ds_read_b128 v[162:165], v240 offset:49152
	ds_read_b128 v[166:169], v240 offset:50176
	ds_read_b128 v[170:173], v240 offset:51200
	ds_read_b128 v[174:177], v240 offset:52224
	ds_read_b128 v[178:181], v240 offset:53248
	ds_read_b128 v[182:185], v240 offset:54272
	ds_read_b128 v[186:189], v240 offset:55296
	ds_read_b128 v[196:199], v240 offset:56320
	global_load_lds_dwordx4 v[210:211], off
	s_add_i32 m0, s22, 0x2000
	s_add_u32 s20, s20, 0x80080
	v_lshl_add_u64 v[210:211], v[212:213], 0, s[58:59]
	s_addc_u32 s21, s21, 0
	s_add_i32 s22, s38, s24
	global_load_lds_dwordx4 v[210:211], off
	v_lshl_add_u64 v[210:211], s[20:21], 0, v[190:191]
	s_mov_b32 m0, s22
	s_nop 0
	global_load_lds_dwordx4 v[210:211], off
	v_lshl_add_u64 v[210:211], s[20:21], 0, v[204:205]
	s_add_i32 m0, s22, 0x2000
	s_nop 0
	global_load_lds_dwordx4 v[210:211], off
	v_lshl_add_u64 v[210:211], v[214:215], 0, s[58:59]
	s_mov_b32 m0, s29
	s_nop 0
	global_load_lds_dwordx4 v[210:211], off
	v_lshl_add_u64 v[210:211], v[216:217], 0, s[58:59]
	s_mov_b32 m0, s30
	s_nop 0
	global_load_lds_dwordx4 v[210:211], off
	s_waitcnt vmcnt(8)
	s_waitcnt lgkmcnt(0)
	s_barrier
	s_setprio 1
	s_waitcnt lgkmcnt(0)
	v_mfma_f32_16x16x32_bf16 v[62:65], v[130:133], v[162:165], v[62:65]
	v_mfma_f32_16x16x32_bf16 v[58:61], v[138:141], v[162:165], v[58:61]
	v_mfma_f32_16x16x32_bf16 v[50:53], v[130:133], v[170:173], v[50:53]
	v_mfma_f32_16x16x32_bf16 v[42:45], v[138:141], v[170:173], v[42:45]
	v_mfma_f32_16x16x32_bf16 v[34:37], v[130:133], v[178:181], v[34:37]
	v_mfma_f32_16x16x32_bf16 v[26:29], v[138:141], v[178:181], v[26:29]
	v_mfma_f32_16x16x32_bf16 v[18:21], v[130:133], v[186:189], v[18:21]
	v_mfma_f32_16x16x32_bf16 v[10:13], v[138:141], v[186:189], v[10:13]
	v_mfma_f32_16x16x32_bf16 v[62:65], v[134:137], v[166:169], v[62:65]
	v_mfma_f32_16x16x32_bf16 v[58:61], v[142:145], v[166:169], v[58:61]
	v_mfma_f32_16x16x32_bf16 v[50:53], v[134:137], v[174:177], v[50:53]
	v_mfma_f32_16x16x32_bf16 v[42:45], v[142:145], v[174:177], v[42:45]
	v_mfma_f32_16x16x32_bf16 v[34:37], v[134:137], v[182:185], v[34:37]
	v_mfma_f32_16x16x32_bf16 v[26:29], v[142:145], v[182:185], v[26:29]
	v_mfma_f32_16x16x32_bf16 v[18:21], v[134:137], v[196:199], v[18:21]
	v_mfma_f32_16x16x32_bf16 v[10:13], v[142:145], v[196:199], v[10:13]
	s_setprio 0
	s_setprio 1
	v_mfma_f32_16x16x32_bf16 v[54:57], v[146:149], v[162:165], v[54:57]
	v_mfma_f32_16x16x32_bf16 v[46:49], v[154:157], v[162:165], v[46:49]
	v_mfma_f32_16x16x32_bf16 v[38:41], v[146:149], v[170:173], v[38:41]
	v_mfma_f32_16x16x32_bf16 v[30:33], v[154:157], v[170:173], v[30:33]
	v_mfma_f32_16x16x32_bf16 v[22:25], v[146:149], v[178:181], v[22:25]
	v_mfma_f32_16x16x32_bf16 v[14:17], v[154:157], v[178:181], v[14:17]
	v_mfma_f32_16x16x32_bf16 v[6:9], v[146:149], v[186:189], v[6:9]
	v_mfma_f32_16x16x32_bf16 v[2:5], v[154:157], v[186:189], v[2:5]
	v_mfma_f32_16x16x32_bf16 v[54:57], v[150:153], v[166:169], v[54:57]
	v_mfma_f32_16x16x32_bf16 v[46:49], v[158:161], v[166:169], v[46:49]
	v_mfma_f32_16x16x32_bf16 v[38:41], v[150:153], v[174:177], v[38:41]
	v_mfma_f32_16x16x32_bf16 v[30:33], v[158:161], v[174:177], v[30:33]
	v_mfma_f32_16x16x32_bf16 v[22:25], v[150:153], v[182:185], v[22:25]
	v_mfma_f32_16x16x32_bf16 v[14:17], v[158:161], v[182:185], v[14:17]
	v_mfma_f32_16x16x32_bf16 v[6:9], v[150:153], v[196:199], v[6:9]
	v_mfma_f32_16x16x32_bf16 v[2:5], v[158:161], v[196:199], v[2:5]
	s_setprio 0
	s_barrier
	s_add_i32 s36, s36, 2
	s_add_u32 s16, s16, 0x100
	s_addc_u32 s17, s17, 0
	s_add_u32 s34, s34, 0x100
	s_addc_u32 s35, s35, 0
	s_cmp_gt_u32 s36, 29
	s_cbranch_scc1 .Lpeel_done_2

.Lpeel_done_2:
	s_and_b64 vcc, exec, s[2:3]
	s_cbranch_vccz .LBB0_751
	s_barrier

.LBB0_771:
	s_ashr_i32 s17, s16, 31
	s_lshl_b64 s[20:21], s[16:17], 20
	v_readlane_b32 s0, v254, 60
	s_add_u32 s20, s0, s20
	v_readlane_b32 s0, v254, 61
	s_addc_u32 s21, s0, s21
	s_and_b64 s[22:23], s[6:7], exec
	s_cselect_b32 s17, s21, s27
	s_cselect_b32 s40, s20, s26
	s_ashr_i32 s15, s14, 31
	s_lshl_b64 s[22:23], s[14:15], 20
	v_readlane_b32 s0, v254, 40
	v_readlane_b32 s1, v254, 41
	s_add_u32 s22, s0, s22
	s_addc_u32 s23, s1, s23
	s_and_b64 s[30:31], s[6:7], exec
	s_cselect_b32 s15, s23, s29
	s_cselect_b32 s41, s22, s28
	s_add_u32 s26, s26, 0x80080
	s_addc_u32 s27, s27, 0
	s_add_u32 s42, s28, 0x100
	s_addc_u32 s43, s29, 0
	s_mov_b32 s46, -2
	v_readlane_b32 s47, v255, 49
	s_nop 3
	s_cmp_eq_u32 s47, 4
	v_writelane_b32 v255, 4, 49
	s_cbranch_scc0 .Ltrip0_strict_3
	s_add_u32 s28, s26, 0xfff80080
	s_addc_u32 s29, s27, -1
	s_add_i32 s47, 0, 0x10000
	s_cmp_eq_u32 s46, 28
	s_cselect_b32 s31, s17, s29
	s_cselect_b32 s30, s40, s28
	s_cselect_b32 s29, s15, s43
	s_cselect_b32 s28, s41, s42
	s_add_i32 s55, 0, 0x14000
	v_add_u32_e32 v142, s47, v220
	v_add_u32_e32 v158, s55, v220
	ds_read_b128 v[130:133], v142
	ds_read_b128 v[134:137], v142 offset:1024
	ds_read_b128 v[138:141], v142 offset:2048
	ds_read_b128 v[142:145], v142 offset:3072
	ds_read_b128 v[146:149], v158
	ds_read_b128 v[150:153], v158 offset:1024
	ds_read_b128 v[154:157], v158 offset:2048
	ds_read_b128 v[158:161], v158 offset:3072
	v_lshl_add_u64 v[210:211], s[26:27], 0, v[202:203]
	s_add_i32 m0, s34, 0xc000
	ds_read_b128 v[162:165], v222
	ds_read_b128 v[166:169], v222 offset:1024
	ds_read_b128 v[170:173], v222 offset:2048
	ds_read_b128 v[174:177], v222 offset:3072
	ds_read_b128 v[178:181], v222 offset:4096
	ds_read_b128 v[182:185], v222 offset:5120
	ds_read_b128 v[196:199], v222 offset:6144
	ds_read_b128 v[206:209], v222 offset:7168
	global_load_lds_dwordx4 v[210:211], off
	v_lshl_add_u64 v[210:211], s[26:27], 0, v[204:205]
	s_add_i32 m0, s34, 0xe000
	s_nop 0
	global_load_lds_dwordx4 v[210:211], off
	s_waitcnt vmcnt(24)
	s_waitcnt lgkmcnt(0)
	s_barrier
	s_setprio 1
	s_waitcnt lgkmcnt(0)
	v_mfma_f32_16x16x32_bf16 v[126:129], v[130:133], v[162:165], 0
	v_mfma_f32_16x16x32_bf16 v[122:125], v[138:141], v[162:165], 0
	v_mfma_f32_16x16x32_bf16 v[110:113], v[130:133], v[170:173], 0
	v_mfma_f32_16x16x32_bf16 v[106:109], v[138:141], v[170:173], 0
	v_mfma_f32_16x16x32_bf16 v[94:97], v[130:133], v[178:181], 0
	v_mfma_f32_16x16x32_bf16 v[90:93], v[138:141], v[178:181], 0
	v_mfma_f32_16x16x32_bf16 v[78:81], v[130:133], v[196:199], 0
	v_mfma_f32_16x16x32_bf16 v[74:77], v[138:141], v[196:199], 0
	v_mfma_f32_16x16x32_bf16 v[126:129], v[134:137], v[166:169], v[126:129]
	v_mfma_f32_16x16x32_bf16 v[122:125], v[142:145], v[166:169], v[122:125]
	v_mfma_f32_16x16x32_bf16 v[110:113], v[134:137], v[174:177], v[110:113]
	v_mfma_f32_16x16x32_bf16 v[106:109], v[142:145], v[174:177], v[106:109]
	v_mfma_f32_16x16x32_bf16 v[94:97], v[134:137], v[182:185], v[94:97]
	v_mfma_f32_16x16x32_bf16 v[90:93], v[142:145], v[182:185], v[90:93]
	v_mfma_f32_16x16x32_bf16 v[78:81], v[134:137], v[206:209], v[78:81]
	v_mfma_f32_16x16x32_bf16 v[74:77], v[142:145], v[206:209], v[74:77]
	s_setprio 0
	s_setprio 1
	v_mfma_f32_16x16x32_bf16 v[118:121], v[146:149], v[162:165], 0
	v_mfma_f32_16x16x32_bf16 v[114:117], v[154:157], v[162:165], 0
	v_mfma_f32_16x16x32_bf16 v[102:105], v[146:149], v[170:173], 0
	v_mfma_f32_16x16x32_bf16 v[98:101], v[154:157], v[170:173], 0
	v_mfma_f32_16x16x32_bf16 v[86:89], v[146:149], v[178:181], 0
	v_mfma_f32_16x16x32_bf16 v[82:85], v[154:157], v[178:181], 0
	v_mfma_f32_16x16x32_bf16 v[70:73], v[146:149], v[196:199], 0
	v_mfma_f32_16x16x32_bf16 v[66:69], v[154:157], v[196:199], 0
	v_mfma_f32_16x16x32_bf16 v[118:121], v[150:153], v[166:169], v[118:121]
	v_mfma_f32_16x16x32_bf16 v[114:117], v[158:161], v[166:169], v[114:117]
	v_mfma_f32_16x16x32_bf16 v[102:105], v[150:153], v[174:177], v[102:105]
	v_mfma_f32_16x16x32_bf16 v[98:101], v[158:161], v[174:177], v[98:101]
	v_mfma_f32_16x16x32_bf16 v[86:89], v[150:153], v[182:185], v[86:89]
	v_mfma_f32_16x16x32_bf16 v[82:85], v[158:161], v[182:185], v[82:85]
	v_mfma_f32_16x16x32_bf16 v[70:73], v[150:153], v[206:209], v[70:73]
	v_mfma_f32_16x16x32_bf16 v[66:69], v[158:161], v[206:209], v[66:69]
	s_setprio 0
	s_barrier
	s_add_i32 s47, s47, s33
	v_lshl_add_u64 v[210:211], s[28:29], 0, v[190:191]
	s_mov_b32 m0, s47
	ds_read_b128 v[162:165], v222 offset:16384
	ds_read_b128 v[166:169], v222 offset:17408
	ds_read_b128 v[170:173], v222 offset:18432
	ds_read_b128 v[174:177], v222 offset:19456
	ds_read_b128 v[178:181], v222 offset:20480
	ds_read_b128 v[182:185], v222 offset:21504
	ds_read_b128 v[196:199], v222 offset:22528
	ds_read_b128 v[206:209], v222 offset:23552
	global_load_lds_dwordx4 v[210:211], off
	s_add_i32 m0, s47, 0x2000
	s_add_u32 s52, s28, 0x80000
	v_lshl_add_u64 v[212:213], s[28:29], 0, v[200:201]
	s_addc_u32 s53, s29, 0
	s_add_i32 s47, s55, s33
	global_load_lds_dwordx4 v[212:213], off
	v_lshl_add_u64 v[214:215], s[52:53], 0, v[190:191]
	s_mov_b32 m0, s47
	v_lshl_add_u64 v[216:217], s[30:31], 0, v[188:189]
	global_load_lds_dwordx4 v[214:215], off
	v_lshl_add_u64 v[214:215], s[52:53], 0, v[200:201]
	s_add_i32 m0, s47, 0x2000
	s_nop 0
	global_load_lds_dwordx4 v[214:215], off
	v_lshl_add_u64 v[214:215], s[30:31], 0, v[186:187]
	s_mov_b32 m0, s34
	s_nop 0
	global_load_lds_dwordx4 v[214:215], off
	s_mov_b32 m0, s35
	s_nop 0
	global_load_lds_dwordx4 v[216:217], off
	s_waitcnt vmcnt(24)
	s_waitcnt lgkmcnt(0)
	s_barrier
	s_setprio 1
	s_waitcnt lgkmcnt(0)
	v_mfma_f32_16x16x32_bf16 v[62:65], v[130:133], v[162:165], 0
	v_mfma_f32_16x16x32_bf16 v[58:61], v[138:141], v[162:165], 0
	v_mfma_f32_16x16x32_bf16 v[46:49], v[130:133], v[170:173], 0
	v_mfma_f32_16x16x32_bf16 v[42:45], v[138:141], v[170:173], 0
	v_mfma_f32_16x16x32_bf16 v[30:33], v[130:133], v[178:181], 0
	v_mfma_f32_16x16x32_bf16 v[26:29], v[138:141], v[178:181], 0
	v_mfma_f32_16x16x32_bf16 v[14:17], v[130:133], v[196:199], 0
	v_mfma_f32_16x16x32_bf16 v[10:13], v[138:141], v[196:199], 0
	v_mfma_f32_16x16x32_bf16 v[62:65], v[134:137], v[166:169], v[62:65]
	v_mfma_f32_16x16x32_bf16 v[58:61], v[142:145], v[166:169], v[58:61]
	v_mfma_f32_16x16x32_bf16 v[46:49], v[134:137], v[174:177], v[46:49]
	v_mfma_f32_16x16x32_bf16 v[42:45], v[142:145], v[174:177], v[42:45]
	v_mfma_f32_16x16x32_bf16 v[30:33], v[134:137], v[182:185], v[30:33]
	v_mfma_f32_16x16x32_bf16 v[26:29], v[142:145], v[182:185], v[26:29]
	v_mfma_f32_16x16x32_bf16 v[14:17], v[134:137], v[206:209], v[14:17]
	v_mfma_f32_16x16x32_bf16 v[10:13], v[142:145], v[206:209], v[10:13]
	s_setprio 0
	s_setprio 1
	v_mfma_f32_16x16x32_bf16 v[54:57], v[146:149], v[162:165], 0
	v_mfma_f32_16x16x32_bf16 v[50:53], v[154:157], v[162:165], 0
	v_mfma_f32_16x16x32_bf16 v[38:41], v[146:149], v[170:173], 0
	v_mfma_f32_16x16x32_bf16 v[34:37], v[154:157], v[170:173], 0
	v_mfma_f32_16x16x32_bf16 v[22:25], v[146:149], v[178:181], 0
	v_mfma_f32_16x16x32_bf16 v[18:21], v[154:157], v[178:181], 0
	v_mfma_f32_16x16x32_bf16 v[6:9], v[146:149], v[196:199], 0
	v_mfma_f32_16x16x32_bf16 v[2:5], v[154:157], v[196:199], 0
	v_mfma_f32_16x16x32_bf16 v[54:57], v[150:153], v[166:169], v[54:57]
	v_mfma_f32_16x16x32_bf16 v[50:53], v[158:161], v[166:169], v[50:53]
	v_mfma_f32_16x16x32_bf16 v[38:41], v[150:153], v[174:177], v[38:41]
	v_mfma_f32_16x16x32_bf16 v[34:37], v[158:161], v[174:177], v[34:37]
	v_mfma_f32_16x16x32_bf16 v[22:25], v[150:153], v[182:185], v[22:25]
	v_mfma_f32_16x16x32_bf16 v[18:21], v[158:161], v[182:185], v[18:21]
	v_mfma_f32_16x16x32_bf16 v[6:9], v[150:153], v[206:209], v[6:9]
	v_mfma_f32_16x16x32_bf16 v[2:5], v[158:161], v[206:209], v[2:5]
	s_setprio 0
	s_barrier
	s_add_i32 s47, 0, 0x18000
	s_add_i32 s52, 0, 0x1c000
	v_add_u32_e32 v142, s47, v220
	v_add_u32_e32 v158, s52, v220
	ds_read_b128 v[130:133], v142
	ds_read_b128 v[134:137], v142 offset:1024
	ds_read_b128 v[138:141], v142 offset:2048
	ds_read_b128 v[142:145], v142 offset:3072
	ds_read_b128 v[146:149], v158
	ds_read_b128 v[150:153], v158 offset:1024
	ds_read_b128 v[154:157], v158 offset:2048
	ds_read_b128 v[158:161], v158 offset:3072
	s_add_u32 s30, s30, 0x80000
	s_addc_u32 s31, s31, 0
	s_mov_b32 m0, s36
	v_lshl_add_u64 v[218:219], s[30:31], 0, v[186:187]
	ds_read_b128 v[162:165], v222 offset:32768
	ds_read_b128 v[166:169], v222 offset:33792
	ds_read_b128 v[170:173], v222 offset:34816
	ds_read_b128 v[174:177], v222 offset:35840
	ds_read_b128 v[178:181], v222 offset:36864
	ds_read_b128 v[182:185], v222 offset:37888
	ds_read_b128 v[196:199], v222 offset:38912
	ds_read_b128 v[206:209], v222 offset:39936
	global_load_lds_dwordx4 v[218:219], off
	v_lshl_add_u64 v[218:219], s[30:31], 0, v[188:189]
	s_mov_b32 m0, s37
	s_nop 0
	global_load_lds_dwordx4 v[218:219], off
	s_waitcnt vmcnt(8)
	s_waitcnt lgkmcnt(0)
	s_barrier
	s_setprio 1
	s_waitcnt lgkmcnt(0)
	v_mfma_f32_16x16x32_bf16 v[126:129], v[130:133], v[162:165], v[126:129]
	v_mfma_f32_16x16x32_bf16 v[122:125], v[138:141], v[162:165], v[122:125]
	v_mfma_f32_16x16x32_bf16 v[110:113], v[130:133], v[170:173], v[110:113]
	v_mfma_f32_16x16x32_bf16 v[106:109], v[138:141], v[170:173], v[106:109]
	v_mfma_f32_16x16x32_bf16 v[94:97], v[130:133], v[178:181], v[94:97]
	v_mfma_f32_16x16x32_bf16 v[90:93], v[138:141], v[178:181], v[90:93]
	v_mfma_f32_16x16x32_bf16 v[78:81], v[130:133], v[196:199], v[78:81]
	v_mfma_f32_16x16x32_bf16 v[74:77], v[138:141], v[196:199], v[74:77]
	v_mfma_f32_16x16x32_bf16 v[126:129], v[134:137], v[166:169], v[126:129]
	v_mfma_f32_16x16x32_bf16 v[122:125], v[142:145], v[166:169], v[122:125]
	v_mfma_f32_16x16x32_bf16 v[110:113], v[134:137], v[174:177], v[110:113]
	v_mfma_f32_16x16x32_bf16 v[106:109], v[142:145], v[174:177], v[106:109]
	v_mfma_f32_16x16x32_bf16 v[94:97], v[134:137], v[182:185], v[94:97]
	v_mfma_f32_16x16x32_bf16 v[90:93], v[142:145], v[182:185], v[90:93]
	v_mfma_f32_16x16x32_bf16 v[78:81], v[134:137], v[206:209], v[78:81]
	v_mfma_f32_16x16x32_bf16 v[74:77], v[142:145], v[206:209], v[74:77]
	s_setprio 0
	s_setprio 1
	v_mfma_f32_16x16x32_bf16 v[118:121], v[146:149], v[162:165], v[118:121]
	v_mfma_f32_16x16x32_bf16 v[114:117], v[154:157], v[162:165], v[114:117]
	v_mfma_f32_16x16x32_bf16 v[102:105], v[146:149], v[170:173], v[102:105]
	v_mfma_f32_16x16x32_bf16 v[98:101], v[154:157], v[170:173], v[98:101]
	v_mfma_f32_16x16x32_bf16 v[86:89], v[146:149], v[178:181], v[86:89]
	v_mfma_f32_16x16x32_bf16 v[82:85], v[154:157], v[178:181], v[82:85]
	v_mfma_f32_16x16x32_bf16 v[70:73], v[146:149], v[196:199], v[70:73]
	v_mfma_f32_16x16x32_bf16 v[66:69], v[154:157], v[196:199], v[66:69]
	v_mfma_f32_16x16x32_bf16 v[118:121], v[150:153], v[166:169], v[118:121]
	v_mfma_f32_16x16x32_bf16 v[114:117], v[158:161], v[166:169], v[114:117]
	v_mfma_f32_16x16x32_bf16 v[102:105], v[150:153], v[174:177], v[102:105]
	v_mfma_f32_16x16x32_bf16 v[98:101], v[158:161], v[174:177], v[98:101]
	v_mfma_f32_16x16x32_bf16 v[86:89], v[150:153], v[182:185], v[86:89]
	v_mfma_f32_16x16x32_bf16 v[82:85], v[158:161], v[182:185], v[82:85]
	v_mfma_f32_16x16x32_bf16 v[70:73], v[150:153], v[206:209], v[70:73]
	v_mfma_f32_16x16x32_bf16 v[66:69], v[158:161], v[206:209], v[66:69]
	s_setprio 0
	s_barrier
	s_add_i32 s30, s47, s33
	v_lshl_add_u64 v[210:211], v[210:211], 0, s[58:59]
	s_mov_b32 m0, s30
	ds_read_b128 v[162:165], v222 offset:49152
	ds_read_b128 v[166:169], v222 offset:50176
	ds_read_b128 v[170:173], v222 offset:51200
	ds_read_b128 v[174:177], v222 offset:52224
	ds_read_b128 v[178:181], v222 offset:53248
	ds_read_b128 v[182:185], v222 offset:54272
	ds_read_b128 v[196:199], v222 offset:55296
	ds_read_b128 v[206:209], v222 offset:56320
	global_load_lds_dwordx4 v[210:211], off
	s_add_i32 m0, s30, 0x2000
	s_add_u32 s28, s28, 0x80080
	v_lshl_add_u64 v[210:211], v[212:213], 0, s[58:59]
	s_addc_u32 s29, s29, 0
	s_add_i32 s30, s52, s33
	global_load_lds_dwordx4 v[210:211], off
	v_lshl_add_u64 v[210:211], s[28:29], 0, v[190:191]
	s_mov_b32 m0, s30
	s_nop 0
	global_load_lds_dwordx4 v[210:211], off
	v_lshl_add_u64 v[210:211], s[28:29], 0, v[200:201]
	s_add_i32 m0, s30, 0x2000
	s_nop 0
	global_load_lds_dwordx4 v[210:211], off
	v_lshl_add_u64 v[210:211], v[214:215], 0, s[58:59]
	s_mov_b32 m0, s38
	s_nop 0
	global_load_lds_dwordx4 v[210:211], off
	v_lshl_add_u64 v[210:211], v[216:217], 0, s[58:59]
	s_mov_b32 m0, s39
	s_nop 0
	global_load_lds_dwordx4 v[210:211], off
	s_waitcnt vmcnt(8)
	s_waitcnt lgkmcnt(0)
	s_barrier
	s_setprio 1
	s_waitcnt lgkmcnt(0)
	v_mfma_f32_16x16x32_bf16 v[62:65], v[130:133], v[162:165], v[62:65]
	v_mfma_f32_16x16x32_bf16 v[58:61], v[138:141], v[162:165], v[58:61]
	v_mfma_f32_16x16x32_bf16 v[46:49], v[130:133], v[170:173], v[46:49]
	v_mfma_f32_16x16x32_bf16 v[42:45], v[138:141], v[170:173], v[42:45]
	v_mfma_f32_16x16x32_bf16 v[30:33], v[130:133], v[178:181], v[30:33]
	v_mfma_f32_16x16x32_bf16 v[26:29], v[138:141], v[178:181], v[26:29]
	v_mfma_f32_16x16x32_bf16 v[14:17], v[130:133], v[196:199], v[14:17]
	v_mfma_f32_16x16x32_bf16 v[10:13], v[138:141], v[196:199], v[10:13]
	v_mfma_f32_16x16x32_bf16 v[62:65], v[134:137], v[166:169], v[62:65]
	v_mfma_f32_16x16x32_bf16 v[58:61], v[142:145], v[166:169], v[58:61]
	v_mfma_f32_16x16x32_bf16 v[46:49], v[134:137], v[174:177], v[46:49]
	v_mfma_f32_16x16x32_bf16 v[42:45], v[142:145], v[174:177], v[42:45]
	v_mfma_f32_16x16x32_bf16 v[30:33], v[134:137], v[182:185], v[30:33]
	v_mfma_f32_16x16x32_bf16 v[26:29], v[142:145], v[182:185], v[26:29]
	v_mfma_f32_16x16x32_bf16 v[14:17], v[134:137], v[206:209], v[14:17]
	v_mfma_f32_16x16x32_bf16 v[10:13], v[142:145], v[206:209], v[10:13]
	s_setprio 0
	s_setprio 1
	v_mfma_f32_16x16x32_bf16 v[54:57], v[146:149], v[162:165], v[54:57]
	v_mfma_f32_16x16x32_bf16 v[50:53], v[154:157], v[162:165], v[50:53]
	v_mfma_f32_16x16x32_bf16 v[38:41], v[146:149], v[170:173], v[38:41]
	v_mfma_f32_16x16x32_bf16 v[34:37], v[154:157], v[170:173], v[34:37]
	v_mfma_f32_16x16x32_bf16 v[22:25], v[146:149], v[178:181], v[22:25]
	v_mfma_f32_16x16x32_bf16 v[18:21], v[154:157], v[178:181], v[18:21]
	v_mfma_f32_16x16x32_bf16 v[6:9], v[146:149], v[196:199], v[6:9]
	v_mfma_f32_16x16x32_bf16 v[2:5], v[154:157], v[196:199], v[2:5]
	v_mfma_f32_16x16x32_bf16 v[54:57], v[150:153], v[166:169], v[54:57]
	v_mfma_f32_16x16x32_bf16 v[50:53], v[158:161], v[166:169], v[50:53]
	v_mfma_f32_16x16x32_bf16 v[38:41], v[150:153], v[174:177], v[38:41]
	v_mfma_f32_16x16x32_bf16 v[34:37], v[158:161], v[174:177], v[34:37]
	v_mfma_f32_16x16x32_bf16 v[22:25], v[150:153], v[182:185], v[22:25]
	v_mfma_f32_16x16x32_bf16 v[18:21], v[158:161], v[182:185], v[18:21]
	v_mfma_f32_16x16x32_bf16 v[6:9], v[150:153], v[206:209], v[6:9]
	v_mfma_f32_16x16x32_bf16 v[2:5], v[158:161], v[206:209], v[2:5]
	s_setprio 0
	s_barrier
	s_add_i32 s46, s46, 2
	s_add_u32 s26, s26, 0x100
	s_addc_u32 s27, s27, 0
	s_add_u32 s42, s42, 0x100
	s_addc_u32 s43, s43, 0
	s_cmp_gt_u32 s46, 29
	s_cbranch_scc1 .Lpeel_done_3
	s_branch .LBB0_772
.Ltrip0_strict_3:
	s_add_u32 s28, s26, 0xfff80080
	s_addc_u32 s29, s27, -1
	s_add_i32 s47, 0, 0x10000
	s_cmp_eq_u32 s46, 28
	s_cselect_b32 s31, s17, s29
	s_cselect_b32 s30, s40, s28
	s_cselect_b32 s29, s15, s43
	s_cselect_b32 s28, s41, s42
	s_add_i32 s55, 0, 0x14000
	v_add_u32_e32 v142, s47, v220
	v_add_u32_e32 v158, s55, v220
	ds_read_b128 v[130:133], v142
	ds_read_b128 v[134:137], v142 offset:1024
	ds_read_b128 v[138:141], v142 offset:2048
	ds_read_b128 v[142:145], v142 offset:3072
	ds_read_b128 v[146:149], v158
	ds_read_b128 v[150:153], v158 offset:1024
	ds_read_b128 v[154:157], v158 offset:2048
	ds_read_b128 v[158:161], v158 offset:3072
	v_lshl_add_u64 v[210:211], s[26:27], 0, v[202:203]
	s_add_i32 m0, s34, 0xc000
	ds_read_b128 v[162:165], v222
	ds_read_b128 v[166:169], v222 offset:1024
	ds_read_b128 v[170:173], v222 offset:2048
	ds_read_b128 v[174:177], v222 offset:3072
	ds_read_b128 v[178:181], v222 offset:4096
	ds_read_b128 v[182:185], v222 offset:5120
	ds_read_b128 v[196:199], v222 offset:6144
	ds_read_b128 v[206:209], v222 offset:7168
	global_load_lds_dwordx4 v[210:211], off
	v_lshl_add_u64 v[210:211], s[26:27], 0, v[204:205]
	s_add_i32 m0, s34, 0xe000
	s_nop 0
	global_load_lds_dwordx4 v[210:211], off
	s_waitcnt vmcnt(8)
	s_waitcnt lgkmcnt(0)
	s_barrier
	s_setprio 1
	s_waitcnt lgkmcnt(0)
	v_mfma_f32_16x16x32_bf16 v[126:129], v[130:133], v[162:165], 0
	v_mfma_f32_16x16x32_bf16 v[122:125], v[138:141], v[162:165], 0
	v_mfma_f32_16x16x32_bf16 v[110:113], v[130:133], v[170:173], 0
	v_mfma_f32_16x16x32_bf16 v[106:109], v[138:141], v[170:173], 0
	v_mfma_f32_16x16x32_bf16 v[94:97], v[130:133], v[178:181], 0
	v_mfma_f32_16x16x32_bf16 v[90:93], v[138:141], v[178:181], 0
	v_mfma_f32_16x16x32_bf16 v[78:81], v[130:133], v[196:199], 0
	v_mfma_f32_16x16x32_bf16 v[74:77], v[138:141], v[196:199], 0
	v_mfma_f32_16x16x32_bf16 v[126:129], v[134:137], v[166:169], v[126:129]
	v_mfma_f32_16x16x32_bf16 v[122:125], v[142:145], v[166:169], v[122:125]
	v_mfma_f32_16x16x32_bf16 v[110:113], v[134:137], v[174:177], v[110:113]
	v_mfma_f32_16x16x32_bf16 v[106:109], v[142:145], v[174:177], v[106:109]
	v_mfma_f32_16x16x32_bf16 v[94:97], v[134:137], v[182:185], v[94:97]
	v_mfma_f32_16x16x32_bf16 v[90:93], v[142:145], v[182:185], v[90:93]
	v_mfma_f32_16x16x32_bf16 v[78:81], v[134:137], v[206:209], v[78:81]
	v_mfma_f32_16x16x32_bf16 v[74:77], v[142:145], v[206:209], v[74:77]
	s_setprio 0
	s_setprio 1
	v_mfma_f32_16x16x32_bf16 v[118:121], v[146:149], v[162:165], 0
	v_mfma_f32_16x16x32_bf16 v[114:117], v[154:157], v[162:165], 0
	v_mfma_f32_16x16x32_bf16 v[102:105], v[146:149], v[170:173], 0
	v_mfma_f32_16x16x32_bf16 v[98:101], v[154:157], v[170:173], 0
	v_mfma_f32_16x16x32_bf16 v[86:89], v[146:149], v[178:181], 0
	v_mfma_f32_16x16x32_bf16 v[82:85], v[154:157], v[178:181], 0
	v_mfma_f32_16x16x32_bf16 v[70:73], v[146:149], v[196:199], 0
	v_mfma_f32_16x16x32_bf16 v[66:69], v[154:157], v[196:199], 0
	v_mfma_f32_16x16x32_bf16 v[118:121], v[150:153], v[166:169], v[118:121]
	v_mfma_f32_16x16x32_bf16 v[114:117], v[158:161], v[166:169], v[114:117]
	v_mfma_f32_16x16x32_bf16 v[102:105], v[150:153], v[174:177], v[102:105]
	v_mfma_f32_16x16x32_bf16 v[98:101], v[158:161], v[174:177], v[98:101]
	v_mfma_f32_16x16x32_bf16 v[86:89], v[150:153], v[182:185], v[86:89]
	v_mfma_f32_16x16x32_bf16 v[82:85], v[158:161], v[182:185], v[82:85]
	v_mfma_f32_16x16x32_bf16 v[70:73], v[150:153], v[206:209], v[70:73]
	v_mfma_f32_16x16x32_bf16 v[66:69], v[158:161], v[206:209], v[66:69]
	s_setprio 0
	s_barrier
	s_add_i32 s47, s47, s33
	v_lshl_add_u64 v[210:211], s[28:29], 0, v[190:191]
	s_mov_b32 m0, s47
	ds_read_b128 v[162:165], v222 offset:16384
	ds_read_b128 v[166:169], v222 offset:17408
	ds_read_b128 v[170:173], v222 offset:18432
	ds_read_b128 v[174:177], v222 offset:19456
	ds_read_b128 v[178:181], v222 offset:20480
	ds_read_b128 v[182:185], v222 offset:21504
	ds_read_b128 v[196:199], v222 offset:22528
	ds_read_b128 v[206:209], v222 offset:23552
	global_load_lds_dwordx4 v[210:211], off
	s_add_i32 m0, s47, 0x2000
	s_add_u32 s52, s28, 0x80000
	v_lshl_add_u64 v[212:213], s[28:29], 0, v[200:201]
	s_addc_u32 s53, s29, 0
	s_add_i32 s47, s55, s33
	global_load_lds_dwordx4 v[212:213], off
	v_lshl_add_u64 v[214:215], s[52:53], 0, v[190:191]
	s_mov_b32 m0, s47
	v_lshl_add_u64 v[216:217], s[30:31], 0, v[188:189]
	global_load_lds_dwordx4 v[214:215], off
	v_lshl_add_u64 v[214:215], s[52:53], 0, v[200:201]
	s_add_i32 m0, s47, 0x2000
	s_nop 0
	global_load_lds_dwordx4 v[214:215], off
	v_lshl_add_u64 v[214:215], s[30:31], 0, v[186:187]
	s_mov_b32 m0, s34
	s_nop 0
	global_load_lds_dwordx4 v[214:215], off
	s_mov_b32 m0, s35
	s_nop 0
	global_load_lds_dwordx4 v[216:217], off
	s_waitcnt vmcnt(8)
	s_waitcnt lgkmcnt(0)
	s_barrier
	s_setprio 1
	s_waitcnt lgkmcnt(0)
	v_mfma_f32_16x16x32_bf16 v[62:65], v[130:133], v[162:165], 0
	v_mfma_f32_16x16x32_bf16 v[58:61], v[138:141], v[162:165], 0
	v_mfma_f32_16x16x32_bf16 v[46:49], v[130:133], v[170:173], 0
	v_mfma_f32_16x16x32_bf16 v[42:45], v[138:141], v[170:173], 0
	v_mfma_f32_16x16x32_bf16 v[30:33], v[130:133], v[178:181], 0
	v_mfma_f32_16x16x32_bf16 v[26:29], v[138:141], v[178:181], 0
	v_mfma_f32_16x16x32_bf16 v[14:17], v[130:133], v[196:199], 0
	v_mfma_f32_16x16x32_bf16 v[10:13], v[138:141], v[196:199], 0
	v_mfma_f32_16x16x32_bf16 v[62:65], v[134:137], v[166:169], v[62:65]
	v_mfma_f32_16x16x32_bf16 v[58:61], v[142:145], v[166:169], v[58:61]
	v_mfma_f32_16x16x32_bf16 v[46:49], v[134:137], v[174:177], v[46:49]
	v_mfma_f32_16x16x32_bf16 v[42:45], v[142:145], v[174:177], v[42:45]
	v_mfma_f32_16x16x32_bf16 v[30:33], v[134:137], v[182:185], v[30:33]
	v_mfma_f32_16x16x32_bf16 v[26:29], v[142:145], v[182:185], v[26:29]
	v_mfma_f32_16x16x32_bf16 v[14:17], v[134:137], v[206:209], v[14:17]
	v_mfma_f32_16x16x32_bf16 v[10:13], v[142:145], v[206:209], v[10:13]
	s_setprio 0
	s_setprio 1
	v_mfma_f32_16x16x32_bf16 v[54:57], v[146:149], v[162:165], 0
	v_mfma_f32_16x16x32_bf16 v[50:53], v[154:157], v[162:165], 0
	v_mfma_f32_16x16x32_bf16 v[38:41], v[146:149], v[170:173], 0
	v_mfma_f32_16x16x32_bf16 v[34:37], v[154:157], v[170:173], 0
	v_mfma_f32_16x16x32_bf16 v[22:25], v[146:149], v[178:181], 0
	v_mfma_f32_16x16x32_bf16 v[18:21], v[154:157], v[178:181], 0
	v_mfma_f32_16x16x32_bf16 v[6:9], v[146:149], v[196:199], 0
	v_mfma_f32_16x16x32_bf16 v[2:5], v[154:157], v[196:199], 0
	v_mfma_f32_16x16x32_bf16 v[54:57], v[150:153], v[166:169], v[54:57]
	v_mfma_f32_16x16x32_bf16 v[50:53], v[158:161], v[166:169], v[50:53]
	v_mfma_f32_16x16x32_bf16 v[38:41], v[150:153], v[174:177], v[38:41]
	v_mfma_f32_16x16x32_bf16 v[34:37], v[158:161], v[174:177], v[34:37]
	v_mfma_f32_16x16x32_bf16 v[22:25], v[150:153], v[182:185], v[22:25]
	v_mfma_f32_16x16x32_bf16 v[18:21], v[158:161], v[182:185], v[18:21]
	v_mfma_f32_16x16x32_bf16 v[6:9], v[150:153], v[206:209], v[6:9]
	v_mfma_f32_16x16x32_bf16 v[2:5], v[158:161], v[206:209], v[2:5]
	s_setprio 0
	s_barrier
	s_add_i32 s47, 0, 0x18000
	s_add_i32 s52, 0, 0x1c000
	v_add_u32_e32 v142, s47, v220
	v_add_u32_e32 v158, s52, v220
	ds_read_b128 v[130:133], v142
	ds_read_b128 v[134:137], v142 offset:1024
	ds_read_b128 v[138:141], v142 offset:2048
	ds_read_b128 v[142:145], v142 offset:3072
	ds_read_b128 v[146:149], v158
	ds_read_b128 v[150:153], v158 offset:1024
	ds_read_b128 v[154:157], v158 offset:2048
	ds_read_b128 v[158:161], v158 offset:3072
	s_add_u32 s30, s30, 0x80000
	s_addc_u32 s31, s31, 0
	s_mov_b32 m0, s36
	v_lshl_add_u64 v[218:219], s[30:31], 0, v[186:187]
	ds_read_b128 v[162:165], v222 offset:32768
	ds_read_b128 v[166:169], v222 offset:33792
	ds_read_b128 v[170:173], v222 offset:34816
	ds_read_b128 v[174:177], v222 offset:35840
	ds_read_b128 v[178:181], v222 offset:36864
	ds_read_b128 v[182:185], v222 offset:37888
	ds_read_b128 v[196:199], v222 offset:38912
	ds_read_b128 v[206:209], v222 offset:39936
	global_load_lds_dwordx4 v[218:219], off
	v_lshl_add_u64 v[218:219], s[30:31], 0, v[188:189]
	s_mov_b32 m0, s37
	s_nop 0
	global_load_lds_dwordx4 v[218:219], off
	s_waitcnt vmcnt(8)
	s_waitcnt lgkmcnt(0)
	s_barrier
	s_setprio 1
	s_waitcnt lgkmcnt(0)
	v_mfma_f32_16x16x32_bf16 v[126:129], v[130:133], v[162:165], v[126:129]
	v_mfma_f32_16x16x32_bf16 v[122:125], v[138:141], v[162:165], v[122:125]
	v_mfma_f32_16x16x32_bf16 v[110:113], v[130:133], v[170:173], v[110:113]
	v_mfma_f32_16x16x32_bf16 v[106:109], v[138:141], v[170:173], v[106:109]
	v_mfma_f32_16x16x32_bf16 v[94:97], v[130:133], v[178:181], v[94:97]
	v_mfma_f32_16x16x32_bf16 v[90:93], v[138:141], v[178:181], v[90:93]
	v_mfma_f32_16x16x32_bf16 v[78:81], v[130:133], v[196:199], v[78:81]
	v_mfma_f32_16x16x32_bf16 v[74:77], v[138:141], v[196:199], v[74:77]
	v_mfma_f32_16x16x32_bf16 v[126:129], v[134:137], v[166:169], v[126:129]
	v_mfma_f32_16x16x32_bf16 v[122:125], v[142:145], v[166:169], v[122:125]
	v_mfma_f32_16x16x32_bf16 v[110:113], v[134:137], v[174:177], v[110:113]
	v_mfma_f32_16x16x32_bf16 v[106:109], v[142:145], v[174:177], v[106:109]
	v_mfma_f32_16x16x32_bf16 v[94:97], v[134:137], v[182:185], v[94:97]
	v_mfma_f32_16x16x32_bf16 v[90:93], v[142:145], v[182:185], v[90:93]
	v_mfma_f32_16x16x32_bf16 v[78:81], v[134:137], v[206:209], v[78:81]
	v_mfma_f32_16x16x32_bf16 v[74:77], v[142:145], v[206:209], v[74:77]
	s_setprio 0
	s_setprio 1
	v_mfma_f32_16x16x32_bf16 v[118:121], v[146:149], v[162:165], v[118:121]
	v_mfma_f32_16x16x32_bf16 v[114:117], v[154:157], v[162:165], v[114:117]
	v_mfma_f32_16x16x32_bf16 v[102:105], v[146:149], v[170:173], v[102:105]
	v_mfma_f32_16x16x32_bf16 v[98:101], v[154:157], v[170:173], v[98:101]
	v_mfma_f32_16x16x32_bf16 v[86:89], v[146:149], v[178:181], v[86:89]
	v_mfma_f32_16x16x32_bf16 v[82:85], v[154:157], v[178:181], v[82:85]
	v_mfma_f32_16x16x32_bf16 v[70:73], v[146:149], v[196:199], v[70:73]
	v_mfma_f32_16x16x32_bf16 v[66:69], v[154:157], v[196:199], v[66:69]
	v_mfma_f32_16x16x32_bf16 v[118:121], v[150:153], v[166:169], v[118:121]
	v_mfma_f32_16x16x32_bf16 v[114:117], v[158:161], v[166:169], v[114:117]
	v_mfma_f32_16x16x32_bf16 v[102:105], v[150:153], v[174:177], v[102:105]
	v_mfma_f32_16x16x32_bf16 v[98:101], v[158:161], v[174:177], v[98:101]
	v_mfma_f32_16x16x32_bf16 v[86:89], v[150:153], v[182:185], v[86:89]
	v_mfma_f32_16x16x32_bf16 v[82:85], v[158:161], v[182:185], v[82:85]
	v_mfma_f32_16x16x32_bf16 v[70:73], v[150:153], v[206:209], v[70:73]
	v_mfma_f32_16x16x32_bf16 v[66:69], v[158:161], v[206:209], v[66:69]
	s_setprio 0
	s_barrier
	s_add_i32 s30, s47, s33
	v_lshl_add_u64 v[210:211], v[210:211], 0, s[58:59]
	s_mov_b32 m0, s30
	ds_read_b128 v[162:165], v222 offset:49152
	ds_read_b128 v[166:169], v222 offset:50176
	ds_read_b128 v[170:173], v222 offset:51200
	ds_read_b128 v[174:177], v222 offset:52224
	ds_read_b128 v[178:181], v222 offset:53248
	ds_read_b128 v[182:185], v222 offset:54272
	ds_read_b128 v[196:199], v222 offset:55296
	ds_read_b128 v[206:209], v222 offset:56320
	global_load_lds_dwordx4 v[210:211], off
	s_add_i32 m0, s30, 0x2000
	s_add_u32 s28, s28, 0x80080
	v_lshl_add_u64 v[210:211], v[212:213], 0, s[58:59]
	s_addc_u32 s29, s29, 0
	s_add_i32 s30, s52, s33
	global_load_lds_dwordx4 v[210:211], off
	v_lshl_add_u64 v[210:211], s[28:29], 0, v[190:191]
	s_mov_b32 m0, s30
	s_nop 0
	global_load_lds_dwordx4 v[210:211], off
	v_lshl_add_u64 v[210:211], s[28:29], 0, v[200:201]
	s_add_i32 m0, s30, 0x2000
	s_nop 0
	global_load_lds_dwordx4 v[210:211], off
	v_lshl_add_u64 v[210:211], v[214:215], 0, s[58:59]
	s_mov_b32 m0, s38
	s_nop 0
	global_load_lds_dwordx4 v[210:211], off
	v_lshl_add_u64 v[210:211], v[216:217], 0, s[58:59]
	s_mov_b32 m0, s39
	s_nop 0
	global_load_lds_dwordx4 v[210:211], off
	s_waitcnt vmcnt(8)
	s_waitcnt lgkmcnt(0)
	s_barrier
	s_setprio 1
	s_waitcnt lgkmcnt(0)
	v_mfma_f32_16x16x32_bf16 v[62:65], v[130:133], v[162:165], v[62:65]
	v_mfma_f32_16x16x32_bf16 v[58:61], v[138:141], v[162:165], v[58:61]
	v_mfma_f32_16x16x32_bf16 v[46:49], v[130:133], v[170:173], v[46:49]
	v_mfma_f32_16x16x32_bf16 v[42:45], v[138:141], v[170:173], v[42:45]
	v_mfma_f32_16x16x32_bf16 v[30:33], v[130:133], v[178:181], v[30:33]
	v_mfma_f32_16x16x32_bf16 v[26:29], v[138:141], v[178:181], v[26:29]
	v_mfma_f32_16x16x32_bf16 v[14:17], v[130:133], v[196:199], v[14:17]
	v_mfma_f32_16x16x32_bf16 v[10:13], v[138:141], v[196:199], v[10:13]
	v_mfma_f32_16x16x32_bf16 v[62:65], v[134:137], v[166:169], v[62:65]
	v_mfma_f32_16x16x32_bf16 v[58:61], v[142:145], v[166:169], v[58:61]
	v_mfma_f32_16x16x32_bf16 v[46:49], v[134:137], v[174:177], v[46:49]
	v_mfma_f32_16x16x32_bf16 v[42:45], v[142:145], v[174:177], v[42:45]
	v_mfma_f32_16x16x32_bf16 v[30:33], v[134:137], v[182:185], v[30:33]
	v_mfma_f32_16x16x32_bf16 v[26:29], v[142:145], v[182:185], v[26:29]
	v_mfma_f32_16x16x32_bf16 v[14:17], v[134:137], v[206:209], v[14:17]
	v_mfma_f32_16x16x32_bf16 v[10:13], v[142:145], v[206:209], v[10:13]
	s_setprio 0
	s_setprio 1
	v_mfma_f32_16x16x32_bf16 v[54:57], v[146:149], v[162:165], v[54:57]
	v_mfma_f32_16x16x32_bf16 v[50:53], v[154:157], v[162:165], v[50:53]
	v_mfma_f32_16x16x32_bf16 v[38:41], v[146:149], v[170:173], v[38:41]
	v_mfma_f32_16x16x32_bf16 v[34:37], v[154:157], v[170:173], v[34:37]
	v_mfma_f32_16x16x32_bf16 v[22:25], v[146:149], v[178:181], v[22:25]
	v_mfma_f32_16x16x32_bf16 v[18:21], v[154:157], v[178:181], v[18:21]
	v_mfma_f32_16x16x32_bf16 v[6:9], v[146:149], v[196:199], v[6:9]
	v_mfma_f32_16x16x32_bf16 v[2:5], v[154:157], v[196:199], v[2:5]
	v_mfma_f32_16x16x32_bf16 v[54:57], v[150:153], v[166:169], v[54:57]
	v_mfma_f32_16x16x32_bf16 v[50:53], v[158:161], v[166:169], v[50:53]
	v_mfma_f32_16x16x32_bf16 v[38:41], v[150:153], v[174:177], v[38:41]
	v_mfma_f32_16x16x32_bf16 v[34:37], v[158:161], v[174:177], v[34:37]
	v_mfma_f32_16x16x32_bf16 v[22:25], v[150:153], v[182:185], v[22:25]
	v_mfma_f32_16x16x32_bf16 v[18:21], v[158:161], v[182:185], v[18:21]
	v_mfma_f32_16x16x32_bf16 v[6:9], v[150:153], v[206:209], v[6:9]
	v_mfma_f32_16x16x32_bf16 v[2:5], v[158:161], v[206:209], v[2:5]
	s_setprio 0
	s_barrier
	s_add_i32 s46, s46, 2
	s_add_u32 s26, s26, 0x100
	s_addc_u32 s27, s27, 0
	s_add_u32 s42, s42, 0x100
	s_addc_u32 s43, s43, 0
	s_cmp_gt_u32 s46, 29
	s_cbranch_scc1 .Lpeel_done_3

.Lpeel_done_3:
	s_and_b64 vcc, exec, s[10:11]
	s_cbranch_vccz .LBB0_775
	s_barrier

.LBB0_799:
	s_ashr_i32 s11, s10, 31
	s_lshl_b64 s[14:15], s[10:11], 20
	s_add_u32 s14, s69, s14
	s_addc_u32 s15, s77, s15
	s_and_b64 s[16:17], s[12:13], exec
	s_cselect_b32 s11, s15, s25
	s_cselect_b32 s21, s14, s24
	s_ashr_i32 s9, s8, 31
	s_lshl_b64 s[16:17], s[8:9], 20
	v_readlane_b32 s0, v254, 42
	v_readlane_b32 s1, v254, 43
	s_add_u32 s16, s0, s16
	s_addc_u32 s17, s1, s17
	s_and_b64 s[28:29], s[12:13], exec
	s_cselect_b32 s9, s17, s27
	s_cselect_b32 s47, s16, s26
	s_add_u32 s24, s24, 0x80080
	s_addc_u32 s25, s25, 0
	s_add_u32 s52, s26, 0x100
	s_addc_u32 s53, s27, 0
	s_mov_b32 s55, -2
	v_readlane_b32 s56, v255, 49
	s_nop 3
	s_cmp_eq_u32 s56, 5
	v_writelane_b32 v255, 5, 49
	s_cbranch_scc0 .Ltrip0_strict_4
	s_add_u32 s26, s24, 0xfff80080
	s_addc_u32 s27, s25, -1
	s_add_i32 s56, 0, 0x10000
	s_cmp_eq_u32 s55, 28
	s_cselect_b32 s29, s11, s27
	s_cselect_b32 s28, s21, s26
	s_cselect_b32 s27, s9, s53
	s_cselect_b32 s26, s47, s52
	s_add_i32 s60, 0, 0x14000
	v_add_u32_e32 v142, s56, v238
	v_add_u32_e32 v158, s60, v238
	ds_read_b128 v[130:133], v142
	ds_read_b128 v[134:137], v142 offset:1024
	ds_read_b128 v[138:141], v142 offset:2048
	ds_read_b128 v[142:145], v142 offset:3072
	ds_read_b128 v[146:149], v158
	ds_read_b128 v[150:153], v158 offset:1024
	ds_read_b128 v[154:157], v158 offset:2048
	ds_read_b128 v[158:161], v158 offset:3072
	v_lshl_add_u64 v[210:211], s[24:25], 0, v[206:207]
	s_add_i32 m0, s23, 0xc000
	ds_read_b128 v[162:165], v240
	ds_read_b128 v[166:169], v240 offset:1024
	ds_read_b128 v[170:173], v240 offset:2048
	ds_read_b128 v[174:177], v240 offset:3072
	ds_read_b128 v[178:181], v240 offset:4096
	ds_read_b128 v[182:185], v240 offset:5120
	ds_read_b128 v[186:189], v240 offset:6144
	ds_read_b128 v[196:199], v240 offset:7168
	global_load_lds_dwordx4 v[210:211], off
	v_lshl_add_u64 v[210:211], s[24:25], 0, v[208:209]
	s_add_i32 m0, s23, 0xe000
	s_nop 0
	global_load_lds_dwordx4 v[210:211], off
	s_waitcnt vmcnt(24)
	s_waitcnt lgkmcnt(0)
	s_barrier
	s_setprio 1
	s_waitcnt lgkmcnt(0)
	v_mfma_f32_16x16x32_bf16 v[126:129], v[130:133], v[162:165], 0
	v_mfma_f32_16x16x32_bf16 v[122:125], v[138:141], v[162:165], 0
	v_mfma_f32_16x16x32_bf16 v[110:113], v[130:133], v[170:173], 0
	v_mfma_f32_16x16x32_bf16 v[106:109], v[138:141], v[170:173], 0
	v_mfma_f32_16x16x32_bf16 v[98:101], v[130:133], v[178:181], 0
	v_mfma_f32_16x16x32_bf16 v[90:93], v[138:141], v[178:181], 0
	v_mfma_f32_16x16x32_bf16 v[82:85], v[130:133], v[186:189], 0
	v_mfma_f32_16x16x32_bf16 v[74:77], v[138:141], v[186:189], 0
	v_mfma_f32_16x16x32_bf16 v[126:129], v[134:137], v[166:169], v[126:129]
	v_mfma_f32_16x16x32_bf16 v[122:125], v[142:145], v[166:169], v[122:125]
	v_mfma_f32_16x16x32_bf16 v[110:113], v[134:137], v[174:177], v[110:113]
	v_mfma_f32_16x16x32_bf16 v[106:109], v[142:145], v[174:177], v[106:109]
	v_mfma_f32_16x16x32_bf16 v[98:101], v[134:137], v[182:185], v[98:101]
	v_mfma_f32_16x16x32_bf16 v[90:93], v[142:145], v[182:185], v[90:93]
	v_mfma_f32_16x16x32_bf16 v[82:85], v[134:137], v[196:199], v[82:85]
	v_mfma_f32_16x16x32_bf16 v[74:77], v[142:145], v[196:199], v[74:77]
	s_setprio 0
	s_setprio 1
	v_mfma_f32_16x16x32_bf16 v[118:121], v[146:149], v[162:165], 0
	v_mfma_f32_16x16x32_bf16 v[114:117], v[154:157], v[162:165], 0
	v_mfma_f32_16x16x32_bf16 v[102:105], v[146:149], v[170:173], 0
	v_mfma_f32_16x16x32_bf16 v[94:97], v[154:157], v[170:173], 0
	v_mfma_f32_16x16x32_bf16 v[86:89], v[146:149], v[178:181], 0
	v_mfma_f32_16x16x32_bf16 v[78:81], v[154:157], v[178:181], 0
	v_mfma_f32_16x16x32_bf16 v[70:73], v[146:149], v[186:189], 0
	v_mfma_f32_16x16x32_bf16 v[66:69], v[154:157], v[186:189], 0
	v_mfma_f32_16x16x32_bf16 v[118:121], v[150:153], v[166:169], v[118:121]
	v_mfma_f32_16x16x32_bf16 v[114:117], v[158:161], v[166:169], v[114:117]
	v_mfma_f32_16x16x32_bf16 v[102:105], v[150:153], v[174:177], v[102:105]
	v_mfma_f32_16x16x32_bf16 v[94:97], v[158:161], v[174:177], v[94:97]
	v_mfma_f32_16x16x32_bf16 v[86:89], v[150:153], v[182:185], v[86:89]
	v_mfma_f32_16x16x32_bf16 v[78:81], v[158:161], v[182:185], v[78:81]
	v_mfma_f32_16x16x32_bf16 v[70:73], v[150:153], v[196:199], v[70:73]
	v_mfma_f32_16x16x32_bf16 v[66:69], v[158:161], v[196:199], v[66:69]
	s_setprio 0
	s_barrier
	s_add_i32 s56, s56, s34
	v_lshl_add_u64 v[210:211], s[26:27], 0, v[190:191]
	s_mov_b32 m0, s56
	ds_read_b128 v[162:165], v240 offset:16384
	ds_read_b128 v[166:169], v240 offset:17408
	ds_read_b128 v[170:173], v240 offset:18432
	ds_read_b128 v[174:177], v240 offset:19456
	ds_read_b128 v[178:181], v240 offset:20480
	ds_read_b128 v[182:185], v240 offset:21504
	ds_read_b128 v[186:189], v240 offset:22528
	ds_read_b128 v[196:199], v240 offset:23552
	global_load_lds_dwordx4 v[210:211], off
	s_add_i32 m0, s56, 0x2000
	s_add_u32 s56, s26, 0x80000
	v_lshl_add_u64 v[212:213], s[26:27], 0, v[204:205]
	s_addc_u32 s57, s27, 0
	s_add_i32 s60, s60, s34
	global_load_lds_dwordx4 v[212:213], off
	v_lshl_add_u64 v[214:215], s[56:57], 0, v[190:191]
	s_mov_b32 m0, s60
	v_lshl_add_u64 v[216:217], s[28:29], 0, v[202:203]
	global_load_lds_dwordx4 v[214:215], off
	v_lshl_add_u64 v[214:215], s[56:57], 0, v[204:205]
	s_add_i32 m0, s60, 0x2000
	s_nop 0
	global_load_lds_dwordx4 v[214:215], off
	v_lshl_add_u64 v[214:215], s[28:29], 0, v[200:201]
	s_mov_b32 m0, s23
	s_nop 0
	global_load_lds_dwordx4 v[214:215], off
	s_mov_b32 m0, s35
	s_nop 0
	global_load_lds_dwordx4 v[216:217], off
	s_waitcnt vmcnt(24)
	s_waitcnt lgkmcnt(0)
	s_barrier
	s_setprio 1
	s_waitcnt lgkmcnt(0)
	v_mfma_f32_16x16x32_bf16 v[62:65], v[130:133], v[162:165], 0
	v_mfma_f32_16x16x32_bf16 v[58:61], v[138:141], v[162:165], 0
	v_mfma_f32_16x16x32_bf16 v[50:53], v[130:133], v[170:173], 0
	v_mfma_f32_16x16x32_bf16 v[42:45], v[138:141], v[170:173], 0
	v_mfma_f32_16x16x32_bf16 v[34:37], v[130:133], v[178:181], 0
	v_mfma_f32_16x16x32_bf16 v[26:29], v[138:141], v[178:181], 0
	v_mfma_f32_16x16x32_bf16 v[18:21], v[130:133], v[186:189], 0
	v_mfma_f32_16x16x32_bf16 v[10:13], v[138:141], v[186:189], 0
	v_mfma_f32_16x16x32_bf16 v[62:65], v[134:137], v[166:169], v[62:65]
	v_mfma_f32_16x16x32_bf16 v[58:61], v[142:145], v[166:169], v[58:61]
	v_mfma_f32_16x16x32_bf16 v[50:53], v[134:137], v[174:177], v[50:53]
	v_mfma_f32_16x16x32_bf16 v[42:45], v[142:145], v[174:177], v[42:45]
	v_mfma_f32_16x16x32_bf16 v[34:37], v[134:137], v[182:185], v[34:37]
	v_mfma_f32_16x16x32_bf16 v[26:29], v[142:145], v[182:185], v[26:29]
	v_mfma_f32_16x16x32_bf16 v[18:21], v[134:137], v[196:199], v[18:21]
	v_mfma_f32_16x16x32_bf16 v[10:13], v[142:145], v[196:199], v[10:13]
	s_setprio 0
	s_setprio 1
	v_mfma_f32_16x16x32_bf16 v[54:57], v[146:149], v[162:165], 0
	v_mfma_f32_16x16x32_bf16 v[46:49], v[154:157], v[162:165], 0
	v_mfma_f32_16x16x32_bf16 v[38:41], v[146:149], v[170:173], 0
	v_mfma_f32_16x16x32_bf16 v[30:33], v[154:157], v[170:173], 0
	v_mfma_f32_16x16x32_bf16 v[22:25], v[146:149], v[178:181], 0
	v_mfma_f32_16x16x32_bf16 v[14:17], v[154:157], v[178:181], 0
	v_mfma_f32_16x16x32_bf16 v[6:9], v[146:149], v[186:189], 0
	v_mfma_f32_16x16x32_bf16 v[2:5], v[154:157], v[186:189], 0
	v_mfma_f32_16x16x32_bf16 v[54:57], v[150:153], v[166:169], v[54:57]
	v_mfma_f32_16x16x32_bf16 v[46:49], v[158:161], v[166:169], v[46:49]
	v_mfma_f32_16x16x32_bf16 v[38:41], v[150:153], v[174:177], v[38:41]
	v_mfma_f32_16x16x32_bf16 v[30:33], v[158:161], v[174:177], v[30:33]
	v_mfma_f32_16x16x32_bf16 v[22:25], v[150:153], v[182:185], v[22:25]
	v_mfma_f32_16x16x32_bf16 v[14:17], v[158:161], v[182:185], v[14:17]
	v_mfma_f32_16x16x32_bf16 v[6:9], v[150:153], v[196:199], v[6:9]
	v_mfma_f32_16x16x32_bf16 v[2:5], v[158:161], v[196:199], v[2:5]
	s_setprio 0
	s_barrier
	s_add_i32 s56, 0, 0x18000
	s_add_i32 s57, 0, 0x1c000
	v_add_u32_e32 v142, s56, v238
	v_add_u32_e32 v158, s57, v238
	ds_read_b128 v[130:133], v142
	ds_read_b128 v[134:137], v142 offset:1024
	ds_read_b128 v[138:141], v142 offset:2048
	ds_read_b128 v[142:145], v142 offset:3072
	ds_read_b128 v[146:149], v158
	ds_read_b128 v[150:153], v158 offset:1024
	ds_read_b128 v[154:157], v158 offset:2048
	ds_read_b128 v[158:161], v158 offset:3072
	s_add_u32 s28, s28, 0x80000
	s_addc_u32 s29, s29, 0
	s_mov_b32 m0, s41
	v_lshl_add_u64 v[218:219], s[28:29], 0, v[200:201]
	ds_read_b128 v[162:165], v240 offset:32768
	ds_read_b128 v[166:169], v240 offset:33792
	ds_read_b128 v[170:173], v240 offset:34816
	ds_read_b128 v[174:177], v240 offset:35840
	ds_read_b128 v[178:181], v240 offset:36864
	ds_read_b128 v[182:185], v240 offset:37888
	ds_read_b128 v[186:189], v240 offset:38912
	ds_read_b128 v[196:199], v240 offset:39936
	global_load_lds_dwordx4 v[218:219], off
	v_lshl_add_u64 v[218:219], s[28:29], 0, v[202:203]
	s_mov_b32 m0, s42
	s_nop 0
	global_load_lds_dwordx4 v[218:219], off
	s_waitcnt vmcnt(8)
	s_waitcnt lgkmcnt(0)
	s_barrier
	s_setprio 1
	s_waitcnt lgkmcnt(0)
	v_mfma_f32_16x16x32_bf16 v[126:129], v[130:133], v[162:165], v[126:129]
	v_mfma_f32_16x16x32_bf16 v[122:125], v[138:141], v[162:165], v[122:125]
	v_mfma_f32_16x16x32_bf16 v[110:113], v[130:133], v[170:173], v[110:113]
	v_mfma_f32_16x16x32_bf16 v[106:109], v[138:141], v[170:173], v[106:109]
	v_mfma_f32_16x16x32_bf16 v[98:101], v[130:133], v[178:181], v[98:101]
	v_mfma_f32_16x16x32_bf16 v[90:93], v[138:141], v[178:181], v[90:93]
	v_mfma_f32_16x16x32_bf16 v[82:85], v[130:133], v[186:189], v[82:85]
	v_mfma_f32_16x16x32_bf16 v[74:77], v[138:141], v[186:189], v[74:77]
	v_mfma_f32_16x16x32_bf16 v[126:129], v[134:137], v[166:169], v[126:129]
	v_mfma_f32_16x16x32_bf16 v[122:125], v[142:145], v[166:169], v[122:125]
	v_mfma_f32_16x16x32_bf16 v[110:113], v[134:137], v[174:177], v[110:113]
	v_mfma_f32_16x16x32_bf16 v[106:109], v[142:145], v[174:177], v[106:109]
	v_mfma_f32_16x16x32_bf16 v[98:101], v[134:137], v[182:185], v[98:101]
	v_mfma_f32_16x16x32_bf16 v[90:93], v[142:145], v[182:185], v[90:93]
	v_mfma_f32_16x16x32_bf16 v[82:85], v[134:137], v[196:199], v[82:85]
	v_mfma_f32_16x16x32_bf16 v[74:77], v[142:145], v[196:199], v[74:77]
	s_setprio 0
	s_setprio 1
	v_mfma_f32_16x16x32_bf16 v[118:121], v[146:149], v[162:165], v[118:121]
	v_mfma_f32_16x16x32_bf16 v[114:117], v[154:157], v[162:165], v[114:117]
	v_mfma_f32_16x16x32_bf16 v[102:105], v[146:149], v[170:173], v[102:105]
	v_mfma_f32_16x16x32_bf16 v[94:97], v[154:157], v[170:173], v[94:97]
	v_mfma_f32_16x16x32_bf16 v[86:89], v[146:149], v[178:181], v[86:89]
	v_mfma_f32_16x16x32_bf16 v[78:81], v[154:157], v[178:181], v[78:81]
	v_mfma_f32_16x16x32_bf16 v[70:73], v[146:149], v[186:189], v[70:73]
	v_mfma_f32_16x16x32_bf16 v[66:69], v[154:157], v[186:189], v[66:69]
	v_mfma_f32_16x16x32_bf16 v[118:121], v[150:153], v[166:169], v[118:121]
	v_mfma_f32_16x16x32_bf16 v[114:117], v[158:161], v[166:169], v[114:117]
	v_mfma_f32_16x16x32_bf16 v[102:105], v[150:153], v[174:177], v[102:105]
	v_mfma_f32_16x16x32_bf16 v[94:97], v[158:161], v[174:177], v[94:97]
	v_mfma_f32_16x16x32_bf16 v[86:89], v[150:153], v[182:185], v[86:89]
	v_mfma_f32_16x16x32_bf16 v[78:81], v[158:161], v[182:185], v[78:81]
	v_mfma_f32_16x16x32_bf16 v[70:73], v[150:153], v[196:199], v[70:73]
	v_mfma_f32_16x16x32_bf16 v[66:69], v[158:161], v[196:199], v[66:69]
	s_setprio 0
	s_barrier
	s_add_i32 s28, s56, s34
	v_lshl_add_u64 v[210:211], v[210:211], 0, s[58:59]
	s_mov_b32 m0, s28
	ds_read_b128 v[162:165], v240 offset:49152
	ds_read_b128 v[166:169], v240 offset:50176
	ds_read_b128 v[170:173], v240 offset:51200
	ds_read_b128 v[174:177], v240 offset:52224
	ds_read_b128 v[178:181], v240 offset:53248
	ds_read_b128 v[182:185], v240 offset:54272
	ds_read_b128 v[186:189], v240 offset:55296
	ds_read_b128 v[196:199], v240 offset:56320
	global_load_lds_dwordx4 v[210:211], off
	s_add_i32 m0, s28, 0x2000
	s_add_u32 s26, s26, 0x80080
	v_lshl_add_u64 v[210:211], v[212:213], 0, s[58:59]
	s_addc_u32 s27, s27, 0
	s_add_i32 s28, s57, s34
	global_load_lds_dwordx4 v[210:211], off
	v_lshl_add_u64 v[210:211], s[26:27], 0, v[190:191]
	s_mov_b32 m0, s28
	s_nop 0
	global_load_lds_dwordx4 v[210:211], off
	v_lshl_add_u64 v[210:211], s[26:27], 0, v[204:205]
	s_add_i32 m0, s28, 0x2000
	s_nop 0
	global_load_lds_dwordx4 v[210:211], off
	v_lshl_add_u64 v[210:211], v[214:215], 0, s[58:59]
	s_mov_b32 m0, s43
	s_nop 0
	global_load_lds_dwordx4 v[210:211], off
	v_lshl_add_u64 v[210:211], v[216:217], 0, s[58:59]
	s_mov_b32 m0, s46
	s_nop 0
	global_load_lds_dwordx4 v[210:211], off
	s_waitcnt vmcnt(8)
	s_waitcnt lgkmcnt(0)
	s_barrier
	s_setprio 1
	s_waitcnt lgkmcnt(0)
	v_mfma_f32_16x16x32_bf16 v[62:65], v[130:133], v[162:165], v[62:65]
	v_mfma_f32_16x16x32_bf16 v[58:61], v[138:141], v[162:165], v[58:61]
	v_mfma_f32_16x16x32_bf16 v[50:53], v[130:133], v[170:173], v[50:53]
	v_mfma_f32_16x16x32_bf16 v[42:45], v[138:141], v[170:173], v[42:45]
	v_mfma_f32_16x16x32_bf16 v[34:37], v[130:133], v[178:181], v[34:37]
	v_mfma_f32_16x16x32_bf16 v[26:29], v[138:141], v[178:181], v[26:29]
	v_mfma_f32_16x16x32_bf16 v[18:21], v[130:133], v[186:189], v[18:21]
	v_mfma_f32_16x16x32_bf16 v[10:13], v[138:141], v[186:189], v[10:13]
	v_mfma_f32_16x16x32_bf16 v[62:65], v[134:137], v[166:169], v[62:65]
	v_mfma_f32_16x16x32_bf16 v[58:61], v[142:145], v[166:169], v[58:61]
	v_mfma_f32_16x16x32_bf16 v[50:53], v[134:137], v[174:177], v[50:53]
	v_mfma_f32_16x16x32_bf16 v[42:45], v[142:145], v[174:177], v[42:45]
	v_mfma_f32_16x16x32_bf16 v[34:37], v[134:137], v[182:185], v[34:37]
	v_mfma_f32_16x16x32_bf16 v[26:29], v[142:145], v[182:185], v[26:29]
	v_mfma_f32_16x16x32_bf16 v[18:21], v[134:137], v[196:199], v[18:21]
	v_mfma_f32_16x16x32_bf16 v[10:13], v[142:145], v[196:199], v[10:13]
	s_setprio 0
	s_setprio 1
	v_mfma_f32_16x16x32_bf16 v[54:57], v[146:149], v[162:165], v[54:57]
	v_mfma_f32_16x16x32_bf16 v[46:49], v[154:157], v[162:165], v[46:49]
	v_mfma_f32_16x16x32_bf16 v[38:41], v[146:149], v[170:173], v[38:41]
	v_mfma_f32_16x16x32_bf16 v[30:33], v[154:157], v[170:173], v[30:33]
	v_mfma_f32_16x16x32_bf16 v[22:25], v[146:149], v[178:181], v[22:25]
	v_mfma_f32_16x16x32_bf16 v[14:17], v[154:157], v[178:181], v[14:17]
	v_mfma_f32_16x16x32_bf16 v[6:9], v[146:149], v[186:189], v[6:9]
	v_mfma_f32_16x16x32_bf16 v[2:5], v[154:157], v[186:189], v[2:5]
	v_mfma_f32_16x16x32_bf16 v[54:57], v[150:153], v[166:169], v[54:57]
	v_mfma_f32_16x16x32_bf16 v[46:49], v[158:161], v[166:169], v[46:49]
	v_mfma_f32_16x16x32_bf16 v[38:41], v[150:153], v[174:177], v[38:41]
	v_mfma_f32_16x16x32_bf16 v[30:33], v[158:161], v[174:177], v[30:33]
	v_mfma_f32_16x16x32_bf16 v[22:25], v[150:153], v[182:185], v[22:25]
	v_mfma_f32_16x16x32_bf16 v[14:17], v[158:161], v[182:185], v[14:17]
	v_mfma_f32_16x16x32_bf16 v[6:9], v[150:153], v[196:199], v[6:9]
	v_mfma_f32_16x16x32_bf16 v[2:5], v[158:161], v[196:199], v[2:5]
	s_setprio 0
	s_barrier
	s_add_i32 s55, s55, 2
	s_add_u32 s24, s24, 0x100
	s_addc_u32 s25, s25, 0
	s_add_u32 s52, s52, 0x100
	s_addc_u32 s53, s53, 0
	s_cmp_gt_u32 s55, 29
	s_cbranch_scc1 .Lpeel_done_4
	s_branch .LBB0_800
.Ltrip0_strict_4:
	s_add_u32 s26, s24, 0xfff80080
	s_addc_u32 s27, s25, -1
	s_add_i32 s56, 0, 0x10000
	s_cmp_eq_u32 s55, 28
	s_cselect_b32 s29, s11, s27
	s_cselect_b32 s28, s21, s26
	s_cselect_b32 s27, s9, s53
	s_cselect_b32 s26, s47, s52
	s_add_i32 s60, 0, 0x14000
	v_add_u32_e32 v142, s56, v238
	v_add_u32_e32 v158, s60, v238
	ds_read_b128 v[130:133], v142
	ds_read_b128 v[134:137], v142 offset:1024
	ds_read_b128 v[138:141], v142 offset:2048
	ds_read_b128 v[142:145], v142 offset:3072
	ds_read_b128 v[146:149], v158
	ds_read_b128 v[150:153], v158 offset:1024
	ds_read_b128 v[154:157], v158 offset:2048
	ds_read_b128 v[158:161], v158 offset:3072
	v_lshl_add_u64 v[210:211], s[24:25], 0, v[206:207]
	s_add_i32 m0, s23, 0xc000
	ds_read_b128 v[162:165], v240
	ds_read_b128 v[166:169], v240 offset:1024
	ds_read_b128 v[170:173], v240 offset:2048
	ds_read_b128 v[174:177], v240 offset:3072
	ds_read_b128 v[178:181], v240 offset:4096
	ds_read_b128 v[182:185], v240 offset:5120
	ds_read_b128 v[186:189], v240 offset:6144
	ds_read_b128 v[196:199], v240 offset:7168
	global_load_lds_dwordx4 v[210:211], off
	v_lshl_add_u64 v[210:211], s[24:25], 0, v[208:209]
	s_add_i32 m0, s23, 0xe000
	s_nop 0
	global_load_lds_dwordx4 v[210:211], off
	s_waitcnt vmcnt(8)
	s_waitcnt lgkmcnt(0)
	s_barrier
	s_setprio 1
	s_waitcnt lgkmcnt(0)
	v_mfma_f32_16x16x32_bf16 v[126:129], v[130:133], v[162:165], 0
	v_mfma_f32_16x16x32_bf16 v[122:125], v[138:141], v[162:165], 0
	v_mfma_f32_16x16x32_bf16 v[110:113], v[130:133], v[170:173], 0
	v_mfma_f32_16x16x32_bf16 v[106:109], v[138:141], v[170:173], 0
	v_mfma_f32_16x16x32_bf16 v[98:101], v[130:133], v[178:181], 0
	v_mfma_f32_16x16x32_bf16 v[90:93], v[138:141], v[178:181], 0
	v_mfma_f32_16x16x32_bf16 v[82:85], v[130:133], v[186:189], 0
	v_mfma_f32_16x16x32_bf16 v[74:77], v[138:141], v[186:189], 0
	v_mfma_f32_16x16x32_bf16 v[126:129], v[134:137], v[166:169], v[126:129]
	v_mfma_f32_16x16x32_bf16 v[122:125], v[142:145], v[166:169], v[122:125]
	v_mfma_f32_16x16x32_bf16 v[110:113], v[134:137], v[174:177], v[110:113]
	v_mfma_f32_16x16x32_bf16 v[106:109], v[142:145], v[174:177], v[106:109]
	v_mfma_f32_16x16x32_bf16 v[98:101], v[134:137], v[182:185], v[98:101]
	v_mfma_f32_16x16x32_bf16 v[90:93], v[142:145], v[182:185], v[90:93]
	v_mfma_f32_16x16x32_bf16 v[82:85], v[134:137], v[196:199], v[82:85]
	v_mfma_f32_16x16x32_bf16 v[74:77], v[142:145], v[196:199], v[74:77]
	s_setprio 0
	s_setprio 1
	v_mfma_f32_16x16x32_bf16 v[118:121], v[146:149], v[162:165], 0
	v_mfma_f32_16x16x32_bf16 v[114:117], v[154:157], v[162:165], 0
	v_mfma_f32_16x16x32_bf16 v[102:105], v[146:149], v[170:173], 0
	v_mfma_f32_16x16x32_bf16 v[94:97], v[154:157], v[170:173], 0
	v_mfma_f32_16x16x32_bf16 v[86:89], v[146:149], v[178:181], 0
	v_mfma_f32_16x16x32_bf16 v[78:81], v[154:157], v[178:181], 0
	v_mfma_f32_16x16x32_bf16 v[70:73], v[146:149], v[186:189], 0
	v_mfma_f32_16x16x32_bf16 v[66:69], v[154:157], v[186:189], 0
	v_mfma_f32_16x16x32_bf16 v[118:121], v[150:153], v[166:169], v[118:121]
	v_mfma_f32_16x16x32_bf16 v[114:117], v[158:161], v[166:169], v[114:117]
	v_mfma_f32_16x16x32_bf16 v[102:105], v[150:153], v[174:177], v[102:105]
	v_mfma_f32_16x16x32_bf16 v[94:97], v[158:161], v[174:177], v[94:97]
	v_mfma_f32_16x16x32_bf16 v[86:89], v[150:153], v[182:185], v[86:89]
	v_mfma_f32_16x16x32_bf16 v[78:81], v[158:161], v[182:185], v[78:81]
	v_mfma_f32_16x16x32_bf16 v[70:73], v[150:153], v[196:199], v[70:73]
	v_mfma_f32_16x16x32_bf16 v[66:69], v[158:161], v[196:199], v[66:69]
	s_setprio 0
	s_barrier
	s_add_i32 s56, s56, s34
	v_lshl_add_u64 v[210:211], s[26:27], 0, v[190:191]
	s_mov_b32 m0, s56
	ds_read_b128 v[162:165], v240 offset:16384
	ds_read_b128 v[166:169], v240 offset:17408
	ds_read_b128 v[170:173], v240 offset:18432
	ds_read_b128 v[174:177], v240 offset:19456
	ds_read_b128 v[178:181], v240 offset:20480
	ds_read_b128 v[182:185], v240 offset:21504
	ds_read_b128 v[186:189], v240 offset:22528
	ds_read_b128 v[196:199], v240 offset:23552
	global_load_lds_dwordx4 v[210:211], off
	s_add_i32 m0, s56, 0x2000
	s_add_u32 s56, s26, 0x80000
	v_lshl_add_u64 v[212:213], s[26:27], 0, v[204:205]
	s_addc_u32 s57, s27, 0
	s_add_i32 s60, s60, s34
	global_load_lds_dwordx4 v[212:213], off
	v_lshl_add_u64 v[214:215], s[56:57], 0, v[190:191]
	s_mov_b32 m0, s60
	v_lshl_add_u64 v[216:217], s[28:29], 0, v[202:203]
	global_load_lds_dwordx4 v[214:215], off
	v_lshl_add_u64 v[214:215], s[56:57], 0, v[204:205]
	s_add_i32 m0, s60, 0x2000
	s_nop 0
	global_load_lds_dwordx4 v[214:215], off
	v_lshl_add_u64 v[214:215], s[28:29], 0, v[200:201]
	s_mov_b32 m0, s23
	s_nop 0
	global_load_lds_dwordx4 v[214:215], off
	s_mov_b32 m0, s35
	s_nop 0
	global_load_lds_dwordx4 v[216:217], off
	s_waitcnt vmcnt(8)
	s_waitcnt lgkmcnt(0)
	s_barrier
	s_setprio 1
	s_waitcnt lgkmcnt(0)
	v_mfma_f32_16x16x32_bf16 v[62:65], v[130:133], v[162:165], 0
	v_mfma_f32_16x16x32_bf16 v[58:61], v[138:141], v[162:165], 0
	v_mfma_f32_16x16x32_bf16 v[50:53], v[130:133], v[170:173], 0
	v_mfma_f32_16x16x32_bf16 v[42:45], v[138:141], v[170:173], 0
	v_mfma_f32_16x16x32_bf16 v[34:37], v[130:133], v[178:181], 0
	v_mfma_f32_16x16x32_bf16 v[26:29], v[138:141], v[178:181], 0
	v_mfma_f32_16x16x32_bf16 v[18:21], v[130:133], v[186:189], 0
	v_mfma_f32_16x16x32_bf16 v[10:13], v[138:141], v[186:189], 0
	v_mfma_f32_16x16x32_bf16 v[62:65], v[134:137], v[166:169], v[62:65]
	v_mfma_f32_16x16x32_bf16 v[58:61], v[142:145], v[166:169], v[58:61]
	v_mfma_f32_16x16x32_bf16 v[50:53], v[134:137], v[174:177], v[50:53]
	v_mfma_f32_16x16x32_bf16 v[42:45], v[142:145], v[174:177], v[42:45]
	v_mfma_f32_16x16x32_bf16 v[34:37], v[134:137], v[182:185], v[34:37]
	v_mfma_f32_16x16x32_bf16 v[26:29], v[142:145], v[182:185], v[26:29]
	v_mfma_f32_16x16x32_bf16 v[18:21], v[134:137], v[196:199], v[18:21]
	v_mfma_f32_16x16x32_bf16 v[10:13], v[142:145], v[196:199], v[10:13]
	s_setprio 0
	s_setprio 1
	v_mfma_f32_16x16x32_bf16 v[54:57], v[146:149], v[162:165], 0
	v_mfma_f32_16x16x32_bf16 v[46:49], v[154:157], v[162:165], 0
	v_mfma_f32_16x16x32_bf16 v[38:41], v[146:149], v[170:173], 0
	v_mfma_f32_16x16x32_bf16 v[30:33], v[154:157], v[170:173], 0
	v_mfma_f32_16x16x32_bf16 v[22:25], v[146:149], v[178:181], 0
	v_mfma_f32_16x16x32_bf16 v[14:17], v[154:157], v[178:181], 0
	v_mfma_f32_16x16x32_bf16 v[6:9], v[146:149], v[186:189], 0
	v_mfma_f32_16x16x32_bf16 v[2:5], v[154:157], v[186:189], 0
	v_mfma_f32_16x16x32_bf16 v[54:57], v[150:153], v[166:169], v[54:57]
	v_mfma_f32_16x16x32_bf16 v[46:49], v[158:161], v[166:169], v[46:49]
	v_mfma_f32_16x16x32_bf16 v[38:41], v[150:153], v[174:177], v[38:41]
	v_mfma_f32_16x16x32_bf16 v[30:33], v[158:161], v[174:177], v[30:33]
	v_mfma_f32_16x16x32_bf16 v[22:25], v[150:153], v[182:185], v[22:25]
	v_mfma_f32_16x16x32_bf16 v[14:17], v[158:161], v[182:185], v[14:17]
	v_mfma_f32_16x16x32_bf16 v[6:9], v[150:153], v[196:199], v[6:9]
	v_mfma_f32_16x16x32_bf16 v[2:5], v[158:161], v[196:199], v[2:5]
	s_setprio 0
	s_barrier
	s_add_i32 s56, 0, 0x18000
	s_add_i32 s57, 0, 0x1c000
	v_add_u32_e32 v142, s56, v238
	v_add_u32_e32 v158, s57, v238
	ds_read_b128 v[130:133], v142
	ds_read_b128 v[134:137], v142 offset:1024
	ds_read_b128 v[138:141], v142 offset:2048
	ds_read_b128 v[142:145], v142 offset:3072
	ds_read_b128 v[146:149], v158
	ds_read_b128 v[150:153], v158 offset:1024
	ds_read_b128 v[154:157], v158 offset:2048
	ds_read_b128 v[158:161], v158 offset:3072
	s_add_u32 s28, s28, 0x80000
	s_addc_u32 s29, s29, 0
	s_mov_b32 m0, s41
	v_lshl_add_u64 v[218:219], s[28:29], 0, v[200:201]
	ds_read_b128 v[162:165], v240 offset:32768
	ds_read_b128 v[166:169], v240 offset:33792
	ds_read_b128 v[170:173], v240 offset:34816
	ds_read_b128 v[174:177], v240 offset:35840
	ds_read_b128 v[178:181], v240 offset:36864
	ds_read_b128 v[182:185], v240 offset:37888
	ds_read_b128 v[186:189], v240 offset:38912
	ds_read_b128 v[196:199], v240 offset:39936
	global_load_lds_dwordx4 v[218:219], off
	v_lshl_add_u64 v[218:219], s[28:29], 0, v[202:203]
	s_mov_b32 m0, s42
	s_nop 0
	global_load_lds_dwordx4 v[218:219], off
	s_waitcnt vmcnt(8)
	s_waitcnt lgkmcnt(0)
	s_barrier
	s_setprio 1
	s_waitcnt lgkmcnt(0)
	v_mfma_f32_16x16x32_bf16 v[126:129], v[130:133], v[162:165], v[126:129]
	v_mfma_f32_16x16x32_bf16 v[122:125], v[138:141], v[162:165], v[122:125]
	v_mfma_f32_16x16x32_bf16 v[110:113], v[130:133], v[170:173], v[110:113]
	v_mfma_f32_16x16x32_bf16 v[106:109], v[138:141], v[170:173], v[106:109]
	v_mfma_f32_16x16x32_bf16 v[98:101], v[130:133], v[178:181], v[98:101]
	v_mfma_f32_16x16x32_bf16 v[90:93], v[138:141], v[178:181], v[90:93]
	v_mfma_f32_16x16x32_bf16 v[82:85], v[130:133], v[186:189], v[82:85]
	v_mfma_f32_16x16x32_bf16 v[74:77], v[138:141], v[186:189], v[74:77]
	v_mfma_f32_16x16x32_bf16 v[126:129], v[134:137], v[166:169], v[126:129]
	v_mfma_f32_16x16x32_bf16 v[122:125], v[142:145], v[166:169], v[122:125]
	v_mfma_f32_16x16x32_bf16 v[110:113], v[134:137], v[174:177], v[110:113]
	v_mfma_f32_16x16x32_bf16 v[106:109], v[142:145], v[174:177], v[106:109]
	v_mfma_f32_16x16x32_bf16 v[98:101], v[134:137], v[182:185], v[98:101]
	v_mfma_f32_16x16x32_bf16 v[90:93], v[142:145], v[182:185], v[90:93]
	v_mfma_f32_16x16x32_bf16 v[82:85], v[134:137], v[196:199], v[82:85]
	v_mfma_f32_16x16x32_bf16 v[74:77], v[142:145], v[196:199], v[74:77]
	s_setprio 0
	s_setprio 1
	v_mfma_f32_16x16x32_bf16 v[118:121], v[146:149], v[162:165], v[118:121]
	v_mfma_f32_16x16x32_bf16 v[114:117], v[154:157], v[162:165], v[114:117]
	v_mfma_f32_16x16x32_bf16 v[102:105], v[146:149], v[170:173], v[102:105]
	v_mfma_f32_16x16x32_bf16 v[94:97], v[154:157], v[170:173], v[94:97]
	v_mfma_f32_16x16x32_bf16 v[86:89], v[146:149], v[178:181], v[86:89]
	v_mfma_f32_16x16x32_bf16 v[78:81], v[154:157], v[178:181], v[78:81]
	v_mfma_f32_16x16x32_bf16 v[70:73], v[146:149], v[186:189], v[70:73]
	v_mfma_f32_16x16x32_bf16 v[66:69], v[154:157], v[186:189], v[66:69]
	v_mfma_f32_16x16x32_bf16 v[118:121], v[150:153], v[166:169], v[118:121]
	v_mfma_f32_16x16x32_bf16 v[114:117], v[158:161], v[166:169], v[114:117]
	v_mfma_f32_16x16x32_bf16 v[102:105], v[150:153], v[174:177], v[102:105]
	v_mfma_f32_16x16x32_bf16 v[94:97], v[158:161], v[174:177], v[94:97]
	v_mfma_f32_16x16x32_bf16 v[86:89], v[150:153], v[182:185], v[86:89]
	v_mfma_f32_16x16x32_bf16 v[78:81], v[158:161], v[182:185], v[78:81]
	v_mfma_f32_16x16x32_bf16 v[70:73], v[150:153], v[196:199], v[70:73]
	v_mfma_f32_16x16x32_bf16 v[66:69], v[158:161], v[196:199], v[66:69]
	s_setprio 0
	s_barrier
	s_add_i32 s28, s56, s34
	v_lshl_add_u64 v[210:211], v[210:211], 0, s[58:59]
	s_mov_b32 m0, s28
	ds_read_b128 v[162:165], v240 offset:49152
	ds_read_b128 v[166:169], v240 offset:50176
	ds_read_b128 v[170:173], v240 offset:51200
	ds_read_b128 v[174:177], v240 offset:52224
	ds_read_b128 v[178:181], v240 offset:53248
	ds_read_b128 v[182:185], v240 offset:54272
	ds_read_b128 v[186:189], v240 offset:55296
	ds_read_b128 v[196:199], v240 offset:56320
	global_load_lds_dwordx4 v[210:211], off
	s_add_i32 m0, s28, 0x2000
	s_add_u32 s26, s26, 0x80080
	v_lshl_add_u64 v[210:211], v[212:213], 0, s[58:59]
	s_addc_u32 s27, s27, 0
	s_add_i32 s28, s57, s34
	global_load_lds_dwordx4 v[210:211], off
	v_lshl_add_u64 v[210:211], s[26:27], 0, v[190:191]
	s_mov_b32 m0, s28
	s_nop 0
	global_load_lds_dwordx4 v[210:211], off
	v_lshl_add_u64 v[210:211], s[26:27], 0, v[204:205]
	s_add_i32 m0, s28, 0x2000
	s_nop 0
	global_load_lds_dwordx4 v[210:211], off
	v_lshl_add_u64 v[210:211], v[214:215], 0, s[58:59]
	s_mov_b32 m0, s43
	s_nop 0
	global_load_lds_dwordx4 v[210:211], off
	v_lshl_add_u64 v[210:211], v[216:217], 0, s[58:59]
	s_mov_b32 m0, s46
	s_nop 0
	global_load_lds_dwordx4 v[210:211], off
	s_waitcnt vmcnt(8)
	s_waitcnt lgkmcnt(0)
	s_barrier
	s_setprio 1
	s_waitcnt lgkmcnt(0)
	v_mfma_f32_16x16x32_bf16 v[62:65], v[130:133], v[162:165], v[62:65]
	v_mfma_f32_16x16x32_bf16 v[58:61], v[138:141], v[162:165], v[58:61]
	v_mfma_f32_16x16x32_bf16 v[50:53], v[130:133], v[170:173], v[50:53]
	v_mfma_f32_16x16x32_bf16 v[42:45], v[138:141], v[170:173], v[42:45]
	v_mfma_f32_16x16x32_bf16 v[34:37], v[130:133], v[178:181], v[34:37]
	v_mfma_f32_16x16x32_bf16 v[26:29], v[138:141], v[178:181], v[26:29]
	v_mfma_f32_16x16x32_bf16 v[18:21], v[130:133], v[186:189], v[18:21]
	v_mfma_f32_16x16x32_bf16 v[10:13], v[138:141], v[186:189], v[10:13]
	v_mfma_f32_16x16x32_bf16 v[62:65], v[134:137], v[166:169], v[62:65]
	v_mfma_f32_16x16x32_bf16 v[58:61], v[142:145], v[166:169], v[58:61]
	v_mfma_f32_16x16x32_bf16 v[50:53], v[134:137], v[174:177], v[50:53]
	v_mfma_f32_16x16x32_bf16 v[42:45], v[142:145], v[174:177], v[42:45]
	v_mfma_f32_16x16x32_bf16 v[34:37], v[134:137], v[182:185], v[34:37]
	v_mfma_f32_16x16x32_bf16 v[26:29], v[142:145], v[182:185], v[26:29]
	v_mfma_f32_16x16x32_bf16 v[18:21], v[134:137], v[196:199], v[18:21]
	v_mfma_f32_16x16x32_bf16 v[10:13], v[142:145], v[196:199], v[10:13]
	s_setprio 0
	s_setprio 1
	v_mfma_f32_16x16x32_bf16 v[54:57], v[146:149], v[162:165], v[54:57]
	v_mfma_f32_16x16x32_bf16 v[46:49], v[154:157], v[162:165], v[46:49]
	v_mfma_f32_16x16x32_bf16 v[38:41], v[146:149], v[170:173], v[38:41]
	v_mfma_f32_16x16x32_bf16 v[30:33], v[154:157], v[170:173], v[30:33]
	v_mfma_f32_16x16x32_bf16 v[22:25], v[146:149], v[178:181], v[22:25]
	v_mfma_f32_16x16x32_bf16 v[14:17], v[154:157], v[178:181], v[14:17]
	v_mfma_f32_16x16x32_bf16 v[6:9], v[146:149], v[186:189], v[6:9]
	v_mfma_f32_16x16x32_bf16 v[2:5], v[154:157], v[186:189], v[2:5]
	v_mfma_f32_16x16x32_bf16 v[54:57], v[150:153], v[166:169], v[54:57]
	v_mfma_f32_16x16x32_bf16 v[46:49], v[158:161], v[166:169], v[46:49]
	v_mfma_f32_16x16x32_bf16 v[38:41], v[150:153], v[174:177], v[38:41]
	v_mfma_f32_16x16x32_bf16 v[30:33], v[158:161], v[174:177], v[30:33]
	v_mfma_f32_16x16x32_bf16 v[22:25], v[150:153], v[182:185], v[22:25]
	v_mfma_f32_16x16x32_bf16 v[14:17], v[158:161], v[182:185], v[14:17]
	v_mfma_f32_16x16x32_bf16 v[6:9], v[150:153], v[196:199], v[6:9]
	v_mfma_f32_16x16x32_bf16 v[2:5], v[158:161], v[196:199], v[2:5]
	s_setprio 0
	s_barrier
	s_add_i32 s55, s55, 2
	s_add_u32 s24, s24, 0x100
	s_addc_u32 s25, s25, 0
	s_add_u32 s52, s52, 0x100
	s_addc_u32 s53, s53, 0
	s_cmp_gt_u32 s55, 29
	s_cbranch_scc1 .Lpeel_done_4

.Lpeel_done_4:
	s_and_b64 vcc, exec, s[6:7]
	s_mov_b32 s55, 0x7f800000
	s_cbranch_vccz .LBB0_803
	s_barrier

.LBB0_822:
	s_ashr_i32 s17, s16, 31
	s_lshl_b64 s[22:23], s[16:17], 20
	v_readlane_b32 s0, v254, 60
	s_add_u32 s22, s0, s22
	v_readlane_b32 s0, v254, 61
	s_addc_u32 s23, s0, s23
	s_and_b64 s[24:25], s[20:21], exec
	s_cselect_b32 s17, s23, s31
	s_cselect_b32 s27, s22, s30
	s_ashr_i32 s15, s14, 31
	s_lshl_b64 s[24:25], s[14:15], 20
	v_readlane_b32 s0, v254, 40
	v_readlane_b32 s1, v254, 41
	s_add_u32 s24, s0, s24
	s_addc_u32 s25, s1, s25
	s_and_b64 s[52:53], s[20:21], exec
	s_cselect_b32 s15, s25, s35
	s_cselect_b32 s29, s24, s34
	s_add_u32 s30, s30, 0x80080
	s_addc_u32 s31, s31, 0
	s_add_u32 s81, s34, 0x100
	s_addc_u32 s88, s35, 0
	s_mov_b32 s89, -2
	v_readlane_b32 s90, v255, 49
	s_nop 3
	s_cmp_eq_u32 s90, 6
	v_writelane_b32 v255, 6, 49
	s_cbranch_scc0 .Ltrip0_strict_5
	s_add_u32 s34, s30, 0xfff80080
	s_addc_u32 s35, s31, -1
	s_add_i32 s90, 0, 0x10000
	s_cmp_eq_u32 s89, 28
	s_cselect_b32 s53, s17, s35
	s_cselect_b32 s52, s27, s34
	s_cselect_b32 s35, s15, s88
	s_cselect_b32 s34, s29, s81
	s_add_i32 s96, 0, 0x14000
	v_add_u32_e32 v142, s90, v220
	v_add_u32_e32 v158, s96, v220
	ds_read_b128 v[130:133], v142
	ds_read_b128 v[134:137], v142 offset:1024
	ds_read_b128 v[138:141], v142 offset:2048
	ds_read_b128 v[142:145], v142 offset:3072
	ds_read_b128 v[146:149], v158
	ds_read_b128 v[150:153], v158 offset:1024
	ds_read_b128 v[154:157], v158 offset:2048
	ds_read_b128 v[158:161], v158 offset:3072
	v_lshl_add_u64 v[210:211], s[30:31], 0, v[202:203]
	s_add_i32 m0, s55, 0xc000
	ds_read_b128 v[162:165], v222
	ds_read_b128 v[166:169], v222 offset:1024
	ds_read_b128 v[170:173], v222 offset:2048
	ds_read_b128 v[174:177], v222 offset:3072
	ds_read_b128 v[178:181], v222 offset:4096
	ds_read_b128 v[182:185], v222 offset:5120
	ds_read_b128 v[196:199], v222 offset:6144
	ds_read_b128 v[206:209], v222 offset:7168
	global_load_lds_dwordx4 v[210:211], off
	v_lshl_add_u64 v[210:211], s[30:31], 0, v[204:205]
	s_add_i32 m0, s55, 0xe000
	s_nop 0
	global_load_lds_dwordx4 v[210:211], off
	s_waitcnt vmcnt(24)
	s_waitcnt lgkmcnt(0)
	s_barrier
	s_setprio 1
	s_waitcnt lgkmcnt(0)
	v_mfma_f32_16x16x32_bf16 v[126:129], v[130:133], v[162:165], 0
	v_mfma_f32_16x16x32_bf16 v[122:125], v[138:141], v[162:165], 0
	v_mfma_f32_16x16x32_bf16 v[110:113], v[130:133], v[170:173], 0
	v_mfma_f32_16x16x32_bf16 v[106:109], v[138:141], v[170:173], 0
	v_mfma_f32_16x16x32_bf16 v[94:97], v[130:133], v[178:181], 0
	v_mfma_f32_16x16x32_bf16 v[90:93], v[138:141], v[178:181], 0
	v_mfma_f32_16x16x32_bf16 v[78:81], v[130:133], v[196:199], 0
	v_mfma_f32_16x16x32_bf16 v[74:77], v[138:141], v[196:199], 0
	v_mfma_f32_16x16x32_bf16 v[126:129], v[134:137], v[166:169], v[126:129]
	v_mfma_f32_16x16x32_bf16 v[122:125], v[142:145], v[166:169], v[122:125]
	v_mfma_f32_16x16x32_bf16 v[110:113], v[134:137], v[174:177], v[110:113]
	v_mfma_f32_16x16x32_bf16 v[106:109], v[142:145], v[174:177], v[106:109]
	v_mfma_f32_16x16x32_bf16 v[94:97], v[134:137], v[182:185], v[94:97]
	v_mfma_f32_16x16x32_bf16 v[90:93], v[142:145], v[182:185], v[90:93]
	v_mfma_f32_16x16x32_bf16 v[78:81], v[134:137], v[206:209], v[78:81]
	v_mfma_f32_16x16x32_bf16 v[74:77], v[142:145], v[206:209], v[74:77]
	s_setprio 0
	s_setprio 1
	v_mfma_f32_16x16x32_bf16 v[118:121], v[146:149], v[162:165], 0
	v_mfma_f32_16x16x32_bf16 v[114:117], v[154:157], v[162:165], 0
	v_mfma_f32_16x16x32_bf16 v[102:105], v[146:149], v[170:173], 0
	v_mfma_f32_16x16x32_bf16 v[98:101], v[154:157], v[170:173], 0
	v_mfma_f32_16x16x32_bf16 v[86:89], v[146:149], v[178:181], 0
	v_mfma_f32_16x16x32_bf16 v[82:85], v[154:157], v[178:181], 0
	v_mfma_f32_16x16x32_bf16 v[70:73], v[146:149], v[196:199], 0
	v_mfma_f32_16x16x32_bf16 v[66:69], v[154:157], v[196:199], 0
	v_mfma_f32_16x16x32_bf16 v[118:121], v[150:153], v[166:169], v[118:121]
	v_mfma_f32_16x16x32_bf16 v[114:117], v[158:161], v[166:169], v[114:117]
	v_mfma_f32_16x16x32_bf16 v[102:105], v[150:153], v[174:177], v[102:105]
	v_mfma_f32_16x16x32_bf16 v[98:101], v[158:161], v[174:177], v[98:101]
	v_mfma_f32_16x16x32_bf16 v[86:89], v[150:153], v[182:185], v[86:89]
	v_mfma_f32_16x16x32_bf16 v[82:85], v[158:161], v[182:185], v[82:85]
	v_mfma_f32_16x16x32_bf16 v[70:73], v[150:153], v[206:209], v[70:73]
	v_mfma_f32_16x16x32_bf16 v[66:69], v[158:161], v[206:209], v[66:69]
	s_setprio 0
	s_barrier
	s_add_i32 s90, s90, s47
	v_lshl_add_u64 v[210:211], s[34:35], 0, v[190:191]
	s_mov_b32 m0, s90
	ds_read_b128 v[162:165], v222 offset:16384
	ds_read_b128 v[166:169], v222 offset:17408
	ds_read_b128 v[170:173], v222 offset:18432
	ds_read_b128 v[174:177], v222 offset:19456
	ds_read_b128 v[178:181], v222 offset:20480
	ds_read_b128 v[182:185], v222 offset:21504
	ds_read_b128 v[196:199], v222 offset:22528
	ds_read_b128 v[206:209], v222 offset:23552
	global_load_lds_dwordx4 v[210:211], off
	s_add_i32 m0, s90, 0x2000
	s_add_u32 s90, s34, 0x80000
	v_lshl_add_u64 v[212:213], s[34:35], 0, v[200:201]
	s_addc_u32 s91, s35, 0
	s_add_i32 s96, s96, s47
	global_load_lds_dwordx4 v[212:213], off
	v_lshl_add_u64 v[214:215], s[90:91], 0, v[190:191]
	s_mov_b32 m0, s96
	v_lshl_add_u64 v[216:217], s[52:53], 0, v[188:189]
	global_load_lds_dwordx4 v[214:215], off
	v_lshl_add_u64 v[214:215], s[90:91], 0, v[200:201]
	s_add_i32 m0, s96, 0x2000
	s_nop 0
	global_load_lds_dwordx4 v[214:215], off
	v_lshl_add_u64 v[214:215], s[52:53], 0, v[186:187]
	s_mov_b32 m0, s55
	s_nop 0
	global_load_lds_dwordx4 v[214:215], off
	s_mov_b32 m0, s56
	s_nop 0
	global_load_lds_dwordx4 v[216:217], off
	s_waitcnt vmcnt(24)
	s_waitcnt lgkmcnt(0)
	s_barrier
	s_setprio 1
	s_waitcnt lgkmcnt(0)
	v_mfma_f32_16x16x32_bf16 v[62:65], v[130:133], v[162:165], 0
	v_mfma_f32_16x16x32_bf16 v[58:61], v[138:141], v[162:165], 0
	v_mfma_f32_16x16x32_bf16 v[46:49], v[130:133], v[170:173], 0
	v_mfma_f32_16x16x32_bf16 v[42:45], v[138:141], v[170:173], 0
	v_mfma_f32_16x16x32_bf16 v[30:33], v[130:133], v[178:181], 0
	v_mfma_f32_16x16x32_bf16 v[26:29], v[138:141], v[178:181], 0
	v_mfma_f32_16x16x32_bf16 v[14:17], v[130:133], v[196:199], 0
	v_mfma_f32_16x16x32_bf16 v[10:13], v[138:141], v[196:199], 0
	v_mfma_f32_16x16x32_bf16 v[62:65], v[134:137], v[166:169], v[62:65]
	v_mfma_f32_16x16x32_bf16 v[58:61], v[142:145], v[166:169], v[58:61]
	v_mfma_f32_16x16x32_bf16 v[46:49], v[134:137], v[174:177], v[46:49]
	v_mfma_f32_16x16x32_bf16 v[42:45], v[142:145], v[174:177], v[42:45]
	v_mfma_f32_16x16x32_bf16 v[30:33], v[134:137], v[182:185], v[30:33]
	v_mfma_f32_16x16x32_bf16 v[26:29], v[142:145], v[182:185], v[26:29]
	v_mfma_f32_16x16x32_bf16 v[14:17], v[134:137], v[206:209], v[14:17]
	v_mfma_f32_16x16x32_bf16 v[10:13], v[142:145], v[206:209], v[10:13]
	s_setprio 0
	s_setprio 1
	v_mfma_f32_16x16x32_bf16 v[54:57], v[146:149], v[162:165], 0
	v_mfma_f32_16x16x32_bf16 v[50:53], v[154:157], v[162:165], 0
	v_mfma_f32_16x16x32_bf16 v[38:41], v[146:149], v[170:173], 0
	v_mfma_f32_16x16x32_bf16 v[34:37], v[154:157], v[170:173], 0
	v_mfma_f32_16x16x32_bf16 v[22:25], v[146:149], v[178:181], 0
	v_mfma_f32_16x16x32_bf16 v[18:21], v[154:157], v[178:181], 0
	v_mfma_f32_16x16x32_bf16 v[6:9], v[146:149], v[196:199], 0
	v_mfma_f32_16x16x32_bf16 v[2:5], v[154:157], v[196:199], 0
	v_mfma_f32_16x16x32_bf16 v[54:57], v[150:153], v[166:169], v[54:57]
	v_mfma_f32_16x16x32_bf16 v[50:53], v[158:161], v[166:169], v[50:53]
	v_mfma_f32_16x16x32_bf16 v[38:41], v[150:153], v[174:177], v[38:41]
	v_mfma_f32_16x16x32_bf16 v[34:37], v[158:161], v[174:177], v[34:37]
	v_mfma_f32_16x16x32_bf16 v[22:25], v[150:153], v[182:185], v[22:25]
	v_mfma_f32_16x16x32_bf16 v[18:21], v[158:161], v[182:185], v[18:21]
	v_mfma_f32_16x16x32_bf16 v[6:9], v[150:153], v[206:209], v[6:9]
	v_mfma_f32_16x16x32_bf16 v[2:5], v[158:161], v[206:209], v[2:5]
	s_setprio 0
	s_barrier
	s_add_i32 s90, 0, 0x18000
	s_add_i32 s91, 0, 0x1c000
	v_add_u32_e32 v142, s90, v220
	v_add_u32_e32 v158, s91, v220
	ds_read_b128 v[130:133], v142
	ds_read_b128 v[134:137], v142 offset:1024
	ds_read_b128 v[138:141], v142 offset:2048
	ds_read_b128 v[142:145], v142 offset:3072
	ds_read_b128 v[146:149], v158
	ds_read_b128 v[150:153], v158 offset:1024
	ds_read_b128 v[154:157], v158 offset:2048
	ds_read_b128 v[158:161], v158 offset:3072
	s_add_u32 s52, s52, 0x80000
	s_addc_u32 s53, s53, 0
	s_mov_b32 m0, s57
	v_lshl_add_u64 v[218:219], s[52:53], 0, v[186:187]
	ds_read_b128 v[162:165], v222 offset:32768
	ds_read_b128 v[166:169], v222 offset:33792
	ds_read_b128 v[170:173], v222 offset:34816
	ds_read_b128 v[174:177], v222 offset:35840
	ds_read_b128 v[178:181], v222 offset:36864
	ds_read_b128 v[182:185], v222 offset:37888
	ds_read_b128 v[196:199], v222 offset:38912
	ds_read_b128 v[206:209], v222 offset:39936
	global_load_lds_dwordx4 v[218:219], off
	v_lshl_add_u64 v[218:219], s[52:53], 0, v[188:189]
	s_mov_b32 m0, s60
	s_nop 0
	global_load_lds_dwordx4 v[218:219], off
	s_waitcnt vmcnt(8)
	s_waitcnt lgkmcnt(0)
	s_barrier
	s_setprio 1
	s_waitcnt lgkmcnt(0)
	v_mfma_f32_16x16x32_bf16 v[126:129], v[130:133], v[162:165], v[126:129]
	v_mfma_f32_16x16x32_bf16 v[122:125], v[138:141], v[162:165], v[122:125]
	v_mfma_f32_16x16x32_bf16 v[110:113], v[130:133], v[170:173], v[110:113]
	v_mfma_f32_16x16x32_bf16 v[106:109], v[138:141], v[170:173], v[106:109]
	v_mfma_f32_16x16x32_bf16 v[94:97], v[130:133], v[178:181], v[94:97]
	v_mfma_f32_16x16x32_bf16 v[90:93], v[138:141], v[178:181], v[90:93]
	v_mfma_f32_16x16x32_bf16 v[78:81], v[130:133], v[196:199], v[78:81]
	v_mfma_f32_16x16x32_bf16 v[74:77], v[138:141], v[196:199], v[74:77]
	v_mfma_f32_16x16x32_bf16 v[126:129], v[134:137], v[166:169], v[126:129]
	v_mfma_f32_16x16x32_bf16 v[122:125], v[142:145], v[166:169], v[122:125]
	v_mfma_f32_16x16x32_bf16 v[110:113], v[134:137], v[174:177], v[110:113]
	v_mfma_f32_16x16x32_bf16 v[106:109], v[142:145], v[174:177], v[106:109]
	v_mfma_f32_16x16x32_bf16 v[94:97], v[134:137], v[182:185], v[94:97]
	v_mfma_f32_16x16x32_bf16 v[90:93], v[142:145], v[182:185], v[90:93]
	v_mfma_f32_16x16x32_bf16 v[78:81], v[134:137], v[206:209], v[78:81]
	v_mfma_f32_16x16x32_bf16 v[74:77], v[142:145], v[206:209], v[74:77]
	s_setprio 0
	s_setprio 1
	v_mfma_f32_16x16x32_bf16 v[118:121], v[146:149], v[162:165], v[118:121]
	v_mfma_f32_16x16x32_bf16 v[114:117], v[154:157], v[162:165], v[114:117]
	v_mfma_f32_16x16x32_bf16 v[102:105], v[146:149], v[170:173], v[102:105]
	v_mfma_f32_16x16x32_bf16 v[98:101], v[154:157], v[170:173], v[98:101]
	v_mfma_f32_16x16x32_bf16 v[86:89], v[146:149], v[178:181], v[86:89]
	v_mfma_f32_16x16x32_bf16 v[82:85], v[154:157], v[178:181], v[82:85]
	v_mfma_f32_16x16x32_bf16 v[70:73], v[146:149], v[196:199], v[70:73]
	v_mfma_f32_16x16x32_bf16 v[66:69], v[154:157], v[196:199], v[66:69]
	v_mfma_f32_16x16x32_bf16 v[118:121], v[150:153], v[166:169], v[118:121]
	v_mfma_f32_16x16x32_bf16 v[114:117], v[158:161], v[166:169], v[114:117]
	v_mfma_f32_16x16x32_bf16 v[102:105], v[150:153], v[174:177], v[102:105]
	v_mfma_f32_16x16x32_bf16 v[98:101], v[158:161], v[174:177], v[98:101]
	v_mfma_f32_16x16x32_bf16 v[86:89], v[150:153], v[182:185], v[86:89]
	v_mfma_f32_16x16x32_bf16 v[82:85], v[158:161], v[182:185], v[82:85]
	v_mfma_f32_16x16x32_bf16 v[70:73], v[150:153], v[206:209], v[70:73]
	v_mfma_f32_16x16x32_bf16 v[66:69], v[158:161], v[206:209], v[66:69]
	s_setprio 0
	s_barrier
	s_add_i32 s52, s90, s47
	v_lshl_add_u64 v[210:211], v[210:211], 0, s[58:59]
	s_mov_b32 m0, s52
	ds_read_b128 v[162:165], v222 offset:49152
	ds_read_b128 v[166:169], v222 offset:50176
	ds_read_b128 v[170:173], v222 offset:51200
	ds_read_b128 v[174:177], v222 offset:52224
	ds_read_b128 v[178:181], v222 offset:53248
	ds_read_b128 v[182:185], v222 offset:54272
	ds_read_b128 v[196:199], v222 offset:55296
	ds_read_b128 v[206:209], v222 offset:56320
	global_load_lds_dwordx4 v[210:211], off
	s_add_i32 m0, s52, 0x2000
	s_add_u32 s34, s34, 0x80080
	v_lshl_add_u64 v[210:211], v[212:213], 0, s[58:59]
	s_addc_u32 s35, s35, 0
	s_add_i32 s52, s91, s47
	global_load_lds_dwordx4 v[210:211], off
	v_lshl_add_u64 v[210:211], s[34:35], 0, v[190:191]
	s_mov_b32 m0, s52
	s_nop 0
	global_load_lds_dwordx4 v[210:211], off
	v_lshl_add_u64 v[210:211], s[34:35], 0, v[200:201]
	s_add_i32 m0, s52, 0x2000
	s_nop 0
	global_load_lds_dwordx4 v[210:211], off
	v_lshl_add_u64 v[210:211], v[214:215], 0, s[58:59]
	s_mov_b32 m0, s61
	s_nop 0
	global_load_lds_dwordx4 v[210:211], off
	v_lshl_add_u64 v[210:211], v[216:217], 0, s[58:59]
	s_mov_b32 m0, s69
	s_nop 0
	global_load_lds_dwordx4 v[210:211], off
	s_waitcnt vmcnt(8)
	s_waitcnt lgkmcnt(0)
	s_barrier
	s_setprio 1
	s_waitcnt lgkmcnt(0)
	v_mfma_f32_16x16x32_bf16 v[62:65], v[130:133], v[162:165], v[62:65]
	v_mfma_f32_16x16x32_bf16 v[58:61], v[138:141], v[162:165], v[58:61]
	v_mfma_f32_16x16x32_bf16 v[46:49], v[130:133], v[170:173], v[46:49]
	v_mfma_f32_16x16x32_bf16 v[42:45], v[138:141], v[170:173], v[42:45]
	v_mfma_f32_16x16x32_bf16 v[30:33], v[130:133], v[178:181], v[30:33]
	v_mfma_f32_16x16x32_bf16 v[26:29], v[138:141], v[178:181], v[26:29]
	v_mfma_f32_16x16x32_bf16 v[14:17], v[130:133], v[196:199], v[14:17]
	v_mfma_f32_16x16x32_bf16 v[10:13], v[138:141], v[196:199], v[10:13]
	v_mfma_f32_16x16x32_bf16 v[62:65], v[134:137], v[166:169], v[62:65]
	v_mfma_f32_16x16x32_bf16 v[58:61], v[142:145], v[166:169], v[58:61]
	v_mfma_f32_16x16x32_bf16 v[46:49], v[134:137], v[174:177], v[46:49]
	v_mfma_f32_16x16x32_bf16 v[42:45], v[142:145], v[174:177], v[42:45]
	v_mfma_f32_16x16x32_bf16 v[30:33], v[134:137], v[182:185], v[30:33]
	v_mfma_f32_16x16x32_bf16 v[26:29], v[142:145], v[182:185], v[26:29]
	v_mfma_f32_16x16x32_bf16 v[14:17], v[134:137], v[206:209], v[14:17]
	v_mfma_f32_16x16x32_bf16 v[10:13], v[142:145], v[206:209], v[10:13]
	s_setprio 0
	s_setprio 1
	v_mfma_f32_16x16x32_bf16 v[54:57], v[146:149], v[162:165], v[54:57]
	v_mfma_f32_16x16x32_bf16 v[50:53], v[154:157], v[162:165], v[50:53]
	v_mfma_f32_16x16x32_bf16 v[38:41], v[146:149], v[170:173], v[38:41]
	v_mfma_f32_16x16x32_bf16 v[34:37], v[154:157], v[170:173], v[34:37]
	v_mfma_f32_16x16x32_bf16 v[22:25], v[146:149], v[178:181], v[22:25]
	v_mfma_f32_16x16x32_bf16 v[18:21], v[154:157], v[178:181], v[18:21]
	v_mfma_f32_16x16x32_bf16 v[6:9], v[146:149], v[196:199], v[6:9]
	v_mfma_f32_16x16x32_bf16 v[2:5], v[154:157], v[196:199], v[2:5]
	v_mfma_f32_16x16x32_bf16 v[54:57], v[150:153], v[166:169], v[54:57]
	v_mfma_f32_16x16x32_bf16 v[50:53], v[158:161], v[166:169], v[50:53]
	v_mfma_f32_16x16x32_bf16 v[38:41], v[150:153], v[174:177], v[38:41]
	v_mfma_f32_16x16x32_bf16 v[34:37], v[158:161], v[174:177], v[34:37]
	v_mfma_f32_16x16x32_bf16 v[22:25], v[150:153], v[182:185], v[22:25]
	v_mfma_f32_16x16x32_bf16 v[18:21], v[158:161], v[182:185], v[18:21]
	v_mfma_f32_16x16x32_bf16 v[6:9], v[150:153], v[206:209], v[6:9]
	v_mfma_f32_16x16x32_bf16 v[2:5], v[158:161], v[206:209], v[2:5]
	s_setprio 0
	s_barrier
	s_add_i32 s89, s89, 2
	s_add_u32 s30, s30, 0x100
	s_addc_u32 s31, s31, 0
	s_add_u32 s81, s81, 0x100
	s_addc_u32 s88, s88, 0
	s_cmp_gt_u32 s89, 29
	s_cbranch_scc1 .Lpeel_done_5
	s_branch .LBB0_823
.Ltrip0_strict_5:
	s_add_u32 s34, s30, 0xfff80080
	s_addc_u32 s35, s31, -1
	s_add_i32 s90, 0, 0x10000
	s_cmp_eq_u32 s89, 28
	s_cselect_b32 s53, s17, s35
	s_cselect_b32 s52, s27, s34
	s_cselect_b32 s35, s15, s88
	s_cselect_b32 s34, s29, s81
	s_add_i32 s96, 0, 0x14000
	v_add_u32_e32 v142, s90, v220
	v_add_u32_e32 v158, s96, v220
	ds_read_b128 v[130:133], v142
	ds_read_b128 v[134:137], v142 offset:1024
	ds_read_b128 v[138:141], v142 offset:2048
	ds_read_b128 v[142:145], v142 offset:3072
	ds_read_b128 v[146:149], v158
	ds_read_b128 v[150:153], v158 offset:1024
	ds_read_b128 v[154:157], v158 offset:2048
	ds_read_b128 v[158:161], v158 offset:3072
	v_lshl_add_u64 v[210:211], s[30:31], 0, v[202:203]
	s_add_i32 m0, s55, 0xc000
	ds_read_b128 v[162:165], v222
	ds_read_b128 v[166:169], v222 offset:1024
	ds_read_b128 v[170:173], v222 offset:2048
	ds_read_b128 v[174:177], v222 offset:3072
	ds_read_b128 v[178:181], v222 offset:4096
	ds_read_b128 v[182:185], v222 offset:5120
	ds_read_b128 v[196:199], v222 offset:6144
	ds_read_b128 v[206:209], v222 offset:7168
	global_load_lds_dwordx4 v[210:211], off
	v_lshl_add_u64 v[210:211], s[30:31], 0, v[204:205]
	s_add_i32 m0, s55, 0xe000
	s_nop 0
	global_load_lds_dwordx4 v[210:211], off
	s_waitcnt vmcnt(8)
	s_waitcnt lgkmcnt(0)
	s_barrier
	s_setprio 1
	s_waitcnt lgkmcnt(0)
	v_mfma_f32_16x16x32_bf16 v[126:129], v[130:133], v[162:165], 0
	v_mfma_f32_16x16x32_bf16 v[122:125], v[138:141], v[162:165], 0
	v_mfma_f32_16x16x32_bf16 v[110:113], v[130:133], v[170:173], 0
	v_mfma_f32_16x16x32_bf16 v[106:109], v[138:141], v[170:173], 0
	v_mfma_f32_16x16x32_bf16 v[94:97], v[130:133], v[178:181], 0
	v_mfma_f32_16x16x32_bf16 v[90:93], v[138:141], v[178:181], 0
	v_mfma_f32_16x16x32_bf16 v[78:81], v[130:133], v[196:199], 0
	v_mfma_f32_16x16x32_bf16 v[74:77], v[138:141], v[196:199], 0
	v_mfma_f32_16x16x32_bf16 v[126:129], v[134:137], v[166:169], v[126:129]
	v_mfma_f32_16x16x32_bf16 v[122:125], v[142:145], v[166:169], v[122:125]
	v_mfma_f32_16x16x32_bf16 v[110:113], v[134:137], v[174:177], v[110:113]
	v_mfma_f32_16x16x32_bf16 v[106:109], v[142:145], v[174:177], v[106:109]
	v_mfma_f32_16x16x32_bf16 v[94:97], v[134:137], v[182:185], v[94:97]
	v_mfma_f32_16x16x32_bf16 v[90:93], v[142:145], v[182:185], v[90:93]
	v_mfma_f32_16x16x32_bf16 v[78:81], v[134:137], v[206:209], v[78:81]
	v_mfma_f32_16x16x32_bf16 v[74:77], v[142:145], v[206:209], v[74:77]
	s_setprio 0
	s_setprio 1
	v_mfma_f32_16x16x32_bf16 v[118:121], v[146:149], v[162:165], 0
	v_mfma_f32_16x16x32_bf16 v[114:117], v[154:157], v[162:165], 0
	v_mfma_f32_16x16x32_bf16 v[102:105], v[146:149], v[170:173], 0
	v_mfma_f32_16x16x32_bf16 v[98:101], v[154:157], v[170:173], 0
	v_mfma_f32_16x16x32_bf16 v[86:89], v[146:149], v[178:181], 0
	v_mfma_f32_16x16x32_bf16 v[82:85], v[154:157], v[178:181], 0
	v_mfma_f32_16x16x32_bf16 v[70:73], v[146:149], v[196:199], 0
	v_mfma_f32_16x16x32_bf16 v[66:69], v[154:157], v[196:199], 0
	v_mfma_f32_16x16x32_bf16 v[118:121], v[150:153], v[166:169], v[118:121]
	v_mfma_f32_16x16x32_bf16 v[114:117], v[158:161], v[166:169], v[114:117]
	v_mfma_f32_16x16x32_bf16 v[102:105], v[150:153], v[174:177], v[102:105]
	v_mfma_f32_16x16x32_bf16 v[98:101], v[158:161], v[174:177], v[98:101]
	v_mfma_f32_16x16x32_bf16 v[86:89], v[150:153], v[182:185], v[86:89]
	v_mfma_f32_16x16x32_bf16 v[82:85], v[158:161], v[182:185], v[82:85]
	v_mfma_f32_16x16x32_bf16 v[70:73], v[150:153], v[206:209], v[70:73]
	v_mfma_f32_16x16x32_bf16 v[66:69], v[158:161], v[206:209], v[66:69]
	s_setprio 0
	s_barrier
	s_add_i32 s90, s90, s47
	v_lshl_add_u64 v[210:211], s[34:35], 0, v[190:191]
	s_mov_b32 m0, s90
	ds_read_b128 v[162:165], v222 offset:16384
	ds_read_b128 v[166:169], v222 offset:17408
	ds_read_b128 v[170:173], v222 offset:18432
	ds_read_b128 v[174:177], v222 offset:19456
	ds_read_b128 v[178:181], v222 offset:20480
	ds_read_b128 v[182:185], v222 offset:21504
	ds_read_b128 v[196:199], v222 offset:22528
	ds_read_b128 v[206:209], v222 offset:23552
	global_load_lds_dwordx4 v[210:211], off
	s_add_i32 m0, s90, 0x2000
	s_add_u32 s90, s34, 0x80000
	v_lshl_add_u64 v[212:213], s[34:35], 0, v[200:201]
	s_addc_u32 s91, s35, 0
	s_add_i32 s96, s96, s47
	global_load_lds_dwordx4 v[212:213], off
	v_lshl_add_u64 v[214:215], s[90:91], 0, v[190:191]
	s_mov_b32 m0, s96
	v_lshl_add_u64 v[216:217], s[52:53], 0, v[188:189]
	global_load_lds_dwordx4 v[214:215], off
	v_lshl_add_u64 v[214:215], s[90:91], 0, v[200:201]
	s_add_i32 m0, s96, 0x2000
	s_nop 0
	global_load_lds_dwordx4 v[214:215], off
	v_lshl_add_u64 v[214:215], s[52:53], 0, v[186:187]
	s_mov_b32 m0, s55
	s_nop 0
	global_load_lds_dwordx4 v[214:215], off
	s_mov_b32 m0, s56
	s_nop 0
	global_load_lds_dwordx4 v[216:217], off
	s_waitcnt vmcnt(8)
	s_waitcnt lgkmcnt(0)
	s_barrier
	s_setprio 1
	s_waitcnt lgkmcnt(0)
	v_mfma_f32_16x16x32_bf16 v[62:65], v[130:133], v[162:165], 0
	v_mfma_f32_16x16x32_bf16 v[58:61], v[138:141], v[162:165], 0
	v_mfma_f32_16x16x32_bf16 v[46:49], v[130:133], v[170:173], 0
	v_mfma_f32_16x16x32_bf16 v[42:45], v[138:141], v[170:173], 0
	v_mfma_f32_16x16x32_bf16 v[30:33], v[130:133], v[178:181], 0
	v_mfma_f32_16x16x32_bf16 v[26:29], v[138:141], v[178:181], 0
	v_mfma_f32_16x16x32_bf16 v[14:17], v[130:133], v[196:199], 0
	v_mfma_f32_16x16x32_bf16 v[10:13], v[138:141], v[196:199], 0
	v_mfma_f32_16x16x32_bf16 v[62:65], v[134:137], v[166:169], v[62:65]
	v_mfma_f32_16x16x32_bf16 v[58:61], v[142:145], v[166:169], v[58:61]
	v_mfma_f32_16x16x32_bf16 v[46:49], v[134:137], v[174:177], v[46:49]
	v_mfma_f32_16x16x32_bf16 v[42:45], v[142:145], v[174:177], v[42:45]
	v_mfma_f32_16x16x32_bf16 v[30:33], v[134:137], v[182:185], v[30:33]
	v_mfma_f32_16x16x32_bf16 v[26:29], v[142:145], v[182:185], v[26:29]
	v_mfma_f32_16x16x32_bf16 v[14:17], v[134:137], v[206:209], v[14:17]
	v_mfma_f32_16x16x32_bf16 v[10:13], v[142:145], v[206:209], v[10:13]
	s_setprio 0
	s_setprio 1
	v_mfma_f32_16x16x32_bf16 v[54:57], v[146:149], v[162:165], 0
	v_mfma_f32_16x16x32_bf16 v[50:53], v[154:157], v[162:165], 0
	v_mfma_f32_16x16x32_bf16 v[38:41], v[146:149], v[170:173], 0
	v_mfma_f32_16x16x32_bf16 v[34:37], v[154:157], v[170:173], 0
	v_mfma_f32_16x16x32_bf16 v[22:25], v[146:149], v[178:181], 0
	v_mfma_f32_16x16x32_bf16 v[18:21], v[154:157], v[178:181], 0
	v_mfma_f32_16x16x32_bf16 v[6:9], v[146:149], v[196:199], 0
	v_mfma_f32_16x16x32_bf16 v[2:5], v[154:157], v[196:199], 0
	v_mfma_f32_16x16x32_bf16 v[54:57], v[150:153], v[166:169], v[54:57]
	v_mfma_f32_16x16x32_bf16 v[50:53], v[158:161], v[166:169], v[50:53]
	v_mfma_f32_16x16x32_bf16 v[38:41], v[150:153], v[174:177], v[38:41]
	v_mfma_f32_16x16x32_bf16 v[34:37], v[158:161], v[174:177], v[34:37]
	v_mfma_f32_16x16x32_bf16 v[22:25], v[150:153], v[182:185], v[22:25]
	v_mfma_f32_16x16x32_bf16 v[18:21], v[158:161], v[182:185], v[18:21]
	v_mfma_f32_16x16x32_bf16 v[6:9], v[150:153], v[206:209], v[6:9]
	v_mfma_f32_16x16x32_bf16 v[2:5], v[158:161], v[206:209], v[2:5]
	s_setprio 0
	s_barrier
	s_add_i32 s90, 0, 0x18000
	s_add_i32 s91, 0, 0x1c000
	v_add_u32_e32 v142, s90, v220
	v_add_u32_e32 v158, s91, v220
	ds_read_b128 v[130:133], v142
	ds_read_b128 v[134:137], v142 offset:1024
	ds_read_b128 v[138:141], v142 offset:2048
	ds_read_b128 v[142:145], v142 offset:3072
	ds_read_b128 v[146:149], v158
	ds_read_b128 v[150:153], v158 offset:1024
	ds_read_b128 v[154:157], v158 offset:2048
	ds_read_b128 v[158:161], v158 offset:3072
	s_add_u32 s52, s52, 0x80000
	s_addc_u32 s53, s53, 0
	s_mov_b32 m0, s57
	v_lshl_add_u64 v[218:219], s[52:53], 0, v[186:187]
	ds_read_b128 v[162:165], v222 offset:32768
	ds_read_b128 v[166:169], v222 offset:33792
	ds_read_b128 v[170:173], v222 offset:34816
	ds_read_b128 v[174:177], v222 offset:35840
	ds_read_b128 v[178:181], v222 offset:36864
	ds_read_b128 v[182:185], v222 offset:37888
	ds_read_b128 v[196:199], v222 offset:38912
	ds_read_b128 v[206:209], v222 offset:39936
	global_load_lds_dwordx4 v[218:219], off
	v_lshl_add_u64 v[218:219], s[52:53], 0, v[188:189]
	s_mov_b32 m0, s60
	s_nop 0
	global_load_lds_dwordx4 v[218:219], off
	s_waitcnt vmcnt(8)
	s_waitcnt lgkmcnt(0)
	s_barrier
	s_setprio 1
	s_waitcnt lgkmcnt(0)
	v_mfma_f32_16x16x32_bf16 v[126:129], v[130:133], v[162:165], v[126:129]
	v_mfma_f32_16x16x32_bf16 v[122:125], v[138:141], v[162:165], v[122:125]
	v_mfma_f32_16x16x32_bf16 v[110:113], v[130:133], v[170:173], v[110:113]
	v_mfma_f32_16x16x32_bf16 v[106:109], v[138:141], v[170:173], v[106:109]
	v_mfma_f32_16x16x32_bf16 v[94:97], v[130:133], v[178:181], v[94:97]
	v_mfma_f32_16x16x32_bf16 v[90:93], v[138:141], v[178:181], v[90:93]
	v_mfma_f32_16x16x32_bf16 v[78:81], v[130:133], v[196:199], v[78:81]
	v_mfma_f32_16x16x32_bf16 v[74:77], v[138:141], v[196:199], v[74:77]
	v_mfma_f32_16x16x32_bf16 v[126:129], v[134:137], v[166:169], v[126:129]
	v_mfma_f32_16x16x32_bf16 v[122:125], v[142:145], v[166:169], v[122:125]
	v_mfma_f32_16x16x32_bf16 v[110:113], v[134:137], v[174:177], v[110:113]
	v_mfma_f32_16x16x32_bf16 v[106:109], v[142:145], v[174:177], v[106:109]
	v_mfma_f32_16x16x32_bf16 v[94:97], v[134:137], v[182:185], v[94:97]
	v_mfma_f32_16x16x32_bf16 v[90:93], v[142:145], v[182:185], v[90:93]
	v_mfma_f32_16x16x32_bf16 v[78:81], v[134:137], v[206:209], v[78:81]
	v_mfma_f32_16x16x32_bf16 v[74:77], v[142:145], v[206:209], v[74:77]
	s_setprio 0
	s_setprio 1
	v_mfma_f32_16x16x32_bf16 v[118:121], v[146:149], v[162:165], v[118:121]
	v_mfma_f32_16x16x32_bf16 v[114:117], v[154:157], v[162:165], v[114:117]
	v_mfma_f32_16x16x32_bf16 v[102:105], v[146:149], v[170:173], v[102:105]
	v_mfma_f32_16x16x32_bf16 v[98:101], v[154:157], v[170:173], v[98:101]
	v_mfma_f32_16x16x32_bf16 v[86:89], v[146:149], v[178:181], v[86:89]
	v_mfma_f32_16x16x32_bf16 v[82:85], v[154:157], v[178:181], v[82:85]
	v_mfma_f32_16x16x32_bf16 v[70:73], v[146:149], v[196:199], v[70:73]
	v_mfma_f32_16x16x32_bf16 v[66:69], v[154:157], v[196:199], v[66:69]
	v_mfma_f32_16x16x32_bf16 v[118:121], v[150:153], v[166:169], v[118:121]
	v_mfma_f32_16x16x32_bf16 v[114:117], v[158:161], v[166:169], v[114:117]
	v_mfma_f32_16x16x32_bf16 v[102:105], v[150:153], v[174:177], v[102:105]
	v_mfma_f32_16x16x32_bf16 v[98:101], v[158:161], v[174:177], v[98:101]
	v_mfma_f32_16x16x32_bf16 v[86:89], v[150:153], v[182:185], v[86:89]
	v_mfma_f32_16x16x32_bf16 v[82:85], v[158:161], v[182:185], v[82:85]
	v_mfma_f32_16x16x32_bf16 v[70:73], v[150:153], v[206:209], v[70:73]
	v_mfma_f32_16x16x32_bf16 v[66:69], v[158:161], v[206:209], v[66:69]
	s_setprio 0
	s_barrier
	s_add_i32 s52, s90, s47
	v_lshl_add_u64 v[210:211], v[210:211], 0, s[58:59]
	s_mov_b32 m0, s52
	ds_read_b128 v[162:165], v222 offset:49152
	ds_read_b128 v[166:169], v222 offset:50176
	ds_read_b128 v[170:173], v222 offset:51200
	ds_read_b128 v[174:177], v222 offset:52224
	ds_read_b128 v[178:181], v222 offset:53248
	ds_read_b128 v[182:185], v222 offset:54272
	ds_read_b128 v[196:199], v222 offset:55296
	ds_read_b128 v[206:209], v222 offset:56320
	global_load_lds_dwordx4 v[210:211], off
	s_add_i32 m0, s52, 0x2000
	s_add_u32 s34, s34, 0x80080
	v_lshl_add_u64 v[210:211], v[212:213], 0, s[58:59]
	s_addc_u32 s35, s35, 0
	s_add_i32 s52, s91, s47
	global_load_lds_dwordx4 v[210:211], off
	v_lshl_add_u64 v[210:211], s[34:35], 0, v[190:191]
	s_mov_b32 m0, s52
	s_nop 0
	global_load_lds_dwordx4 v[210:211], off
	v_lshl_add_u64 v[210:211], s[34:35], 0, v[200:201]
	s_add_i32 m0, s52, 0x2000
	s_nop 0
	global_load_lds_dwordx4 v[210:211], off
	v_lshl_add_u64 v[210:211], v[214:215], 0, s[58:59]
	s_mov_b32 m0, s61
	s_nop 0
	global_load_lds_dwordx4 v[210:211], off
	v_lshl_add_u64 v[210:211], v[216:217], 0, s[58:59]
	s_mov_b32 m0, s69
	s_nop 0
	global_load_lds_dwordx4 v[210:211], off
	s_waitcnt vmcnt(8)
	s_waitcnt lgkmcnt(0)
	s_barrier
	s_setprio 1
	s_waitcnt lgkmcnt(0)
	v_mfma_f32_16x16x32_bf16 v[62:65], v[130:133], v[162:165], v[62:65]
	v_mfma_f32_16x16x32_bf16 v[58:61], v[138:141], v[162:165], v[58:61]
	v_mfma_f32_16x16x32_bf16 v[46:49], v[130:133], v[170:173], v[46:49]
	v_mfma_f32_16x16x32_bf16 v[42:45], v[138:141], v[170:173], v[42:45]
	v_mfma_f32_16x16x32_bf16 v[30:33], v[130:133], v[178:181], v[30:33]
	v_mfma_f32_16x16x32_bf16 v[26:29], v[138:141], v[178:181], v[26:29]
	v_mfma_f32_16x16x32_bf16 v[14:17], v[130:133], v[196:199], v[14:17]
	v_mfma_f32_16x16x32_bf16 v[10:13], v[138:141], v[196:199], v[10:13]
	v_mfma_f32_16x16x32_bf16 v[62:65], v[134:137], v[166:169], v[62:65]
	v_mfma_f32_16x16x32_bf16 v[58:61], v[142:145], v[166:169], v[58:61]
	v_mfma_f32_16x16x32_bf16 v[46:49], v[134:137], v[174:177], v[46:49]
	v_mfma_f32_16x16x32_bf16 v[42:45], v[142:145], v[174:177], v[42:45]
	v_mfma_f32_16x16x32_bf16 v[30:33], v[134:137], v[182:185], v[30:33]
	v_mfma_f32_16x16x32_bf16 v[26:29], v[142:145], v[182:185], v[26:29]
	v_mfma_f32_16x16x32_bf16 v[14:17], v[134:137], v[206:209], v[14:17]
	v_mfma_f32_16x16x32_bf16 v[10:13], v[142:145], v[206:209], v[10:13]
	s_setprio 0
	s_setprio 1
	v_mfma_f32_16x16x32_bf16 v[54:57], v[146:149], v[162:165], v[54:57]
	v_mfma_f32_16x16x32_bf16 v[50:53], v[154:157], v[162:165], v[50:53]
	v_mfma_f32_16x16x32_bf16 v[38:41], v[146:149], v[170:173], v[38:41]
	v_mfma_f32_16x16x32_bf16 v[34:37], v[154:157], v[170:173], v[34:37]
	v_mfma_f32_16x16x32_bf16 v[22:25], v[146:149], v[178:181], v[22:25]
	v_mfma_f32_16x16x32_bf16 v[18:21], v[154:157], v[178:181], v[18:21]
	v_mfma_f32_16x16x32_bf16 v[6:9], v[146:149], v[196:199], v[6:9]
	v_mfma_f32_16x16x32_bf16 v[2:5], v[154:157], v[196:199], v[2:5]
	v_mfma_f32_16x16x32_bf16 v[54:57], v[150:153], v[166:169], v[54:57]
	v_mfma_f32_16x16x32_bf16 v[50:53], v[158:161], v[166:169], v[50:53]
	v_mfma_f32_16x16x32_bf16 v[38:41], v[150:153], v[174:177], v[38:41]
	v_mfma_f32_16x16x32_bf16 v[34:37], v[158:161], v[174:177], v[34:37]
	v_mfma_f32_16x16x32_bf16 v[22:25], v[150:153], v[182:185], v[22:25]
	v_mfma_f32_16x16x32_bf16 v[18:21], v[158:161], v[182:185], v[18:21]
	v_mfma_f32_16x16x32_bf16 v[6:9], v[150:153], v[206:209], v[6:9]
	v_mfma_f32_16x16x32_bf16 v[2:5], v[158:161], v[206:209], v[2:5]
	s_setprio 0
	s_barrier
	s_add_i32 s89, s89, 2
	s_add_u32 s30, s30, 0x100
	s_addc_u32 s31, s31, 0
	s_add_u32 s81, s81, 0x100
	s_addc_u32 s88, s88, 0
	s_cmp_gt_u32 s89, 29
	s_cbranch_scc1 .Lpeel_done_5

.Lpeel_done_5:
	s_and_b64 vcc, exec, s[12:13]
	s_cbranch_vccz .LBB0_826
	s_barrier

.LBB0_937:
	s_ashr_i32 s23, s22, 31
	s_lshl_b64 s[4:5], s[22:23], 20
	s_add_u32 s4, s86, s4
	s_addc_u32 s5, s87, s5
	s_and_b64 s[26:27], s[24:25], exec
	s_cselect_b32 s11, s5, s29
	s_cselect_b32 s23, s4, s28
	s_ashr_i32 s21, s20, 31
	s_lshl_b64 s[26:27], s[20:21], 20
	v_readlane_b32 s0, v254, 38
	v_readlane_b32 s1, v254, 39
	s_add_u32 s26, s0, s26
	s_addc_u32 s27, s1, s27
	s_and_b64 s[34:35], s[24:25], exec
	s_cselect_b32 s21, s27, s31
	s_cselect_b32 s53, s26, s30
	s_add_u32 s28, s28, 0x80080
	s_addc_u32 s29, s29, 0
	s_add_u32 s55, s30, 0x100
	s_addc_u32 s56, s31, 0
	s_mov_b32 s57, -2
	v_readlane_b32 s60, v255, 49
	s_nop 3
	s_cmp_eq_u32 s60, 7
	v_writelane_b32 v255, 7, 49
	s_cbranch_scc0 .Ltrip0_strict_6
	s_add_u32 s30, s28, 0xfff80080
	s_addc_u32 s31, s29, -1
	s_add_i32 s60, 0, 0x10000
	s_cmp_eq_u32 s57, 28
	s_cselect_b32 s35, s11, s31
	s_cselect_b32 s34, s23, s30
	s_cselect_b32 s31, s21, s56
	s_cselect_b32 s30, s53, s55
	s_add_i32 s66, 0, 0x14000
	v_add_u32_e32 v154, s60, v139
	v_add_u32_e32 v170, s66, v139
	ds_read_b128 v[142:145], v154
	ds_read_b128 v[146:149], v154 offset:1024
	ds_read_b128 v[150:153], v154 offset:2048
	ds_read_b128 v[154:157], v154 offset:3072
	ds_read_b128 v[158:161], v170
	ds_read_b128 v[162:165], v170 offset:1024
	ds_read_b128 v[166:169], v170 offset:2048
	ds_read_b128 v[170:173], v170 offset:3072
	v_lshl_add_u64 v[186:187], s[28:29], 0, v[134:135]
	s_add_i32 m0, s13, 0xc000
	ds_read_b128 v[174:177], v141
	ds_read_b128 v[178:181], v141 offset:1024
	ds_read_b128 v[182:185], v141 offset:2048
	ds_read_b128 v[196:199], v141 offset:3072
	ds_read_b128 v[200:203], v141 offset:4096
	ds_read_b128 v[204:207], v141 offset:5120
	ds_read_b128 v[208:211], v141 offset:6144
	ds_read_b128 v[212:215], v141 offset:7168
	global_load_lds_dwordx4 v[186:187], off
	v_lshl_add_u64 v[186:187], s[28:29], 0, v[136:137]
	s_add_i32 m0, s13, 0xe000
	s_nop 0
	global_load_lds_dwordx4 v[186:187], off
	s_waitcnt vmcnt(24)
	s_waitcnt lgkmcnt(0)
	s_barrier
	s_setprio 1
	s_waitcnt lgkmcnt(0)
	v_mfma_f32_16x16x32_bf16 v[124:127], v[142:145], v[174:177], 0
	v_mfma_f32_16x16x32_bf16 v[120:123], v[150:153], v[174:177], 0
	v_mfma_f32_16x16x32_bf16 v[116:119], v[142:145], v[182:185], 0
	v_mfma_f32_16x16x32_bf16 v[112:115], v[150:153], v[182:185], 0
	v_mfma_f32_16x16x32_bf16 v[100:103], v[142:145], v[200:203], 0
	v_mfma_f32_16x16x32_bf16 v[96:99], v[150:153], v[200:203], 0
	v_mfma_f32_16x16x32_bf16 v[84:87], v[142:145], v[208:211], 0
	v_mfma_f32_16x16x32_bf16 v[80:83], v[150:153], v[208:211], 0
	v_mfma_f32_16x16x32_bf16 v[124:127], v[146:149], v[178:181], v[124:127]
	v_mfma_f32_16x16x32_bf16 v[120:123], v[154:157], v[178:181], v[120:123]
	v_mfma_f32_16x16x32_bf16 v[116:119], v[146:149], v[196:199], v[116:119]
	v_mfma_f32_16x16x32_bf16 v[112:115], v[154:157], v[196:199], v[112:115]
	v_mfma_f32_16x16x32_bf16 v[100:103], v[146:149], v[204:207], v[100:103]
	v_mfma_f32_16x16x32_bf16 v[96:99], v[154:157], v[204:207], v[96:99]
	v_mfma_f32_16x16x32_bf16 v[84:87], v[146:149], v[212:215], v[84:87]
	v_mfma_f32_16x16x32_bf16 v[80:83], v[154:157], v[212:215], v[80:83]
	s_setprio 0
	s_setprio 1
	v_mfma_f32_16x16x32_bf16 v[108:111], v[158:161], v[174:177], 0
	v_mfma_f32_16x16x32_bf16 v[104:107], v[166:169], v[174:177], 0
	v_mfma_f32_16x16x32_bf16 v[92:95], v[158:161], v[182:185], 0
	v_mfma_f32_16x16x32_bf16 v[88:91], v[166:169], v[182:185], 0
	v_mfma_f32_16x16x32_bf16 v[76:79], v[158:161], v[200:203], 0
	v_mfma_f32_16x16x32_bf16 v[72:75], v[166:169], v[200:203], 0
	v_mfma_f32_16x16x32_bf16 v[68:71], v[158:161], v[208:211], 0
	v_mfma_f32_16x16x32_bf16 v[64:67], v[166:169], v[208:211], 0
	v_mfma_f32_16x16x32_bf16 v[108:111], v[162:165], v[178:181], v[108:111]
	v_mfma_f32_16x16x32_bf16 v[104:107], v[170:173], v[178:181], v[104:107]
	v_mfma_f32_16x16x32_bf16 v[92:95], v[162:165], v[196:199], v[92:95]
	v_mfma_f32_16x16x32_bf16 v[88:91], v[170:173], v[196:199], v[88:91]
	v_mfma_f32_16x16x32_bf16 v[76:79], v[162:165], v[204:207], v[76:79]
	v_mfma_f32_16x16x32_bf16 v[72:75], v[170:173], v[204:207], v[72:75]
	v_mfma_f32_16x16x32_bf16 v[68:71], v[162:165], v[212:215], v[68:71]
	v_mfma_f32_16x16x32_bf16 v[64:67], v[170:173], v[212:215], v[64:67]
	s_setprio 0
	s_barrier
	s_add_i32 s60, s60, s38
	v_lshl_add_u64 v[186:187], s[30:31], 0, v[190:191]
	s_mov_b32 m0, s60
	ds_read_b128 v[174:177], v141 offset:16384
	ds_read_b128 v[178:181], v141 offset:17408
	ds_read_b128 v[182:185], v141 offset:18432
	ds_read_b128 v[196:199], v141 offset:19456
	ds_read_b128 v[200:203], v141 offset:20480
	ds_read_b128 v[204:207], v141 offset:21504
	ds_read_b128 v[208:211], v141 offset:22528
	ds_read_b128 v[212:215], v141 offset:23552
	global_load_lds_dwordx4 v[186:187], off
	s_add_i32 m0, s60, 0x2000
	s_add_u32 s60, s30, 0x80000
	v_lshl_add_u64 v[216:217], s[30:31], 0, v[132:133]
	s_addc_u32 s61, s31, 0
	s_add_i32 s66, s66, s38
	global_load_lds_dwordx4 v[216:217], off
	v_lshl_add_u64 v[218:219], s[60:61], 0, v[190:191]
	s_mov_b32 m0, s66
	v_lshl_add_u64 v[220:221], s[34:35], 0, v[130:131]
	global_load_lds_dwordx4 v[218:219], off
	v_lshl_add_u64 v[218:219], s[60:61], 0, v[132:133]
	s_add_i32 m0, s66, 0x2000
	s_nop 0
	global_load_lds_dwordx4 v[218:219], off
	v_lshl_add_u64 v[218:219], s[34:35], 0, v[128:129]
	s_mov_b32 m0, s13
	s_nop 0
	global_load_lds_dwordx4 v[218:219], off
	s_mov_b32 m0, s39
	s_nop 0
	global_load_lds_dwordx4 v[220:221], off
	s_waitcnt vmcnt(24)
	s_waitcnt lgkmcnt(0)
	s_barrier
	s_setprio 1
	s_waitcnt lgkmcnt(0)
	v_mfma_f32_16x16x32_bf16 v[60:63], v[142:145], v[174:177], 0
	v_mfma_f32_16x16x32_bf16 v[56:59], v[150:153], v[174:177], 0
	v_mfma_f32_16x16x32_bf16 v[52:55], v[142:145], v[182:185], 0
	v_mfma_f32_16x16x32_bf16 v[48:51], v[150:153], v[182:185], 0
	v_mfma_f32_16x16x32_bf16 v[36:39], v[142:145], v[200:203], 0
	v_mfma_f32_16x16x32_bf16 v[32:35], v[150:153], v[200:203], 0
	v_mfma_f32_16x16x32_bf16 v[20:23], v[142:145], v[208:211], 0
	v_mfma_f32_16x16x32_bf16 v[16:19], v[150:153], v[208:211], 0
	v_mfma_f32_16x16x32_bf16 v[60:63], v[146:149], v[178:181], v[60:63]
	v_mfma_f32_16x16x32_bf16 v[56:59], v[154:157], v[178:181], v[56:59]
	v_mfma_f32_16x16x32_bf16 v[52:55], v[146:149], v[196:199], v[52:55]
	v_mfma_f32_16x16x32_bf16 v[48:51], v[154:157], v[196:199], v[48:51]
	v_mfma_f32_16x16x32_bf16 v[36:39], v[146:149], v[204:207], v[36:39]
	v_mfma_f32_16x16x32_bf16 v[32:35], v[154:157], v[204:207], v[32:35]
	v_mfma_f32_16x16x32_bf16 v[20:23], v[146:149], v[212:215], v[20:23]
	v_mfma_f32_16x16x32_bf16 v[16:19], v[154:157], v[212:215], v[16:19]
	s_setprio 0
	s_setprio 1
	v_mfma_f32_16x16x32_bf16 v[44:47], v[158:161], v[174:177], 0
	v_mfma_f32_16x16x32_bf16 v[40:43], v[166:169], v[174:177], 0
	v_mfma_f32_16x16x32_bf16 v[28:31], v[158:161], v[182:185], 0
	v_mfma_f32_16x16x32_bf16 v[24:27], v[166:169], v[182:185], 0
	v_mfma_f32_16x16x32_bf16 v[12:15], v[158:161], v[200:203], 0
	v_mfma_f32_16x16x32_bf16 v[8:11], v[166:169], v[200:203], 0
	v_mfma_f32_16x16x32_bf16 v[4:7], v[158:161], v[208:211], 0
	v_mfma_f32_16x16x32_bf16 v[0:3], v[166:169], v[208:211], 0
	v_mfma_f32_16x16x32_bf16 v[44:47], v[162:165], v[178:181], v[44:47]
	v_mfma_f32_16x16x32_bf16 v[40:43], v[170:173], v[178:181], v[40:43]
	v_mfma_f32_16x16x32_bf16 v[28:31], v[162:165], v[196:199], v[28:31]
	v_mfma_f32_16x16x32_bf16 v[24:27], v[170:173], v[196:199], v[24:27]
	v_mfma_f32_16x16x32_bf16 v[12:15], v[162:165], v[204:207], v[12:15]
	v_mfma_f32_16x16x32_bf16 v[8:11], v[170:173], v[204:207], v[8:11]
	v_mfma_f32_16x16x32_bf16 v[4:7], v[162:165], v[212:215], v[4:7]
	v_mfma_f32_16x16x32_bf16 v[0:3], v[170:173], v[212:215], v[0:3]
	s_setprio 0
	s_barrier
	s_add_i32 s60, 0, 0x18000
	s_add_i32 s61, 0, 0x1c000
	v_add_u32_e32 v154, s60, v139
	v_add_u32_e32 v170, s61, v139
	ds_read_b128 v[142:145], v154
	ds_read_b128 v[146:149], v154 offset:1024
	ds_read_b128 v[150:153], v154 offset:2048
	ds_read_b128 v[154:157], v154 offset:3072
	ds_read_b128 v[158:161], v170
	ds_read_b128 v[162:165], v170 offset:1024
	ds_read_b128 v[166:169], v170 offset:2048
	ds_read_b128 v[170:173], v170 offset:3072
	s_add_u32 s34, s34, 0x80000
	s_addc_u32 s35, s35, 0
	s_mov_b32 m0, s41
	v_lshl_add_u64 v[222:223], s[34:35], 0, v[128:129]
	ds_read_b128 v[174:177], v141 offset:32768
	ds_read_b128 v[178:181], v141 offset:33792
	ds_read_b128 v[182:185], v141 offset:34816
	ds_read_b128 v[196:199], v141 offset:35840
	ds_read_b128 v[200:203], v141 offset:36864
	ds_read_b128 v[204:207], v141 offset:37888
	ds_read_b128 v[208:211], v141 offset:38912
	ds_read_b128 v[212:215], v141 offset:39936
	global_load_lds_dwordx4 v[222:223], off
	v_lshl_add_u64 v[222:223], s[34:35], 0, v[130:131]
	s_mov_b32 m0, s42
	s_nop 0
	global_load_lds_dwordx4 v[222:223], off
	s_waitcnt vmcnt(8)
	s_waitcnt lgkmcnt(0)
	s_barrier
	s_setprio 1
	s_waitcnt lgkmcnt(0)
	v_mfma_f32_16x16x32_bf16 v[124:127], v[142:145], v[174:177], v[124:127]
	v_mfma_f32_16x16x32_bf16 v[120:123], v[150:153], v[174:177], v[120:123]
	v_mfma_f32_16x16x32_bf16 v[116:119], v[142:145], v[182:185], v[116:119]
	v_mfma_f32_16x16x32_bf16 v[112:115], v[150:153], v[182:185], v[112:115]
	v_mfma_f32_16x16x32_bf16 v[100:103], v[142:145], v[200:203], v[100:103]
	v_mfma_f32_16x16x32_bf16 v[96:99], v[150:153], v[200:203], v[96:99]
	v_mfma_f32_16x16x32_bf16 v[84:87], v[142:145], v[208:211], v[84:87]
	v_mfma_f32_16x16x32_bf16 v[80:83], v[150:153], v[208:211], v[80:83]
	v_mfma_f32_16x16x32_bf16 v[124:127], v[146:149], v[178:181], v[124:127]
	v_mfma_f32_16x16x32_bf16 v[120:123], v[154:157], v[178:181], v[120:123]
	v_mfma_f32_16x16x32_bf16 v[116:119], v[146:149], v[196:199], v[116:119]
	v_mfma_f32_16x16x32_bf16 v[112:115], v[154:157], v[196:199], v[112:115]
	v_mfma_f32_16x16x32_bf16 v[100:103], v[146:149], v[204:207], v[100:103]
	v_mfma_f32_16x16x32_bf16 v[96:99], v[154:157], v[204:207], v[96:99]
	v_mfma_f32_16x16x32_bf16 v[84:87], v[146:149], v[212:215], v[84:87]
	v_mfma_f32_16x16x32_bf16 v[80:83], v[154:157], v[212:215], v[80:83]
	s_setprio 0
	s_setprio 1
	v_mfma_f32_16x16x32_bf16 v[108:111], v[158:161], v[174:177], v[108:111]
	v_mfma_f32_16x16x32_bf16 v[104:107], v[166:169], v[174:177], v[104:107]
	v_mfma_f32_16x16x32_bf16 v[92:95], v[158:161], v[182:185], v[92:95]
	v_mfma_f32_16x16x32_bf16 v[88:91], v[166:169], v[182:185], v[88:91]
	v_mfma_f32_16x16x32_bf16 v[76:79], v[158:161], v[200:203], v[76:79]
	v_mfma_f32_16x16x32_bf16 v[72:75], v[166:169], v[200:203], v[72:75]
	v_mfma_f32_16x16x32_bf16 v[68:71], v[158:161], v[208:211], v[68:71]
	v_mfma_f32_16x16x32_bf16 v[64:67], v[166:169], v[208:211], v[64:67]
	v_mfma_f32_16x16x32_bf16 v[108:111], v[162:165], v[178:181], v[108:111]
	v_mfma_f32_16x16x32_bf16 v[104:107], v[170:173], v[178:181], v[104:107]
	v_mfma_f32_16x16x32_bf16 v[92:95], v[162:165], v[196:199], v[92:95]
	v_mfma_f32_16x16x32_bf16 v[88:91], v[170:173], v[196:199], v[88:91]
	v_mfma_f32_16x16x32_bf16 v[76:79], v[162:165], v[204:207], v[76:79]
	v_mfma_f32_16x16x32_bf16 v[72:75], v[170:173], v[204:207], v[72:75]
	v_mfma_f32_16x16x32_bf16 v[68:71], v[162:165], v[212:215], v[68:71]
	v_mfma_f32_16x16x32_bf16 v[64:67], v[170:173], v[212:215], v[64:67]
	s_setprio 0
	s_barrier
	s_add_i32 s34, s60, s38
	v_lshl_add_u64 v[186:187], v[186:187], 0, s[58:59]
	s_mov_b32 m0, s34
	ds_read_b128 v[174:177], v141 offset:49152
	ds_read_b128 v[178:181], v141 offset:50176
	ds_read_b128 v[182:185], v141 offset:51200
	ds_read_b128 v[196:199], v141 offset:52224
	ds_read_b128 v[200:203], v141 offset:53248
	ds_read_b128 v[204:207], v141 offset:54272
	ds_read_b128 v[208:211], v141 offset:55296
	ds_read_b128 v[212:215], v141 offset:56320
	global_load_lds_dwordx4 v[186:187], off
	s_add_i32 m0, s34, 0x2000
	s_add_u32 s30, s30, 0x80080
	v_lshl_add_u64 v[186:187], v[216:217], 0, s[58:59]
	s_addc_u32 s31, s31, 0
	s_add_i32 s34, s61, s38
	global_load_lds_dwordx4 v[186:187], off
	v_lshl_add_u64 v[186:187], s[30:31], 0, v[190:191]
	s_mov_b32 m0, s34
	s_nop 0
	global_load_lds_dwordx4 v[186:187], off
	v_lshl_add_u64 v[186:187], s[30:31], 0, v[132:133]
	s_add_i32 m0, s34, 0x2000
	s_nop 0
	global_load_lds_dwordx4 v[186:187], off
	v_lshl_add_u64 v[186:187], v[218:219], 0, s[58:59]
	s_mov_b32 m0, s43
	s_nop 0
	global_load_lds_dwordx4 v[186:187], off
	v_lshl_add_u64 v[186:187], v[220:221], 0, s[58:59]
	s_mov_b32 m0, s47
	s_nop 0
	global_load_lds_dwordx4 v[186:187], off
	s_waitcnt vmcnt(8)
	s_waitcnt lgkmcnt(0)
	s_barrier
	s_setprio 1
	s_waitcnt lgkmcnt(0)
	v_mfma_f32_16x16x32_bf16 v[60:63], v[142:145], v[174:177], v[60:63]
	v_mfma_f32_16x16x32_bf16 v[56:59], v[150:153], v[174:177], v[56:59]
	v_mfma_f32_16x16x32_bf16 v[52:55], v[142:145], v[182:185], v[52:55]
	v_mfma_f32_16x16x32_bf16 v[48:51], v[150:153], v[182:185], v[48:51]
	v_mfma_f32_16x16x32_bf16 v[36:39], v[142:145], v[200:203], v[36:39]
	v_mfma_f32_16x16x32_bf16 v[32:35], v[150:153], v[200:203], v[32:35]
	v_mfma_f32_16x16x32_bf16 v[20:23], v[142:145], v[208:211], v[20:23]
	v_mfma_f32_16x16x32_bf16 v[16:19], v[150:153], v[208:211], v[16:19]
	v_mfma_f32_16x16x32_bf16 v[60:63], v[146:149], v[178:181], v[60:63]
	v_mfma_f32_16x16x32_bf16 v[56:59], v[154:157], v[178:181], v[56:59]
	v_mfma_f32_16x16x32_bf16 v[52:55], v[146:149], v[196:199], v[52:55]
	v_mfma_f32_16x16x32_bf16 v[48:51], v[154:157], v[196:199], v[48:51]
	v_mfma_f32_16x16x32_bf16 v[36:39], v[146:149], v[204:207], v[36:39]
	v_mfma_f32_16x16x32_bf16 v[32:35], v[154:157], v[204:207], v[32:35]
	v_mfma_f32_16x16x32_bf16 v[20:23], v[146:149], v[212:215], v[20:23]
	v_mfma_f32_16x16x32_bf16 v[16:19], v[154:157], v[212:215], v[16:19]
	s_setprio 0
	s_setprio 1
	v_mfma_f32_16x16x32_bf16 v[44:47], v[158:161], v[174:177], v[44:47]
	v_mfma_f32_16x16x32_bf16 v[40:43], v[166:169], v[174:177], v[40:43]
	v_mfma_f32_16x16x32_bf16 v[28:31], v[158:161], v[182:185], v[28:31]
	v_mfma_f32_16x16x32_bf16 v[24:27], v[166:169], v[182:185], v[24:27]
	v_mfma_f32_16x16x32_bf16 v[12:15], v[158:161], v[200:203], v[12:15]
	v_mfma_f32_16x16x32_bf16 v[8:11], v[166:169], v[200:203], v[8:11]
	v_mfma_f32_16x16x32_bf16 v[4:7], v[158:161], v[208:211], v[4:7]
	v_mfma_f32_16x16x32_bf16 v[0:3], v[166:169], v[208:211], v[0:3]
	v_mfma_f32_16x16x32_bf16 v[44:47], v[162:165], v[178:181], v[44:47]
	v_mfma_f32_16x16x32_bf16 v[40:43], v[170:173], v[178:181], v[40:43]
	v_mfma_f32_16x16x32_bf16 v[28:31], v[162:165], v[196:199], v[28:31]
	v_mfma_f32_16x16x32_bf16 v[24:27], v[170:173], v[196:199], v[24:27]
	v_mfma_f32_16x16x32_bf16 v[12:15], v[162:165], v[204:207], v[12:15]
	v_mfma_f32_16x16x32_bf16 v[8:11], v[170:173], v[204:207], v[8:11]
	v_mfma_f32_16x16x32_bf16 v[4:7], v[162:165], v[212:215], v[4:7]
	v_mfma_f32_16x16x32_bf16 v[0:3], v[170:173], v[212:215], v[0:3]
	s_setprio 0
	s_barrier
	s_add_i32 s57, s57, 2
	s_add_u32 s28, s28, 0x100
	s_addc_u32 s29, s29, 0
	s_add_u32 s55, s55, 0x100
	s_addc_u32 s56, s56, 0
	s_cmp_gt_u32 s57, 29
	s_cbranch_scc1 .Lpeel_done_6
	s_branch .LBB0_938
.Ltrip0_strict_6:
	s_add_u32 s30, s28, 0xfff80080
	s_addc_u32 s31, s29, -1
	s_add_i32 s60, 0, 0x10000
	s_cmp_eq_u32 s57, 28
	s_cselect_b32 s35, s11, s31
	s_cselect_b32 s34, s23, s30
	s_cselect_b32 s31, s21, s56
	s_cselect_b32 s30, s53, s55
	s_add_i32 s66, 0, 0x14000
	v_add_u32_e32 v154, s60, v139
	v_add_u32_e32 v170, s66, v139
	ds_read_b128 v[142:145], v154
	ds_read_b128 v[146:149], v154 offset:1024
	ds_read_b128 v[150:153], v154 offset:2048
	ds_read_b128 v[154:157], v154 offset:3072
	ds_read_b128 v[158:161], v170
	ds_read_b128 v[162:165], v170 offset:1024
	ds_read_b128 v[166:169], v170 offset:2048
	ds_read_b128 v[170:173], v170 offset:3072
	v_lshl_add_u64 v[186:187], s[28:29], 0, v[134:135]
	s_add_i32 m0, s13, 0xc000
	ds_read_b128 v[174:177], v141
	ds_read_b128 v[178:181], v141 offset:1024
	ds_read_b128 v[182:185], v141 offset:2048
	ds_read_b128 v[196:199], v141 offset:3072
	ds_read_b128 v[200:203], v141 offset:4096
	ds_read_b128 v[204:207], v141 offset:5120
	ds_read_b128 v[208:211], v141 offset:6144
	ds_read_b128 v[212:215], v141 offset:7168
	global_load_lds_dwordx4 v[186:187], off
	v_lshl_add_u64 v[186:187], s[28:29], 0, v[136:137]
	s_add_i32 m0, s13, 0xe000
	s_nop 0
	global_load_lds_dwordx4 v[186:187], off
	s_waitcnt vmcnt(8)
	s_waitcnt lgkmcnt(0)
	s_barrier
	s_setprio 1
	s_waitcnt lgkmcnt(0)
	v_mfma_f32_16x16x32_bf16 v[124:127], v[142:145], v[174:177], 0
	v_mfma_f32_16x16x32_bf16 v[120:123], v[150:153], v[174:177], 0
	v_mfma_f32_16x16x32_bf16 v[116:119], v[142:145], v[182:185], 0
	v_mfma_f32_16x16x32_bf16 v[112:115], v[150:153], v[182:185], 0
	v_mfma_f32_16x16x32_bf16 v[100:103], v[142:145], v[200:203], 0
	v_mfma_f32_16x16x32_bf16 v[96:99], v[150:153], v[200:203], 0
	v_mfma_f32_16x16x32_bf16 v[84:87], v[142:145], v[208:211], 0
	v_mfma_f32_16x16x32_bf16 v[80:83], v[150:153], v[208:211], 0
	v_mfma_f32_16x16x32_bf16 v[124:127], v[146:149], v[178:181], v[124:127]
	v_mfma_f32_16x16x32_bf16 v[120:123], v[154:157], v[178:181], v[120:123]
	v_mfma_f32_16x16x32_bf16 v[116:119], v[146:149], v[196:199], v[116:119]
	v_mfma_f32_16x16x32_bf16 v[112:115], v[154:157], v[196:199], v[112:115]
	v_mfma_f32_16x16x32_bf16 v[100:103], v[146:149], v[204:207], v[100:103]
	v_mfma_f32_16x16x32_bf16 v[96:99], v[154:157], v[204:207], v[96:99]
	v_mfma_f32_16x16x32_bf16 v[84:87], v[146:149], v[212:215], v[84:87]
	v_mfma_f32_16x16x32_bf16 v[80:83], v[154:157], v[212:215], v[80:83]
	s_setprio 0
	s_setprio 1
	v_mfma_f32_16x16x32_bf16 v[108:111], v[158:161], v[174:177], 0
	v_mfma_f32_16x16x32_bf16 v[104:107], v[166:169], v[174:177], 0
	v_mfma_f32_16x16x32_bf16 v[92:95], v[158:161], v[182:185], 0
	v_mfma_f32_16x16x32_bf16 v[88:91], v[166:169], v[182:185], 0
	v_mfma_f32_16x16x32_bf16 v[76:79], v[158:161], v[200:203], 0
	v_mfma_f32_16x16x32_bf16 v[72:75], v[166:169], v[200:203], 0
	v_mfma_f32_16x16x32_bf16 v[68:71], v[158:161], v[208:211], 0
	v_mfma_f32_16x16x32_bf16 v[64:67], v[166:169], v[208:211], 0
	v_mfma_f32_16x16x32_bf16 v[108:111], v[162:165], v[178:181], v[108:111]
	v_mfma_f32_16x16x32_bf16 v[104:107], v[170:173], v[178:181], v[104:107]
	v_mfma_f32_16x16x32_bf16 v[92:95], v[162:165], v[196:199], v[92:95]
	v_mfma_f32_16x16x32_bf16 v[88:91], v[170:173], v[196:199], v[88:91]
	v_mfma_f32_16x16x32_bf16 v[76:79], v[162:165], v[204:207], v[76:79]
	v_mfma_f32_16x16x32_bf16 v[72:75], v[170:173], v[204:207], v[72:75]
	v_mfma_f32_16x16x32_bf16 v[68:71], v[162:165], v[212:215], v[68:71]
	v_mfma_f32_16x16x32_bf16 v[64:67], v[170:173], v[212:215], v[64:67]
	s_setprio 0
	s_barrier
	s_add_i32 s60, s60, s38
	v_lshl_add_u64 v[186:187], s[30:31], 0, v[190:191]
	s_mov_b32 m0, s60
	ds_read_b128 v[174:177], v141 offset:16384
	ds_read_b128 v[178:181], v141 offset:17408
	ds_read_b128 v[182:185], v141 offset:18432
	ds_read_b128 v[196:199], v141 offset:19456
	ds_read_b128 v[200:203], v141 offset:20480
	ds_read_b128 v[204:207], v141 offset:21504
	ds_read_b128 v[208:211], v141 offset:22528
	ds_read_b128 v[212:215], v141 offset:23552
	global_load_lds_dwordx4 v[186:187], off
	s_add_i32 m0, s60, 0x2000
	s_add_u32 s60, s30, 0x80000
	v_lshl_add_u64 v[216:217], s[30:31], 0, v[132:133]
	s_addc_u32 s61, s31, 0
	s_add_i32 s66, s66, s38
	global_load_lds_dwordx4 v[216:217], off
	v_lshl_add_u64 v[218:219], s[60:61], 0, v[190:191]
	s_mov_b32 m0, s66
	v_lshl_add_u64 v[220:221], s[34:35], 0, v[130:131]
	global_load_lds_dwordx4 v[218:219], off
	v_lshl_add_u64 v[218:219], s[60:61], 0, v[132:133]
	s_add_i32 m0, s66, 0x2000
	s_nop 0
	global_load_lds_dwordx4 v[218:219], off
	v_lshl_add_u64 v[218:219], s[34:35], 0, v[128:129]
	s_mov_b32 m0, s13
	s_nop 0
	global_load_lds_dwordx4 v[218:219], off
	s_mov_b32 m0, s39
	s_nop 0
	global_load_lds_dwordx4 v[220:221], off
	s_waitcnt vmcnt(8)
	s_waitcnt lgkmcnt(0)
	s_barrier
	s_setprio 1
	s_waitcnt lgkmcnt(0)
	v_mfma_f32_16x16x32_bf16 v[60:63], v[142:145], v[174:177], 0
	v_mfma_f32_16x16x32_bf16 v[56:59], v[150:153], v[174:177], 0
	v_mfma_f32_16x16x32_bf16 v[52:55], v[142:145], v[182:185], 0
	v_mfma_f32_16x16x32_bf16 v[48:51], v[150:153], v[182:185], 0
	v_mfma_f32_16x16x32_bf16 v[36:39], v[142:145], v[200:203], 0
	v_mfma_f32_16x16x32_bf16 v[32:35], v[150:153], v[200:203], 0
	v_mfma_f32_16x16x32_bf16 v[20:23], v[142:145], v[208:211], 0
	v_mfma_f32_16x16x32_bf16 v[16:19], v[150:153], v[208:211], 0
	v_mfma_f32_16x16x32_bf16 v[60:63], v[146:149], v[178:181], v[60:63]
	v_mfma_f32_16x16x32_bf16 v[56:59], v[154:157], v[178:181], v[56:59]
	v_mfma_f32_16x16x32_bf16 v[52:55], v[146:149], v[196:199], v[52:55]
	v_mfma_f32_16x16x32_bf16 v[48:51], v[154:157], v[196:199], v[48:51]
	v_mfma_f32_16x16x32_bf16 v[36:39], v[146:149], v[204:207], v[36:39]
	v_mfma_f32_16x16x32_bf16 v[32:35], v[154:157], v[204:207], v[32:35]
	v_mfma_f32_16x16x32_bf16 v[20:23], v[146:149], v[212:215], v[20:23]
	v_mfma_f32_16x16x32_bf16 v[16:19], v[154:157], v[212:215], v[16:19]
	s_setprio 0
	s_setprio 1
	v_mfma_f32_16x16x32_bf16 v[44:47], v[158:161], v[174:177], 0
	v_mfma_f32_16x16x32_bf16 v[40:43], v[166:169], v[174:177], 0
	v_mfma_f32_16x16x32_bf16 v[28:31], v[158:161], v[182:185], 0
	v_mfma_f32_16x16x32_bf16 v[24:27], v[166:169], v[182:185], 0
	v_mfma_f32_16x16x32_bf16 v[12:15], v[158:161], v[200:203], 0
	v_mfma_f32_16x16x32_bf16 v[8:11], v[166:169], v[200:203], 0
	v_mfma_f32_16x16x32_bf16 v[4:7], v[158:161], v[208:211], 0
	v_mfma_f32_16x16x32_bf16 v[0:3], v[166:169], v[208:211], 0
	v_mfma_f32_16x16x32_bf16 v[44:47], v[162:165], v[178:181], v[44:47]
	v_mfma_f32_16x16x32_bf16 v[40:43], v[170:173], v[178:181], v[40:43]
	v_mfma_f32_16x16x32_bf16 v[28:31], v[162:165], v[196:199], v[28:31]
	v_mfma_f32_16x16x32_bf16 v[24:27], v[170:173], v[196:199], v[24:27]
	v_mfma_f32_16x16x32_bf16 v[12:15], v[162:165], v[204:207], v[12:15]
	v_mfma_f32_16x16x32_bf16 v[8:11], v[170:173], v[204:207], v[8:11]
	v_mfma_f32_16x16x32_bf16 v[4:7], v[162:165], v[212:215], v[4:7]
	v_mfma_f32_16x16x32_bf16 v[0:3], v[170:173], v[212:215], v[0:3]
	s_setprio 0
	s_barrier
	s_add_i32 s60, 0, 0x18000
	s_add_i32 s61, 0, 0x1c000
	v_add_u32_e32 v154, s60, v139
	v_add_u32_e32 v170, s61, v139
	ds_read_b128 v[142:145], v154
	ds_read_b128 v[146:149], v154 offset:1024
	ds_read_b128 v[150:153], v154 offset:2048
	ds_read_b128 v[154:157], v154 offset:3072
	ds_read_b128 v[158:161], v170
	ds_read_b128 v[162:165], v170 offset:1024
	ds_read_b128 v[166:169], v170 offset:2048
	ds_read_b128 v[170:173], v170 offset:3072
	s_add_u32 s34, s34, 0x80000
	s_addc_u32 s35, s35, 0
	s_mov_b32 m0, s41
	v_lshl_add_u64 v[222:223], s[34:35], 0, v[128:129]
	ds_read_b128 v[174:177], v141 offset:32768
	ds_read_b128 v[178:181], v141 offset:33792
	ds_read_b128 v[182:185], v141 offset:34816
	ds_read_b128 v[196:199], v141 offset:35840
	ds_read_b128 v[200:203], v141 offset:36864
	ds_read_b128 v[204:207], v141 offset:37888
	ds_read_b128 v[208:211], v141 offset:38912
	ds_read_b128 v[212:215], v141 offset:39936
	global_load_lds_dwordx4 v[222:223], off
	v_lshl_add_u64 v[222:223], s[34:35], 0, v[130:131]
	s_mov_b32 m0, s42
	s_nop 0
	global_load_lds_dwordx4 v[222:223], off
	s_waitcnt vmcnt(8)
	s_waitcnt lgkmcnt(0)
	s_barrier
	s_setprio 1
	s_waitcnt lgkmcnt(0)
	v_mfma_f32_16x16x32_bf16 v[124:127], v[142:145], v[174:177], v[124:127]
	v_mfma_f32_16x16x32_bf16 v[120:123], v[150:153], v[174:177], v[120:123]
	v_mfma_f32_16x16x32_bf16 v[116:119], v[142:145], v[182:185], v[116:119]
	v_mfma_f32_16x16x32_bf16 v[112:115], v[150:153], v[182:185], v[112:115]
	v_mfma_f32_16x16x32_bf16 v[100:103], v[142:145], v[200:203], v[100:103]
	v_mfma_f32_16x16x32_bf16 v[96:99], v[150:153], v[200:203], v[96:99]
	v_mfma_f32_16x16x32_bf16 v[84:87], v[142:145], v[208:211], v[84:87]
	v_mfma_f32_16x16x32_bf16 v[80:83], v[150:153], v[208:211], v[80:83]
	v_mfma_f32_16x16x32_bf16 v[124:127], v[146:149], v[178:181], v[124:127]
	v_mfma_f32_16x16x32_bf16 v[120:123], v[154:157], v[178:181], v[120:123]
	v_mfma_f32_16x16x32_bf16 v[116:119], v[146:149], v[196:199], v[116:119]
	v_mfma_f32_16x16x32_bf16 v[112:115], v[154:157], v[196:199], v[112:115]
	v_mfma_f32_16x16x32_bf16 v[100:103], v[146:149], v[204:207], v[100:103]
	v_mfma_f32_16x16x32_bf16 v[96:99], v[154:157], v[204:207], v[96:99]
	v_mfma_f32_16x16x32_bf16 v[84:87], v[146:149], v[212:215], v[84:87]
	v_mfma_f32_16x16x32_bf16 v[80:83], v[154:157], v[212:215], v[80:83]
	s_setprio 0
	s_setprio 1
	v_mfma_f32_16x16x32_bf16 v[108:111], v[158:161], v[174:177], v[108:111]
	v_mfma_f32_16x16x32_bf16 v[104:107], v[166:169], v[174:177], v[104:107]
	v_mfma_f32_16x16x32_bf16 v[92:95], v[158:161], v[182:185], v[92:95]
	v_mfma_f32_16x16x32_bf16 v[88:91], v[166:169], v[182:185], v[88:91]
	v_mfma_f32_16x16x32_bf16 v[76:79], v[158:161], v[200:203], v[76:79]
	v_mfma_f32_16x16x32_bf16 v[72:75], v[166:169], v[200:203], v[72:75]
	v_mfma_f32_16x16x32_bf16 v[68:71], v[158:161], v[208:211], v[68:71]
	v_mfma_f32_16x16x32_bf16 v[64:67], v[166:169], v[208:211], v[64:67]
	v_mfma_f32_16x16x32_bf16 v[108:111], v[162:165], v[178:181], v[108:111]
	v_mfma_f32_16x16x32_bf16 v[104:107], v[170:173], v[178:181], v[104:107]
	v_mfma_f32_16x16x32_bf16 v[92:95], v[162:165], v[196:199], v[92:95]
	v_mfma_f32_16x16x32_bf16 v[88:91], v[170:173], v[196:199], v[88:91]
	v_mfma_f32_16x16x32_bf16 v[76:79], v[162:165], v[204:207], v[76:79]
	v_mfma_f32_16x16x32_bf16 v[72:75], v[170:173], v[204:207], v[72:75]
	v_mfma_f32_16x16x32_bf16 v[68:71], v[162:165], v[212:215], v[68:71]
	v_mfma_f32_16x16x32_bf16 v[64:67], v[170:173], v[212:215], v[64:67]
	s_setprio 0
	s_barrier
	s_add_i32 s34, s60, s38
	v_lshl_add_u64 v[186:187], v[186:187], 0, s[58:59]
	s_mov_b32 m0, s34
	ds_read_b128 v[174:177], v141 offset:49152
	ds_read_b128 v[178:181], v141 offset:50176
	ds_read_b128 v[182:185], v141 offset:51200
	ds_read_b128 v[196:199], v141 offset:52224
	ds_read_b128 v[200:203], v141 offset:53248
	ds_read_b128 v[204:207], v141 offset:54272
	ds_read_b128 v[208:211], v141 offset:55296
	ds_read_b128 v[212:215], v141 offset:56320
	global_load_lds_dwordx4 v[186:187], off
	s_add_i32 m0, s34, 0x2000
	s_add_u32 s30, s30, 0x80080
	v_lshl_add_u64 v[186:187], v[216:217], 0, s[58:59]
	s_addc_u32 s31, s31, 0
	s_add_i32 s34, s61, s38
	global_load_lds_dwordx4 v[186:187], off
	v_lshl_add_u64 v[186:187], s[30:31], 0, v[190:191]
	s_mov_b32 m0, s34
	s_nop 0
	global_load_lds_dwordx4 v[186:187], off
	v_lshl_add_u64 v[186:187], s[30:31], 0, v[132:133]
	s_add_i32 m0, s34, 0x2000
	s_nop 0
	global_load_lds_dwordx4 v[186:187], off
	v_lshl_add_u64 v[186:187], v[218:219], 0, s[58:59]
	s_mov_b32 m0, s43
	s_nop 0
	global_load_lds_dwordx4 v[186:187], off
	v_lshl_add_u64 v[186:187], v[220:221], 0, s[58:59]
	s_mov_b32 m0, s47
	s_nop 0
	global_load_lds_dwordx4 v[186:187], off
	s_waitcnt vmcnt(8)
	s_waitcnt lgkmcnt(0)
	s_barrier
	s_setprio 1
	s_waitcnt lgkmcnt(0)
	v_mfma_f32_16x16x32_bf16 v[60:63], v[142:145], v[174:177], v[60:63]
	v_mfma_f32_16x16x32_bf16 v[56:59], v[150:153], v[174:177], v[56:59]
	v_mfma_f32_16x16x32_bf16 v[52:55], v[142:145], v[182:185], v[52:55]
	v_mfma_f32_16x16x32_bf16 v[48:51], v[150:153], v[182:185], v[48:51]
	v_mfma_f32_16x16x32_bf16 v[36:39], v[142:145], v[200:203], v[36:39]
	v_mfma_f32_16x16x32_bf16 v[32:35], v[150:153], v[200:203], v[32:35]
	v_mfma_f32_16x16x32_bf16 v[20:23], v[142:145], v[208:211], v[20:23]
	v_mfma_f32_16x16x32_bf16 v[16:19], v[150:153], v[208:211], v[16:19]
	v_mfma_f32_16x16x32_bf16 v[60:63], v[146:149], v[178:181], v[60:63]
	v_mfma_f32_16x16x32_bf16 v[56:59], v[154:157], v[178:181], v[56:59]
	v_mfma_f32_16x16x32_bf16 v[52:55], v[146:149], v[196:199], v[52:55]
	v_mfma_f32_16x16x32_bf16 v[48:51], v[154:157], v[196:199], v[48:51]
	v_mfma_f32_16x16x32_bf16 v[36:39], v[146:149], v[204:207], v[36:39]
	v_mfma_f32_16x16x32_bf16 v[32:35], v[154:157], v[204:207], v[32:35]
	v_mfma_f32_16x16x32_bf16 v[20:23], v[146:149], v[212:215], v[20:23]
	v_mfma_f32_16x16x32_bf16 v[16:19], v[154:157], v[212:215], v[16:19]
	s_setprio 0
	s_setprio 1
	v_mfma_f32_16x16x32_bf16 v[44:47], v[158:161], v[174:177], v[44:47]
	v_mfma_f32_16x16x32_bf16 v[40:43], v[166:169], v[174:177], v[40:43]
	v_mfma_f32_16x16x32_bf16 v[28:31], v[158:161], v[182:185], v[28:31]
	v_mfma_f32_16x16x32_bf16 v[24:27], v[166:169], v[182:185], v[24:27]
	v_mfma_f32_16x16x32_bf16 v[12:15], v[158:161], v[200:203], v[12:15]
	v_mfma_f32_16x16x32_bf16 v[8:11], v[166:169], v[200:203], v[8:11]
	v_mfma_f32_16x16x32_bf16 v[4:7], v[158:161], v[208:211], v[4:7]
	v_mfma_f32_16x16x32_bf16 v[0:3], v[166:169], v[208:211], v[0:3]
	v_mfma_f32_16x16x32_bf16 v[44:47], v[162:165], v[178:181], v[44:47]
	v_mfma_f32_16x16x32_bf16 v[40:43], v[170:173], v[178:181], v[40:43]
	v_mfma_f32_16x16x32_bf16 v[28:31], v[162:165], v[196:199], v[28:31]
	v_mfma_f32_16x16x32_bf16 v[24:27], v[170:173], v[196:199], v[24:27]
	v_mfma_f32_16x16x32_bf16 v[12:15], v[162:165], v[204:207], v[12:15]
	v_mfma_f32_16x16x32_bf16 v[8:11], v[170:173], v[204:207], v[8:11]
	v_mfma_f32_16x16x32_bf16 v[4:7], v[162:165], v[212:215], v[4:7]
	v_mfma_f32_16x16x32_bf16 v[0:3], v[170:173], v[212:215], v[0:3]
	s_setprio 0
	s_barrier
	s_add_i32 s57, s57, 2
	s_add_u32 s28, s28, 0x100
	s_addc_u32 s29, s29, 0
	s_add_u32 s55, s55, 0x100
	s_addc_u32 s56, s56, 0
	s_cmp_gt_u32 s57, 29
	s_cbranch_scc1 .Lpeel_done_6

.Lpeel_done_6:
	s_and_b64 vcc, exec, s[14:15]
	s_cbranch_vccz .LBB0_941
	s_barrier

.LBB0_1104:
	s_ashr_i32 s61, s60, 31
	s_lshl_b64 s[52:53], s[60:61], 20
	v_readlane_b32 s0, v254, 17
	v_readlane_b32 s1, v254, 18
	s_add_u32 s88, s0, s52
	s_addc_u32 s89, s1, s53
	s_and_b64 s[52:53], s[8:9], exec
	s_cselect_b32 s13, s89, s11
	s_cselect_b32 s15, s88, s10
	s_ashr_i32 s57, s56, 31
	s_lshl_b64 s[52:53], s[56:57], 20
	v_readlane_b32 s0, v254, 36
	v_readlane_b32 s1, v254, 37
	s_add_u32 s90, s0, s52
	s_addc_u32 s91, s1, s53
	s_and_b64 s[52:53], s[8:9], exec
	s_cselect_b32 s57, s91, s17
	s_cselect_b32 s61, s90, s16
	s_add_u32 s66, s16, 0x100
	s_addc_u32 s67, s17, 0
	s_mov_b32 vcc_lo, -2
	v_readlane_b32 s0, v255, 49
	s_nop 3
	s_cmp_eq_u32 s0, 8
	v_writelane_b32 v255, 8, 49
	s_cbranch_scc0 .Ltrip0_strict_7
	s_add_u32 s16, s10, 0x100
	s_addc_u32 s17, s11, 0
	s_add_i32 vcc_hi, 0, 0x10000
	s_cmp_eq_u32 vcc_lo, 28
	s_cselect_b32 s69, s13, s17
	s_cselect_b32 s68, s15, s16
	s_cselect_b32 s53, s57, s67
	s_cselect_b32 s52, s61, s66
	s_add_i32 s0, 0, 0x14000
	v_add_u32_e32 v140, vcc_hi, v200
	v_add_u32_e32 v156, s0, v200
	ds_read_b128 v[128:131], v140
	ds_read_b128 v[132:135], v140 offset:1024
	ds_read_b128 v[136:139], v140 offset:2048
	ds_read_b128 v[140:143], v140 offset:3072
	ds_read_b128 v[144:147], v156
	ds_read_b128 v[148:151], v156 offset:1024
	ds_read_b128 v[152:155], v156 offset:2048
	ds_read_b128 v[156:159], v156 offset:3072
	v_lshl_add_u64 v[186:187], s[10:11], 0, v[182:183]
	s_add_i32 m0, s40, 0xc000
	ds_read_b128 v[160:163], v206
	ds_read_b128 v[164:167], v206 offset:1024
	ds_read_b128 v[168:171], v206 offset:2048
	ds_read_b128 v[172:175], v206 offset:3072
	ds_read_b128 v[196:199], v206 offset:4096
	ds_read_b128 v[208:211], v206 offset:5120
	ds_read_b128 v[212:215], v206 offset:6144
	ds_read_b128 v[216:219], v206 offset:7168
	global_load_lds_dwordx4 v[186:187], off
	v_lshl_add_u64 v[186:187], s[10:11], 0, v[184:185]
	s_add_i32 m0, s40, 0xe000
	s_nop 0
	global_load_lds_dwordx4 v[186:187], off
	s_waitcnt vmcnt(24)
	s_waitcnt lgkmcnt(0)
	s_barrier
	s_setprio 1
	s_waitcnt lgkmcnt(0)
	v_mfma_f32_16x16x32_bf16 v[120:123], v[128:131], v[160:163], 0
	v_mfma_f32_16x16x32_bf16 v[48:51], v[136:139], v[160:163], 0
	v_mfma_f32_16x16x32_bf16 v[124:127], v[128:131], v[168:171], 0
	v_mfma_f32_16x16x32_bf16 v[60:63], v[136:139], v[168:171], 0
	v_mfma_f32_16x16x32_bf16 v[112:115], v[128:131], v[196:199], 0
	v_mfma_f32_16x16x32_bf16 v[52:55], v[136:139], v[196:199], 0
	v_mfma_f32_16x16x32_bf16 v[108:111], v[128:131], v[212:215], 0
	v_mfma_f32_16x16x32_bf16 v[36:39], v[136:139], v[212:215], 0
	v_mfma_f32_16x16x32_bf16 v[120:123], v[132:135], v[164:167], v[120:123]
	v_mfma_f32_16x16x32_bf16 v[48:51], v[140:143], v[164:167], v[48:51]
	v_mfma_f32_16x16x32_bf16 v[124:127], v[132:135], v[172:175], v[124:127]
	v_mfma_f32_16x16x32_bf16 v[60:63], v[140:143], v[172:175], v[60:63]
	v_mfma_f32_16x16x32_bf16 v[112:115], v[132:135], v[208:211], v[112:115]
	v_mfma_f32_16x16x32_bf16 v[52:55], v[140:143], v[208:211], v[52:55]
	v_mfma_f32_16x16x32_bf16 v[108:111], v[132:135], v[216:219], v[108:111]
	v_mfma_f32_16x16x32_bf16 v[36:39], v[140:143], v[216:219], v[36:39]
	s_setprio 0
	s_setprio 1
	v_mfma_f32_16x16x32_bf16 v[100:103], v[144:147], v[160:163], 0
	v_mfma_f32_16x16x32_bf16 v[40:43], v[152:155], v[160:163], 0
	v_mfma_f32_16x16x32_bf16 v[116:119], v[144:147], v[168:171], 0
	v_mfma_f32_16x16x32_bf16 v[56:59], v[152:155], v[168:171], 0
	v_mfma_f32_16x16x32_bf16 v[104:107], v[144:147], v[196:199], 0
	v_mfma_f32_16x16x32_bf16 v[44:47], v[152:155], v[196:199], 0
	v_mfma_f32_16x16x32_bf16 v[96:99], v[144:147], v[212:215], 0
	v_mfma_f32_16x16x32_bf16 v[32:35], v[152:155], v[212:215], 0
	v_mfma_f32_16x16x32_bf16 v[100:103], v[148:151], v[164:167], v[100:103]
	v_mfma_f32_16x16x32_bf16 v[40:43], v[156:159], v[164:167], v[40:43]
	v_mfma_f32_16x16x32_bf16 v[116:119], v[148:151], v[172:175], v[116:119]
	v_mfma_f32_16x16x32_bf16 v[56:59], v[156:159], v[172:175], v[56:59]
	v_mfma_f32_16x16x32_bf16 v[104:107], v[148:151], v[208:211], v[104:107]
	v_mfma_f32_16x16x32_bf16 v[44:47], v[156:159], v[208:211], v[44:47]
	v_mfma_f32_16x16x32_bf16 v[96:99], v[148:151], v[216:219], v[96:99]
	v_mfma_f32_16x16x32_bf16 v[32:35], v[156:159], v[216:219], v[32:35]
	s_setprio 0
	s_barrier
	s_add_i32 s1, vcc_hi, s33
	v_lshl_add_u64 v[186:187], s[52:53], 0, v[190:191]
	s_mov_b32 m0, s1
	ds_read_b128 v[160:163], v206 offset:16384
	ds_read_b128 v[164:167], v206 offset:17408
	ds_read_b128 v[168:171], v206 offset:18432
	ds_read_b128 v[172:175], v206 offset:19456
	ds_read_b128 v[196:199], v206 offset:20480
	ds_read_b128 v[208:211], v206 offset:21504
	ds_read_b128 v[212:215], v206 offset:22528
	ds_read_b128 v[216:219], v206 offset:23552
	global_load_lds_dwordx4 v[186:187], off
	s_add_i32 m0, s1, 0x2000
	s_add_u32 s10, s52, 0x80000
	v_lshl_add_u64 v[220:221], s[52:53], 0, v[180:181]
	s_addc_u32 s11, s53, 0
	s_add_i32 s0, s0, s33
	global_load_lds_dwordx4 v[220:221], off
	v_lshl_add_u64 v[222:223], s[10:11], 0, v[190:191]
	s_mov_b32 m0, s0
	v_lshl_add_u64 v[224:225], s[68:69], 0, v[178:179]
	global_load_lds_dwordx4 v[222:223], off
	v_lshl_add_u64 v[222:223], s[10:11], 0, v[180:181]
	s_add_i32 m0, s0, 0x2000
	s_nop 0
	global_load_lds_dwordx4 v[222:223], off
	v_lshl_add_u64 v[222:223], s[68:69], 0, v[176:177]
	s_mov_b32 m0, s40
	s_nop 0
	global_load_lds_dwordx4 v[222:223], off
	s_mov_b32 m0, s41
	s_nop 0
	global_load_lds_dwordx4 v[224:225], off
	s_waitcnt vmcnt(24)
	s_waitcnt lgkmcnt(0)
	s_barrier
	s_setprio 1
	s_waitcnt lgkmcnt(0)
	v_mfma_f32_16x16x32_bf16 v[88:91], v[128:131], v[160:163], 0
	v_mfma_f32_16x16x32_bf16 v[20:23], v[136:139], v[160:163], 0
	v_mfma_f32_16x16x32_bf16 v[92:95], v[128:131], v[168:171], 0
	v_mfma_f32_16x16x32_bf16 v[28:31], v[136:139], v[168:171], 0
	v_mfma_f32_16x16x32_bf16 v[80:83], v[128:131], v[196:199], 0
	v_mfma_f32_16x16x32_bf16 v[16:19], v[136:139], v[196:199], 0
	v_mfma_f32_16x16x32_bf16 v[76:79], v[128:131], v[212:215], 0
	v_mfma_f32_16x16x32_bf16 v[12:15], v[136:139], v[212:215], 0
	v_mfma_f32_16x16x32_bf16 v[88:91], v[132:135], v[164:167], v[88:91]
	v_mfma_f32_16x16x32_bf16 v[20:23], v[140:143], v[164:167], v[20:23]
	v_mfma_f32_16x16x32_bf16 v[92:95], v[132:135], v[172:175], v[92:95]
	v_mfma_f32_16x16x32_bf16 v[28:31], v[140:143], v[172:175], v[28:31]
	v_mfma_f32_16x16x32_bf16 v[80:83], v[132:135], v[208:211], v[80:83]
	v_mfma_f32_16x16x32_bf16 v[16:19], v[140:143], v[208:211], v[16:19]
	v_mfma_f32_16x16x32_bf16 v[76:79], v[132:135], v[216:219], v[76:79]
	v_mfma_f32_16x16x32_bf16 v[12:15], v[140:143], v[216:219], v[12:15]
	s_setprio 0
	s_setprio 1
	v_mfma_f32_16x16x32_bf16 v[68:71], v[144:147], v[160:163], 0
	v_mfma_f32_16x16x32_bf16 v[4:7], v[152:155], v[160:163], 0
	v_mfma_f32_16x16x32_bf16 v[84:87], v[144:147], v[168:171], 0
	v_mfma_f32_16x16x32_bf16 v[24:27], v[152:155], v[168:171], 0
	v_mfma_f32_16x16x32_bf16 v[72:75], v[144:147], v[196:199], 0
	v_mfma_f32_16x16x32_bf16 v[8:11], v[152:155], v[196:199], 0
	v_mfma_f32_16x16x32_bf16 v[64:67], v[144:147], v[212:215], 0
	v_mfma_f32_16x16x32_bf16 v[0:3], v[152:155], v[212:215], 0
	v_mfma_f32_16x16x32_bf16 v[68:71], v[148:151], v[164:167], v[68:71]
	v_mfma_f32_16x16x32_bf16 v[4:7], v[156:159], v[164:167], v[4:7]
	v_mfma_f32_16x16x32_bf16 v[84:87], v[148:151], v[172:175], v[84:87]
	v_mfma_f32_16x16x32_bf16 v[24:27], v[156:159], v[172:175], v[24:27]
	v_mfma_f32_16x16x32_bf16 v[72:75], v[148:151], v[208:211], v[72:75]
	v_mfma_f32_16x16x32_bf16 v[8:11], v[156:159], v[208:211], v[8:11]
	v_mfma_f32_16x16x32_bf16 v[64:67], v[148:151], v[216:219], v[64:67]
	v_mfma_f32_16x16x32_bf16 v[0:3], v[156:159], v[216:219], v[0:3]
	s_setprio 0
	s_barrier
	s_add_i32 s0, 0, 0x18000
	s_add_i32 s1, 0, 0x1c000
	v_add_u32_e32 v140, s0, v200
	v_add_u32_e32 v156, s1, v200
	ds_read_b128 v[128:131], v140
	ds_read_b128 v[132:135], v140 offset:1024
	ds_read_b128 v[136:139], v140 offset:2048
	ds_read_b128 v[140:143], v140 offset:3072
	ds_read_b128 v[144:147], v156
	ds_read_b128 v[148:151], v156 offset:1024
	ds_read_b128 v[152:155], v156 offset:2048
	ds_read_b128 v[156:159], v156 offset:3072
	s_add_u32 s10, s68, 0x80000
	s_addc_u32 s11, s69, 0
	s_mov_b32 m0, s42
	v_lshl_add_u64 v[226:227], s[10:11], 0, v[176:177]
	ds_read_b128 v[160:163], v206 offset:32768
	ds_read_b128 v[164:167], v206 offset:33792
	ds_read_b128 v[168:171], v206 offset:34816
	ds_read_b128 v[172:175], v206 offset:35840
	ds_read_b128 v[196:199], v206 offset:36864
	ds_read_b128 v[208:211], v206 offset:37888
	ds_read_b128 v[212:215], v206 offset:38912
	ds_read_b128 v[216:219], v206 offset:39936
	global_load_lds_dwordx4 v[226:227], off
	v_lshl_add_u64 v[226:227], s[10:11], 0, v[178:179]
	s_mov_b32 m0, s43
	s_nop 0
	global_load_lds_dwordx4 v[226:227], off
	s_waitcnt vmcnt(8)
	s_waitcnt lgkmcnt(0)
	s_barrier
	s_setprio 1
	s_waitcnt lgkmcnt(0)
	v_mfma_f32_16x16x32_bf16 v[120:123], v[128:131], v[160:163], v[120:123]
	v_mfma_f32_16x16x32_bf16 v[48:51], v[136:139], v[160:163], v[48:51]
	v_mfma_f32_16x16x32_bf16 v[124:127], v[128:131], v[168:171], v[124:127]
	v_mfma_f32_16x16x32_bf16 v[60:63], v[136:139], v[168:171], v[60:63]
	v_mfma_f32_16x16x32_bf16 v[112:115], v[128:131], v[196:199], v[112:115]
	v_mfma_f32_16x16x32_bf16 v[52:55], v[136:139], v[196:199], v[52:55]
	v_mfma_f32_16x16x32_bf16 v[108:111], v[128:131], v[212:215], v[108:111]
	v_mfma_f32_16x16x32_bf16 v[36:39], v[136:139], v[212:215], v[36:39]
	v_mfma_f32_16x16x32_bf16 v[120:123], v[132:135], v[164:167], v[120:123]
	v_mfma_f32_16x16x32_bf16 v[48:51], v[140:143], v[164:167], v[48:51]
	v_mfma_f32_16x16x32_bf16 v[124:127], v[132:135], v[172:175], v[124:127]
	v_mfma_f32_16x16x32_bf16 v[60:63], v[140:143], v[172:175], v[60:63]
	v_mfma_f32_16x16x32_bf16 v[112:115], v[132:135], v[208:211], v[112:115]
	v_mfma_f32_16x16x32_bf16 v[52:55], v[140:143], v[208:211], v[52:55]
	v_mfma_f32_16x16x32_bf16 v[108:111], v[132:135], v[216:219], v[108:111]
	v_mfma_f32_16x16x32_bf16 v[36:39], v[140:143], v[216:219], v[36:39]
	s_setprio 0
	s_setprio 1
	v_mfma_f32_16x16x32_bf16 v[100:103], v[144:147], v[160:163], v[100:103]
	v_mfma_f32_16x16x32_bf16 v[40:43], v[152:155], v[160:163], v[40:43]
	v_mfma_f32_16x16x32_bf16 v[116:119], v[144:147], v[168:171], v[116:119]
	v_mfma_f32_16x16x32_bf16 v[56:59], v[152:155], v[168:171], v[56:59]
	v_mfma_f32_16x16x32_bf16 v[104:107], v[144:147], v[196:199], v[104:107]
	v_mfma_f32_16x16x32_bf16 v[44:47], v[152:155], v[196:199], v[44:47]
	v_mfma_f32_16x16x32_bf16 v[96:99], v[144:147], v[212:215], v[96:99]
	v_mfma_f32_16x16x32_bf16 v[32:35], v[152:155], v[212:215], v[32:35]
	v_mfma_f32_16x16x32_bf16 v[100:103], v[148:151], v[164:167], v[100:103]
	v_mfma_f32_16x16x32_bf16 v[40:43], v[156:159], v[164:167], v[40:43]
	v_mfma_f32_16x16x32_bf16 v[116:119], v[148:151], v[172:175], v[116:119]
	v_mfma_f32_16x16x32_bf16 v[56:59], v[156:159], v[172:175], v[56:59]
	v_mfma_f32_16x16x32_bf16 v[104:107], v[148:151], v[208:211], v[104:107]
	v_mfma_f32_16x16x32_bf16 v[44:47], v[156:159], v[208:211], v[44:47]
	v_mfma_f32_16x16x32_bf16 v[96:99], v[148:151], v[216:219], v[96:99]
	v_mfma_f32_16x16x32_bf16 v[32:35], v[156:159], v[216:219], v[32:35]
	s_setprio 0
	s_barrier
	s_add_i32 s0, s0, s33
	v_lshl_add_u64 v[186:187], v[186:187], 0, s[58:59]
	s_mov_b32 m0, s0
	ds_read_b128 v[160:163], v206 offset:49152
	ds_read_b128 v[164:167], v206 offset:50176
	ds_read_b128 v[168:171], v206 offset:51200
	ds_read_b128 v[172:175], v206 offset:52224
	ds_read_b128 v[196:199], v206 offset:53248
	ds_read_b128 v[208:211], v206 offset:54272
	ds_read_b128 v[212:215], v206 offset:55296
	ds_read_b128 v[216:219], v206 offset:56320
	global_load_lds_dwordx4 v[186:187], off
	s_add_i32 m0, s0, 0x2000
	s_add_u32 s10, s52, 0x80080
	v_lshl_add_u64 v[186:187], v[220:221], 0, s[58:59]
	s_addc_u32 s11, s53, 0
	s_add_i32 s0, s1, s33
	global_load_lds_dwordx4 v[186:187], off
	v_lshl_add_u64 v[186:187], s[10:11], 0, v[190:191]
	s_mov_b32 m0, s0
	s_nop 0
	global_load_lds_dwordx4 v[186:187], off
	v_lshl_add_u64 v[186:187], s[10:11], 0, v[180:181]
	s_add_i32 m0, s0, 0x2000
	s_nop 0
	global_load_lds_dwordx4 v[186:187], off
	v_lshl_add_u64 v[186:187], v[222:223], 0, s[58:59]
	s_mov_b32 m0, s55
	s_nop 0
	global_load_lds_dwordx4 v[186:187], off
	v_lshl_add_u64 v[186:187], v[224:225], 0, s[58:59]
	s_mov_b32 m0, s77
	s_nop 0
	global_load_lds_dwordx4 v[186:187], off
	s_waitcnt vmcnt(8)
	s_waitcnt lgkmcnt(0)
	s_barrier
	s_setprio 1
	s_waitcnt lgkmcnt(0)
	v_mfma_f32_16x16x32_bf16 v[88:91], v[128:131], v[160:163], v[88:91]
	v_mfma_f32_16x16x32_bf16 v[20:23], v[136:139], v[160:163], v[20:23]
	v_mfma_f32_16x16x32_bf16 v[92:95], v[128:131], v[168:171], v[92:95]
	v_mfma_f32_16x16x32_bf16 v[28:31], v[136:139], v[168:171], v[28:31]
	v_mfma_f32_16x16x32_bf16 v[80:83], v[128:131], v[196:199], v[80:83]
	v_mfma_f32_16x16x32_bf16 v[16:19], v[136:139], v[196:199], v[16:19]
	v_mfma_f32_16x16x32_bf16 v[76:79], v[128:131], v[212:215], v[76:79]
	v_mfma_f32_16x16x32_bf16 v[12:15], v[136:139], v[212:215], v[12:15]
	v_mfma_f32_16x16x32_bf16 v[88:91], v[132:135], v[164:167], v[88:91]
	v_mfma_f32_16x16x32_bf16 v[20:23], v[140:143], v[164:167], v[20:23]
	v_mfma_f32_16x16x32_bf16 v[92:95], v[132:135], v[172:175], v[92:95]
	v_mfma_f32_16x16x32_bf16 v[28:31], v[140:143], v[172:175], v[28:31]
	v_mfma_f32_16x16x32_bf16 v[80:83], v[132:135], v[208:211], v[80:83]
	v_mfma_f32_16x16x32_bf16 v[16:19], v[140:143], v[208:211], v[16:19]
	v_mfma_f32_16x16x32_bf16 v[76:79], v[132:135], v[216:219], v[76:79]
	v_mfma_f32_16x16x32_bf16 v[12:15], v[140:143], v[216:219], v[12:15]
	s_setprio 0
	s_setprio 1
	v_mfma_f32_16x16x32_bf16 v[68:71], v[144:147], v[160:163], v[68:71]
	v_mfma_f32_16x16x32_bf16 v[4:7], v[152:155], v[160:163], v[4:7]
	v_mfma_f32_16x16x32_bf16 v[84:87], v[144:147], v[168:171], v[84:87]
	v_mfma_f32_16x16x32_bf16 v[24:27], v[152:155], v[168:171], v[24:27]
	v_mfma_f32_16x16x32_bf16 v[72:75], v[144:147], v[196:199], v[72:75]
	v_mfma_f32_16x16x32_bf16 v[8:11], v[152:155], v[196:199], v[8:11]
	v_mfma_f32_16x16x32_bf16 v[64:67], v[144:147], v[212:215], v[64:67]
	v_mfma_f32_16x16x32_bf16 v[0:3], v[152:155], v[212:215], v[0:3]
	v_mfma_f32_16x16x32_bf16 v[68:71], v[148:151], v[164:167], v[68:71]
	v_mfma_f32_16x16x32_bf16 v[4:7], v[156:159], v[164:167], v[4:7]
	v_mfma_f32_16x16x32_bf16 v[84:87], v[148:151], v[172:175], v[84:87]
	v_mfma_f32_16x16x32_bf16 v[24:27], v[156:159], v[172:175], v[24:27]
	v_mfma_f32_16x16x32_bf16 v[72:75], v[148:151], v[208:211], v[72:75]
	v_mfma_f32_16x16x32_bf16 v[8:11], v[156:159], v[208:211], v[8:11]
	v_mfma_f32_16x16x32_bf16 v[64:67], v[148:151], v[216:219], v[64:67]
	v_mfma_f32_16x16x32_bf16 v[0:3], v[156:159], v[216:219], v[0:3]
	s_setprio 0
	s_barrier
	s_add_i32 vcc_lo, vcc_lo, 2
	s_add_u32 s66, s66, 0x100
	s_addc_u32 s67, s67, 0
	s_cmp_gt_u32 vcc_lo, 29
	s_mov_b64 s[10:11], s[16:17]
	s_cbranch_scc1 .Lpeel_done_7
	s_branch .LBB0_1105
.Ltrip0_strict_7:
	s_add_u32 s16, s10, 0x100
	s_addc_u32 s17, s11, 0
	s_add_i32 vcc_hi, 0, 0x10000
	s_cmp_eq_u32 vcc_lo, 28
	s_cselect_b32 s69, s13, s17
	s_cselect_b32 s68, s15, s16
	s_cselect_b32 s53, s57, s67
	s_cselect_b32 s52, s61, s66
	s_add_i32 s0, 0, 0x14000
	v_add_u32_e32 v140, vcc_hi, v200
	v_add_u32_e32 v156, s0, v200
	ds_read_b128 v[128:131], v140
	ds_read_b128 v[132:135], v140 offset:1024
	ds_read_b128 v[136:139], v140 offset:2048
	ds_read_b128 v[140:143], v140 offset:3072
	ds_read_b128 v[144:147], v156
	ds_read_b128 v[148:151], v156 offset:1024
	ds_read_b128 v[152:155], v156 offset:2048
	ds_read_b128 v[156:159], v156 offset:3072
	v_lshl_add_u64 v[186:187], s[10:11], 0, v[182:183]
	s_add_i32 m0, s40, 0xc000
	ds_read_b128 v[160:163], v206
	ds_read_b128 v[164:167], v206 offset:1024
	ds_read_b128 v[168:171], v206 offset:2048
	ds_read_b128 v[172:175], v206 offset:3072
	ds_read_b128 v[196:199], v206 offset:4096
	ds_read_b128 v[208:211], v206 offset:5120
	ds_read_b128 v[212:215], v206 offset:6144
	ds_read_b128 v[216:219], v206 offset:7168
	global_load_lds_dwordx4 v[186:187], off
	v_lshl_add_u64 v[186:187], s[10:11], 0, v[184:185]
	s_add_i32 m0, s40, 0xe000
	s_nop 0
	global_load_lds_dwordx4 v[186:187], off
	s_waitcnt vmcnt(8)
	s_waitcnt lgkmcnt(0)
	s_barrier
	s_setprio 1
	s_waitcnt lgkmcnt(0)
	v_mfma_f32_16x16x32_bf16 v[120:123], v[128:131], v[160:163], 0
	v_mfma_f32_16x16x32_bf16 v[48:51], v[136:139], v[160:163], 0
	v_mfma_f32_16x16x32_bf16 v[124:127], v[128:131], v[168:171], 0
	v_mfma_f32_16x16x32_bf16 v[60:63], v[136:139], v[168:171], 0
	v_mfma_f32_16x16x32_bf16 v[112:115], v[128:131], v[196:199], 0
	v_mfma_f32_16x16x32_bf16 v[52:55], v[136:139], v[196:199], 0
	v_mfma_f32_16x16x32_bf16 v[108:111], v[128:131], v[212:215], 0
	v_mfma_f32_16x16x32_bf16 v[36:39], v[136:139], v[212:215], 0
	v_mfma_f32_16x16x32_bf16 v[120:123], v[132:135], v[164:167], v[120:123]
	v_mfma_f32_16x16x32_bf16 v[48:51], v[140:143], v[164:167], v[48:51]
	v_mfma_f32_16x16x32_bf16 v[124:127], v[132:135], v[172:175], v[124:127]
	v_mfma_f32_16x16x32_bf16 v[60:63], v[140:143], v[172:175], v[60:63]
	v_mfma_f32_16x16x32_bf16 v[112:115], v[132:135], v[208:211], v[112:115]
	v_mfma_f32_16x16x32_bf16 v[52:55], v[140:143], v[208:211], v[52:55]
	v_mfma_f32_16x16x32_bf16 v[108:111], v[132:135], v[216:219], v[108:111]
	v_mfma_f32_16x16x32_bf16 v[36:39], v[140:143], v[216:219], v[36:39]
	s_setprio 0
	s_setprio 1
	v_mfma_f32_16x16x32_bf16 v[100:103], v[144:147], v[160:163], 0
	v_mfma_f32_16x16x32_bf16 v[40:43], v[152:155], v[160:163], 0
	v_mfma_f32_16x16x32_bf16 v[116:119], v[144:147], v[168:171], 0
	v_mfma_f32_16x16x32_bf16 v[56:59], v[152:155], v[168:171], 0
	v_mfma_f32_16x16x32_bf16 v[104:107], v[144:147], v[196:199], 0
	v_mfma_f32_16x16x32_bf16 v[44:47], v[152:155], v[196:199], 0
	v_mfma_f32_16x16x32_bf16 v[96:99], v[144:147], v[212:215], 0
	v_mfma_f32_16x16x32_bf16 v[32:35], v[152:155], v[212:215], 0
	v_mfma_f32_16x16x32_bf16 v[100:103], v[148:151], v[164:167], v[100:103]
	v_mfma_f32_16x16x32_bf16 v[40:43], v[156:159], v[164:167], v[40:43]
	v_mfma_f32_16x16x32_bf16 v[116:119], v[148:151], v[172:175], v[116:119]
	v_mfma_f32_16x16x32_bf16 v[56:59], v[156:159], v[172:175], v[56:59]
	v_mfma_f32_16x16x32_bf16 v[104:107], v[148:151], v[208:211], v[104:107]
	v_mfma_f32_16x16x32_bf16 v[44:47], v[156:159], v[208:211], v[44:47]
	v_mfma_f32_16x16x32_bf16 v[96:99], v[148:151], v[216:219], v[96:99]
	v_mfma_f32_16x16x32_bf16 v[32:35], v[156:159], v[216:219], v[32:35]
	s_setprio 0
	s_barrier
	s_add_i32 s1, vcc_hi, s33
	v_lshl_add_u64 v[186:187], s[52:53], 0, v[190:191]
	s_mov_b32 m0, s1
	ds_read_b128 v[160:163], v206 offset:16384
	ds_read_b128 v[164:167], v206 offset:17408
	ds_read_b128 v[168:171], v206 offset:18432
	ds_read_b128 v[172:175], v206 offset:19456
	ds_read_b128 v[196:199], v206 offset:20480
	ds_read_b128 v[208:211], v206 offset:21504
	ds_read_b128 v[212:215], v206 offset:22528
	ds_read_b128 v[216:219], v206 offset:23552
	global_load_lds_dwordx4 v[186:187], off
	s_add_i32 m0, s1, 0x2000
	s_add_u32 s10, s52, 0x80000
	v_lshl_add_u64 v[220:221], s[52:53], 0, v[180:181]
	s_addc_u32 s11, s53, 0
	s_add_i32 s0, s0, s33
	global_load_lds_dwordx4 v[220:221], off
	v_lshl_add_u64 v[222:223], s[10:11], 0, v[190:191]
	s_mov_b32 m0, s0
	v_lshl_add_u64 v[224:225], s[68:69], 0, v[178:179]
	global_load_lds_dwordx4 v[222:223], off
	v_lshl_add_u64 v[222:223], s[10:11], 0, v[180:181]
	s_add_i32 m0, s0, 0x2000
	s_nop 0
	global_load_lds_dwordx4 v[222:223], off
	v_lshl_add_u64 v[222:223], s[68:69], 0, v[176:177]
	s_mov_b32 m0, s40
	s_nop 0
	global_load_lds_dwordx4 v[222:223], off
	s_mov_b32 m0, s41
	s_nop 0
	global_load_lds_dwordx4 v[224:225], off
	s_waitcnt vmcnt(8)
	s_waitcnt lgkmcnt(0)
	s_barrier
	s_setprio 1
	s_waitcnt lgkmcnt(0)
	v_mfma_f32_16x16x32_bf16 v[88:91], v[128:131], v[160:163], 0
	v_mfma_f32_16x16x32_bf16 v[20:23], v[136:139], v[160:163], 0
	v_mfma_f32_16x16x32_bf16 v[92:95], v[128:131], v[168:171], 0
	v_mfma_f32_16x16x32_bf16 v[28:31], v[136:139], v[168:171], 0
	v_mfma_f32_16x16x32_bf16 v[80:83], v[128:131], v[196:199], 0
	v_mfma_f32_16x16x32_bf16 v[16:19], v[136:139], v[196:199], 0
	v_mfma_f32_16x16x32_bf16 v[76:79], v[128:131], v[212:215], 0
	v_mfma_f32_16x16x32_bf16 v[12:15], v[136:139], v[212:215], 0
	v_mfma_f32_16x16x32_bf16 v[88:91], v[132:135], v[164:167], v[88:91]
	v_mfma_f32_16x16x32_bf16 v[20:23], v[140:143], v[164:167], v[20:23]
	v_mfma_f32_16x16x32_bf16 v[92:95], v[132:135], v[172:175], v[92:95]
	v_mfma_f32_16x16x32_bf16 v[28:31], v[140:143], v[172:175], v[28:31]
	v_mfma_f32_16x16x32_bf16 v[80:83], v[132:135], v[208:211], v[80:83]
	v_mfma_f32_16x16x32_bf16 v[16:19], v[140:143], v[208:211], v[16:19]
	v_mfma_f32_16x16x32_bf16 v[76:79], v[132:135], v[216:219], v[76:79]
	v_mfma_f32_16x16x32_bf16 v[12:15], v[140:143], v[216:219], v[12:15]
	s_setprio 0
	s_setprio 1
	v_mfma_f32_16x16x32_bf16 v[68:71], v[144:147], v[160:163], 0
	v_mfma_f32_16x16x32_bf16 v[4:7], v[152:155], v[160:163], 0
	v_mfma_f32_16x16x32_bf16 v[84:87], v[144:147], v[168:171], 0
	v_mfma_f32_16x16x32_bf16 v[24:27], v[152:155], v[168:171], 0
	v_mfma_f32_16x16x32_bf16 v[72:75], v[144:147], v[196:199], 0
	v_mfma_f32_16x16x32_bf16 v[8:11], v[152:155], v[196:199], 0
	v_mfma_f32_16x16x32_bf16 v[64:67], v[144:147], v[212:215], 0
	v_mfma_f32_16x16x32_bf16 v[0:3], v[152:155], v[212:215], 0
	v_mfma_f32_16x16x32_bf16 v[68:71], v[148:151], v[164:167], v[68:71]
	v_mfma_f32_16x16x32_bf16 v[4:7], v[156:159], v[164:167], v[4:7]
	v_mfma_f32_16x16x32_bf16 v[84:87], v[148:151], v[172:175], v[84:87]
	v_mfma_f32_16x16x32_bf16 v[24:27], v[156:159], v[172:175], v[24:27]
	v_mfma_f32_16x16x32_bf16 v[72:75], v[148:151], v[208:211], v[72:75]
	v_mfma_f32_16x16x32_bf16 v[8:11], v[156:159], v[208:211], v[8:11]
	v_mfma_f32_16x16x32_bf16 v[64:67], v[148:151], v[216:219], v[64:67]
	v_mfma_f32_16x16x32_bf16 v[0:3], v[156:159], v[216:219], v[0:3]
	s_setprio 0
	s_barrier
	s_add_i32 s0, 0, 0x18000
	s_add_i32 s1, 0, 0x1c000
	v_add_u32_e32 v140, s0, v200
	v_add_u32_e32 v156, s1, v200
	ds_read_b128 v[128:131], v140
	ds_read_b128 v[132:135], v140 offset:1024
	ds_read_b128 v[136:139], v140 offset:2048
	ds_read_b128 v[140:143], v140 offset:3072
	ds_read_b128 v[144:147], v156
	ds_read_b128 v[148:151], v156 offset:1024
	ds_read_b128 v[152:155], v156 offset:2048
	ds_read_b128 v[156:159], v156 offset:3072
	s_add_u32 s10, s68, 0x80000
	s_addc_u32 s11, s69, 0
	s_mov_b32 m0, s42
	v_lshl_add_u64 v[226:227], s[10:11], 0, v[176:177]
	ds_read_b128 v[160:163], v206 offset:32768
	ds_read_b128 v[164:167], v206 offset:33792
	ds_read_b128 v[168:171], v206 offset:34816
	ds_read_b128 v[172:175], v206 offset:35840
	ds_read_b128 v[196:199], v206 offset:36864
	ds_read_b128 v[208:211], v206 offset:37888
	ds_read_b128 v[212:215], v206 offset:38912
	ds_read_b128 v[216:219], v206 offset:39936
	global_load_lds_dwordx4 v[226:227], off
	v_lshl_add_u64 v[226:227], s[10:11], 0, v[178:179]
	s_mov_b32 m0, s43
	s_nop 0
	global_load_lds_dwordx4 v[226:227], off
	s_waitcnt vmcnt(8)
	s_waitcnt lgkmcnt(0)
	s_barrier
	s_setprio 1
	s_waitcnt lgkmcnt(0)
	v_mfma_f32_16x16x32_bf16 v[120:123], v[128:131], v[160:163], v[120:123]
	v_mfma_f32_16x16x32_bf16 v[48:51], v[136:139], v[160:163], v[48:51]
	v_mfma_f32_16x16x32_bf16 v[124:127], v[128:131], v[168:171], v[124:127]
	v_mfma_f32_16x16x32_bf16 v[60:63], v[136:139], v[168:171], v[60:63]
	v_mfma_f32_16x16x32_bf16 v[112:115], v[128:131], v[196:199], v[112:115]
	v_mfma_f32_16x16x32_bf16 v[52:55], v[136:139], v[196:199], v[52:55]
	v_mfma_f32_16x16x32_bf16 v[108:111], v[128:131], v[212:215], v[108:111]
	v_mfma_f32_16x16x32_bf16 v[36:39], v[136:139], v[212:215], v[36:39]
	v_mfma_f32_16x16x32_bf16 v[120:123], v[132:135], v[164:167], v[120:123]
	v_mfma_f32_16x16x32_bf16 v[48:51], v[140:143], v[164:167], v[48:51]
	v_mfma_f32_16x16x32_bf16 v[124:127], v[132:135], v[172:175], v[124:127]
	v_mfma_f32_16x16x32_bf16 v[60:63], v[140:143], v[172:175], v[60:63]
	v_mfma_f32_16x16x32_bf16 v[112:115], v[132:135], v[208:211], v[112:115]
	v_mfma_f32_16x16x32_bf16 v[52:55], v[140:143], v[208:211], v[52:55]
	v_mfma_f32_16x16x32_bf16 v[108:111], v[132:135], v[216:219], v[108:111]
	v_mfma_f32_16x16x32_bf16 v[36:39], v[140:143], v[216:219], v[36:39]
	s_setprio 0
	s_setprio 1
	v_mfma_f32_16x16x32_bf16 v[100:103], v[144:147], v[160:163], v[100:103]
	v_mfma_f32_16x16x32_bf16 v[40:43], v[152:155], v[160:163], v[40:43]
	v_mfma_f32_16x16x32_bf16 v[116:119], v[144:147], v[168:171], v[116:119]
	v_mfma_f32_16x16x32_bf16 v[56:59], v[152:155], v[168:171], v[56:59]
	v_mfma_f32_16x16x32_bf16 v[104:107], v[144:147], v[196:199], v[104:107]
	v_mfma_f32_16x16x32_bf16 v[44:47], v[152:155], v[196:199], v[44:47]
	v_mfma_f32_16x16x32_bf16 v[96:99], v[144:147], v[212:215], v[96:99]
	v_mfma_f32_16x16x32_bf16 v[32:35], v[152:155], v[212:215], v[32:35]
	v_mfma_f32_16x16x32_bf16 v[100:103], v[148:151], v[164:167], v[100:103]
	v_mfma_f32_16x16x32_bf16 v[40:43], v[156:159], v[164:167], v[40:43]
	v_mfma_f32_16x16x32_bf16 v[116:119], v[148:151], v[172:175], v[116:119]
	v_mfma_f32_16x16x32_bf16 v[56:59], v[156:159], v[172:175], v[56:59]
	v_mfma_f32_16x16x32_bf16 v[104:107], v[148:151], v[208:211], v[104:107]
	v_mfma_f32_16x16x32_bf16 v[44:47], v[156:159], v[208:211], v[44:47]
	v_mfma_f32_16x16x32_bf16 v[96:99], v[148:151], v[216:219], v[96:99]
	v_mfma_f32_16x16x32_bf16 v[32:35], v[156:159], v[216:219], v[32:35]
	s_setprio 0
	s_barrier
	s_add_i32 s0, s0, s33
	v_lshl_add_u64 v[186:187], v[186:187], 0, s[58:59]
	s_mov_b32 m0, s0
	ds_read_b128 v[160:163], v206 offset:49152
	ds_read_b128 v[164:167], v206 offset:50176
	ds_read_b128 v[168:171], v206 offset:51200
	ds_read_b128 v[172:175], v206 offset:52224
	ds_read_b128 v[196:199], v206 offset:53248
	ds_read_b128 v[208:211], v206 offset:54272
	ds_read_b128 v[212:215], v206 offset:55296
	ds_read_b128 v[216:219], v206 offset:56320
	global_load_lds_dwordx4 v[186:187], off
	s_add_i32 m0, s0, 0x2000
	s_add_u32 s10, s52, 0x80080
	v_lshl_add_u64 v[186:187], v[220:221], 0, s[58:59]
	s_addc_u32 s11, s53, 0
	s_add_i32 s0, s1, s33
	global_load_lds_dwordx4 v[186:187], off
	v_lshl_add_u64 v[186:187], s[10:11], 0, v[190:191]
	s_mov_b32 m0, s0
	s_nop 0
	global_load_lds_dwordx4 v[186:187], off
	v_lshl_add_u64 v[186:187], s[10:11], 0, v[180:181]
	s_add_i32 m0, s0, 0x2000
	s_nop 0
	global_load_lds_dwordx4 v[186:187], off
	v_lshl_add_u64 v[186:187], v[222:223], 0, s[58:59]
	s_mov_b32 m0, s55
	s_nop 0
	global_load_lds_dwordx4 v[186:187], off
	v_lshl_add_u64 v[186:187], v[224:225], 0, s[58:59]
	s_mov_b32 m0, s77
	s_nop 0
	global_load_lds_dwordx4 v[186:187], off
	s_waitcnt vmcnt(8)
	s_waitcnt lgkmcnt(0)
	s_barrier
	s_setprio 1
	s_waitcnt lgkmcnt(0)
	v_mfma_f32_16x16x32_bf16 v[88:91], v[128:131], v[160:163], v[88:91]
	v_mfma_f32_16x16x32_bf16 v[20:23], v[136:139], v[160:163], v[20:23]
	v_mfma_f32_16x16x32_bf16 v[92:95], v[128:131], v[168:171], v[92:95]
	v_mfma_f32_16x16x32_bf16 v[28:31], v[136:139], v[168:171], v[28:31]
	v_mfma_f32_16x16x32_bf16 v[80:83], v[128:131], v[196:199], v[80:83]
	v_mfma_f32_16x16x32_bf16 v[16:19], v[136:139], v[196:199], v[16:19]
	v_mfma_f32_16x16x32_bf16 v[76:79], v[128:131], v[212:215], v[76:79]
	v_mfma_f32_16x16x32_bf16 v[12:15], v[136:139], v[212:215], v[12:15]
	v_mfma_f32_16x16x32_bf16 v[88:91], v[132:135], v[164:167], v[88:91]
	v_mfma_f32_16x16x32_bf16 v[20:23], v[140:143], v[164:167], v[20:23]
	v_mfma_f32_16x16x32_bf16 v[92:95], v[132:135], v[172:175], v[92:95]
	v_mfma_f32_16x16x32_bf16 v[28:31], v[140:143], v[172:175], v[28:31]
	v_mfma_f32_16x16x32_bf16 v[80:83], v[132:135], v[208:211], v[80:83]
	v_mfma_f32_16x16x32_bf16 v[16:19], v[140:143], v[208:211], v[16:19]
	v_mfma_f32_16x16x32_bf16 v[76:79], v[132:135], v[216:219], v[76:79]
	v_mfma_f32_16x16x32_bf16 v[12:15], v[140:143], v[216:219], v[12:15]
	s_setprio 0
	s_setprio 1
	v_mfma_f32_16x16x32_bf16 v[68:71], v[144:147], v[160:163], v[68:71]
	v_mfma_f32_16x16x32_bf16 v[4:7], v[152:155], v[160:163], v[4:7]
	v_mfma_f32_16x16x32_bf16 v[84:87], v[144:147], v[168:171], v[84:87]
	v_mfma_f32_16x16x32_bf16 v[24:27], v[152:155], v[168:171], v[24:27]
	v_mfma_f32_16x16x32_bf16 v[72:75], v[144:147], v[196:199], v[72:75]
	v_mfma_f32_16x16x32_bf16 v[8:11], v[152:155], v[196:199], v[8:11]
	v_mfma_f32_16x16x32_bf16 v[64:67], v[144:147], v[212:215], v[64:67]
	v_mfma_f32_16x16x32_bf16 v[0:3], v[152:155], v[212:215], v[0:3]
	v_mfma_f32_16x16x32_bf16 v[68:71], v[148:151], v[164:167], v[68:71]
	v_mfma_f32_16x16x32_bf16 v[4:7], v[156:159], v[164:167], v[4:7]
	v_mfma_f32_16x16x32_bf16 v[84:87], v[148:151], v[172:175], v[84:87]
	v_mfma_f32_16x16x32_bf16 v[24:27], v[156:159], v[172:175], v[24:27]
	v_mfma_f32_16x16x32_bf16 v[72:75], v[148:151], v[208:211], v[72:75]
	v_mfma_f32_16x16x32_bf16 v[8:11], v[156:159], v[208:211], v[8:11]
	v_mfma_f32_16x16x32_bf16 v[64:67], v[148:151], v[216:219], v[64:67]
	v_mfma_f32_16x16x32_bf16 v[0:3], v[156:159], v[216:219], v[0:3]
	s_setprio 0
	s_barrier
	s_add_i32 vcc_lo, vcc_lo, 2
	s_add_u32 s66, s66, 0x100
	s_addc_u32 s67, s67, 0
	s_cmp_gt_u32 vcc_lo, 29
	s_mov_b64 s[10:11], s[16:17]
	s_cbranch_scc1 .Lpeel_done_7

.Lpeel_done_7:
	s_and_b64 vcc, exec, s[22:23]
	s_cbranch_vccz .LBB0_1108
	s_barrier

.LBB0_1349:
	s_add_u32 s47, s20, 0x100
	s_addc_u32 s52, s21, 0
	s_mov_b32 s53, -2
	v_readlane_b32 s0, v255, 49
	s_nop 3
	s_cmp_eq_u32 s0, 9
	v_writelane_b32 v255, 9, 49
	s_cbranch_scc0 .Ltrip0_strict_8
	s_add_u32 s20, s16, 0x100
	s_addc_u32 s21, s17, 0
	s_add_i32 s0, 0, 0x10000
	s_cmpk_eq_i32 s53, 0x54
	s_cselect_b32 s25, s13, s21
	s_cselect_b32 s24, s12, s20
	s_cselect_b32 s23, s15, s52
	s_cselect_b32 s22, s14, s47
	s_add_i32 s1, 0, 0x14000
	v_add_u32_e32 v154, s0, v139
	v_add_u32_e32 v170, s1, v139
	ds_read_b128 v[142:145], v154
	ds_read_b128 v[146:149], v154 offset:1024
	ds_read_b128 v[150:153], v154 offset:2048
	ds_read_b128 v[154:157], v154 offset:3072
	ds_read_b128 v[158:161], v170
	ds_read_b128 v[162:165], v170 offset:1024
	ds_read_b128 v[166:169], v170 offset:2048
	ds_read_b128 v[170:173], v170 offset:3072
	v_lshl_add_u64 v[186:187], s[16:17], 0, v[134:135]
	s_add_i32 m0, s29, 0xc000
	ds_read_b128 v[174:177], v141
	ds_read_b128 v[178:181], v141 offset:1024
	ds_read_b128 v[182:185], v141 offset:2048
	ds_read_b128 v[196:199], v141 offset:3072
	ds_read_b128 v[200:203], v141 offset:4096
	ds_read_b128 v[204:207], v141 offset:5120
	ds_read_b128 v[208:211], v141 offset:6144
	ds_read_b128 v[212:215], v141 offset:7168
	global_load_lds_dwordx4 v[186:187], off
	v_lshl_add_u64 v[186:187], s[16:17], 0, v[136:137]
	s_add_i32 m0, s29, 0xe000
	s_nop 0
	global_load_lds_dwordx4 v[186:187], off
	s_waitcnt vmcnt(24)
	s_waitcnt lgkmcnt(0)
	s_barrier
	s_setprio 1
	s_waitcnt lgkmcnt(0)
	v_mfma_f32_16x16x32_bf16 v[124:127], v[142:145], v[174:177], 0
	v_mfma_f32_16x16x32_bf16 v[120:123], v[150:153], v[174:177], 0
	v_mfma_f32_16x16x32_bf16 v[116:119], v[142:145], v[182:185], 0
	v_mfma_f32_16x16x32_bf16 v[112:115], v[150:153], v[182:185], 0
	v_mfma_f32_16x16x32_bf16 v[100:103], v[142:145], v[200:203], 0
	v_mfma_f32_16x16x32_bf16 v[96:99], v[150:153], v[200:203], 0
	v_mfma_f32_16x16x32_bf16 v[84:87], v[142:145], v[208:211], 0
	v_mfma_f32_16x16x32_bf16 v[80:83], v[150:153], v[208:211], 0
	v_mfma_f32_16x16x32_bf16 v[124:127], v[146:149], v[178:181], v[124:127]
	v_mfma_f32_16x16x32_bf16 v[120:123], v[154:157], v[178:181], v[120:123]
	v_mfma_f32_16x16x32_bf16 v[116:119], v[146:149], v[196:199], v[116:119]
	v_mfma_f32_16x16x32_bf16 v[112:115], v[154:157], v[196:199], v[112:115]
	v_mfma_f32_16x16x32_bf16 v[100:103], v[146:149], v[204:207], v[100:103]
	v_mfma_f32_16x16x32_bf16 v[96:99], v[154:157], v[204:207], v[96:99]
	v_mfma_f32_16x16x32_bf16 v[84:87], v[146:149], v[212:215], v[84:87]
	v_mfma_f32_16x16x32_bf16 v[80:83], v[154:157], v[212:215], v[80:83]
	s_setprio 0
	s_setprio 1
	v_mfma_f32_16x16x32_bf16 v[108:111], v[158:161], v[174:177], 0
	v_mfma_f32_16x16x32_bf16 v[104:107], v[166:169], v[174:177], 0
	v_mfma_f32_16x16x32_bf16 v[92:95], v[158:161], v[182:185], 0
	v_mfma_f32_16x16x32_bf16 v[88:91], v[166:169], v[182:185], 0
	v_mfma_f32_16x16x32_bf16 v[76:79], v[158:161], v[200:203], 0
	v_mfma_f32_16x16x32_bf16 v[72:75], v[166:169], v[200:203], 0
	v_mfma_f32_16x16x32_bf16 v[68:71], v[158:161], v[208:211], 0
	v_mfma_f32_16x16x32_bf16 v[64:67], v[166:169], v[208:211], 0
	v_mfma_f32_16x16x32_bf16 v[108:111], v[162:165], v[178:181], v[108:111]
	v_mfma_f32_16x16x32_bf16 v[104:107], v[170:173], v[178:181], v[104:107]
	v_mfma_f32_16x16x32_bf16 v[92:95], v[162:165], v[196:199], v[92:95]
	v_mfma_f32_16x16x32_bf16 v[88:91], v[170:173], v[196:199], v[88:91]
	v_mfma_f32_16x16x32_bf16 v[76:79], v[162:165], v[204:207], v[76:79]
	v_mfma_f32_16x16x32_bf16 v[72:75], v[170:173], v[204:207], v[72:75]
	v_mfma_f32_16x16x32_bf16 v[68:71], v[162:165], v[212:215], v[68:71]
	v_mfma_f32_16x16x32_bf16 v[64:67], v[170:173], v[212:215], v[64:67]
	s_setprio 0
	s_barrier
	s_add_i32 s0, s0, s28
	v_lshl_add_u64 v[186:187], s[22:23], 0, v[190:191]
	s_mov_b32 m0, s0
	ds_read_b128 v[174:177], v141 offset:16384
	ds_read_b128 v[178:181], v141 offset:17408
	ds_read_b128 v[182:185], v141 offset:18432
	ds_read_b128 v[196:199], v141 offset:19456
	ds_read_b128 v[200:203], v141 offset:20480
	ds_read_b128 v[204:207], v141 offset:21504
	ds_read_b128 v[208:211], v141 offset:22528
	ds_read_b128 v[212:215], v141 offset:23552
	global_load_lds_dwordx4 v[186:187], off
	s_add_i32 m0, s0, 0x2000
	s_add_u32 s16, s22, 0x160000
	v_lshl_add_u64 v[216:217], s[22:23], 0, v[132:133]
	s_addc_u32 s17, s23, 0
	s_add_i32 s0, s1, s28
	global_load_lds_dwordx4 v[216:217], off
	v_lshl_add_u64 v[218:219], s[16:17], 0, v[190:191]
	s_mov_b32 m0, s0
	v_lshl_add_u64 v[220:221], s[24:25], 0, v[130:131]
	global_load_lds_dwordx4 v[218:219], off
	v_lshl_add_u64 v[218:219], s[16:17], 0, v[132:133]
	s_add_i32 m0, s0, 0x2000
	s_nop 0
	global_load_lds_dwordx4 v[218:219], off
	v_lshl_add_u64 v[218:219], s[24:25], 0, v[128:129]
	s_mov_b32 m0, s29
	s_nop 0
	global_load_lds_dwordx4 v[218:219], off
	s_mov_b32 m0, s30
	s_nop 0
	global_load_lds_dwordx4 v[220:221], off
	s_waitcnt vmcnt(24)
	s_waitcnt lgkmcnt(0)
	s_barrier
	s_setprio 1
	s_waitcnt lgkmcnt(0)
	v_mfma_f32_16x16x32_bf16 v[60:63], v[142:145], v[174:177], 0
	v_mfma_f32_16x16x32_bf16 v[56:59], v[150:153], v[174:177], 0
	v_mfma_f32_16x16x32_bf16 v[52:55], v[142:145], v[182:185], 0
	v_mfma_f32_16x16x32_bf16 v[48:51], v[150:153], v[182:185], 0
	v_mfma_f32_16x16x32_bf16 v[36:39], v[142:145], v[200:203], 0
	v_mfma_f32_16x16x32_bf16 v[32:35], v[150:153], v[200:203], 0
	v_mfma_f32_16x16x32_bf16 v[20:23], v[142:145], v[208:211], 0
	v_mfma_f32_16x16x32_bf16 v[16:19], v[150:153], v[208:211], 0
	v_mfma_f32_16x16x32_bf16 v[60:63], v[146:149], v[178:181], v[60:63]
	v_mfma_f32_16x16x32_bf16 v[56:59], v[154:157], v[178:181], v[56:59]
	v_mfma_f32_16x16x32_bf16 v[52:55], v[146:149], v[196:199], v[52:55]
	v_mfma_f32_16x16x32_bf16 v[48:51], v[154:157], v[196:199], v[48:51]
	v_mfma_f32_16x16x32_bf16 v[36:39], v[146:149], v[204:207], v[36:39]
	v_mfma_f32_16x16x32_bf16 v[32:35], v[154:157], v[204:207], v[32:35]
	v_mfma_f32_16x16x32_bf16 v[20:23], v[146:149], v[212:215], v[20:23]
	v_mfma_f32_16x16x32_bf16 v[16:19], v[154:157], v[212:215], v[16:19]
	s_setprio 0
	s_setprio 1
	v_mfma_f32_16x16x32_bf16 v[44:47], v[158:161], v[174:177], 0
	v_mfma_f32_16x16x32_bf16 v[40:43], v[166:169], v[174:177], 0
	v_mfma_f32_16x16x32_bf16 v[28:31], v[158:161], v[182:185], 0
	v_mfma_f32_16x16x32_bf16 v[24:27], v[166:169], v[182:185], 0
	v_mfma_f32_16x16x32_bf16 v[12:15], v[158:161], v[200:203], 0
	v_mfma_f32_16x16x32_bf16 v[8:11], v[166:169], v[200:203], 0
	v_mfma_f32_16x16x32_bf16 v[4:7], v[158:161], v[208:211], 0
	v_mfma_f32_16x16x32_bf16 v[0:3], v[166:169], v[208:211], 0
	v_mfma_f32_16x16x32_bf16 v[44:47], v[162:165], v[178:181], v[44:47]
	v_mfma_f32_16x16x32_bf16 v[40:43], v[170:173], v[178:181], v[40:43]
	v_mfma_f32_16x16x32_bf16 v[28:31], v[162:165], v[196:199], v[28:31]
	v_mfma_f32_16x16x32_bf16 v[24:27], v[170:173], v[196:199], v[24:27]
	v_mfma_f32_16x16x32_bf16 v[12:15], v[162:165], v[204:207], v[12:15]
	v_mfma_f32_16x16x32_bf16 v[8:11], v[170:173], v[204:207], v[8:11]
	v_mfma_f32_16x16x32_bf16 v[4:7], v[162:165], v[212:215], v[4:7]
	v_mfma_f32_16x16x32_bf16 v[0:3], v[170:173], v[212:215], v[0:3]
	s_setprio 0
	s_barrier
	s_add_i32 s0, 0, 0x18000
	s_add_i32 s1, 0, 0x1c000
	v_add_u32_e32 v154, s0, v139
	v_add_u32_e32 v170, s1, v139
	ds_read_b128 v[142:145], v154
	ds_read_b128 v[146:149], v154 offset:1024
	ds_read_b128 v[150:153], v154 offset:2048
	ds_read_b128 v[154:157], v154 offset:3072
	ds_read_b128 v[158:161], v170
	ds_read_b128 v[162:165], v170 offset:1024
	ds_read_b128 v[166:169], v170 offset:2048
	ds_read_b128 v[170:173], v170 offset:3072
	s_add_u32 s16, s24, 0x160000
	s_addc_u32 s17, s25, 0
	s_mov_b32 m0, s31
	v_lshl_add_u64 v[222:223], s[16:17], 0, v[128:129]
	ds_read_b128 v[174:177], v141 offset:32768
	ds_read_b128 v[178:181], v141 offset:33792
	ds_read_b128 v[182:185], v141 offset:34816
	ds_read_b128 v[196:199], v141 offset:35840
	ds_read_b128 v[200:203], v141 offset:36864
	ds_read_b128 v[204:207], v141 offset:37888
	ds_read_b128 v[208:211], v141 offset:38912
	ds_read_b128 v[212:215], v141 offset:39936
	global_load_lds_dwordx4 v[222:223], off
	v_lshl_add_u64 v[222:223], s[16:17], 0, v[130:131]
	s_mov_b32 m0, s33
	s_nop 0
	global_load_lds_dwordx4 v[222:223], off
	s_waitcnt vmcnt(8)
	s_waitcnt lgkmcnt(0)
	s_barrier
	s_setprio 1
	s_waitcnt lgkmcnt(0)
	v_mfma_f32_16x16x32_bf16 v[124:127], v[142:145], v[174:177], v[124:127]
	v_mfma_f32_16x16x32_bf16 v[120:123], v[150:153], v[174:177], v[120:123]
	v_mfma_f32_16x16x32_bf16 v[116:119], v[142:145], v[182:185], v[116:119]
	v_mfma_f32_16x16x32_bf16 v[112:115], v[150:153], v[182:185], v[112:115]
	v_mfma_f32_16x16x32_bf16 v[100:103], v[142:145], v[200:203], v[100:103]
	v_mfma_f32_16x16x32_bf16 v[96:99], v[150:153], v[200:203], v[96:99]
	v_mfma_f32_16x16x32_bf16 v[84:87], v[142:145], v[208:211], v[84:87]
	v_mfma_f32_16x16x32_bf16 v[80:83], v[150:153], v[208:211], v[80:83]
	v_mfma_f32_16x16x32_bf16 v[124:127], v[146:149], v[178:181], v[124:127]
	v_mfma_f32_16x16x32_bf16 v[120:123], v[154:157], v[178:181], v[120:123]
	v_mfma_f32_16x16x32_bf16 v[116:119], v[146:149], v[196:199], v[116:119]
	v_mfma_f32_16x16x32_bf16 v[112:115], v[154:157], v[196:199], v[112:115]
	v_mfma_f32_16x16x32_bf16 v[100:103], v[146:149], v[204:207], v[100:103]
	v_mfma_f32_16x16x32_bf16 v[96:99], v[154:157], v[204:207], v[96:99]
	v_mfma_f32_16x16x32_bf16 v[84:87], v[146:149], v[212:215], v[84:87]
	v_mfma_f32_16x16x32_bf16 v[80:83], v[154:157], v[212:215], v[80:83]
	s_setprio 0
	s_setprio 1
	v_mfma_f32_16x16x32_bf16 v[108:111], v[158:161], v[174:177], v[108:111]
	v_mfma_f32_16x16x32_bf16 v[104:107], v[166:169], v[174:177], v[104:107]
	v_mfma_f32_16x16x32_bf16 v[92:95], v[158:161], v[182:185], v[92:95]
	v_mfma_f32_16x16x32_bf16 v[88:91], v[166:169], v[182:185], v[88:91]
	v_mfma_f32_16x16x32_bf16 v[76:79], v[158:161], v[200:203], v[76:79]
	v_mfma_f32_16x16x32_bf16 v[72:75], v[166:169], v[200:203], v[72:75]
	v_mfma_f32_16x16x32_bf16 v[68:71], v[158:161], v[208:211], v[68:71]
	v_mfma_f32_16x16x32_bf16 v[64:67], v[166:169], v[208:211], v[64:67]
	v_mfma_f32_16x16x32_bf16 v[108:111], v[162:165], v[178:181], v[108:111]
	v_mfma_f32_16x16x32_bf16 v[104:107], v[170:173], v[178:181], v[104:107]
	v_mfma_f32_16x16x32_bf16 v[92:95], v[162:165], v[196:199], v[92:95]
	v_mfma_f32_16x16x32_bf16 v[88:91], v[170:173], v[196:199], v[88:91]
	v_mfma_f32_16x16x32_bf16 v[76:79], v[162:165], v[204:207], v[76:79]
	v_mfma_f32_16x16x32_bf16 v[72:75], v[170:173], v[204:207], v[72:75]
	v_mfma_f32_16x16x32_bf16 v[68:71], v[162:165], v[212:215], v[68:71]
	v_mfma_f32_16x16x32_bf16 v[64:67], v[170:173], v[212:215], v[64:67]
	s_setprio 0
	s_barrier
	s_add_i32 s0, s0, s28
	v_lshl_add_u64 v[186:187], v[186:187], 0, s[58:59]
	s_mov_b32 m0, s0
	ds_read_b128 v[174:177], v141 offset:49152
	ds_read_b128 v[178:181], v141 offset:50176
	ds_read_b128 v[182:185], v141 offset:51200
	ds_read_b128 v[196:199], v141 offset:52224
	ds_read_b128 v[200:203], v141 offset:53248
	ds_read_b128 v[204:207], v141 offset:54272
	ds_read_b128 v[208:211], v141 offset:55296
	ds_read_b128 v[212:215], v141 offset:56320
	global_load_lds_dwordx4 v[186:187], off
	s_add_i32 m0, s0, 0x2000
	s_add_u32 s16, s22, 0x160080
	v_lshl_add_u64 v[186:187], v[216:217], 0, s[58:59]
	s_addc_u32 s17, s23, 0
	s_add_i32 s0, s1, s28
	global_load_lds_dwordx4 v[186:187], off
	v_lshl_add_u64 v[186:187], s[16:17], 0, v[190:191]
	s_mov_b32 m0, s0
	s_nop 0
	global_load_lds_dwordx4 v[186:187], off
	v_lshl_add_u64 v[186:187], s[16:17], 0, v[132:133]
	s_add_i32 m0, s0, 0x2000
	s_nop 0
	global_load_lds_dwordx4 v[186:187], off
	v_lshl_add_u64 v[186:187], v[218:219], 0, s[58:59]
	s_mov_b32 m0, s37
	s_nop 0
	global_load_lds_dwordx4 v[186:187], off
	v_lshl_add_u64 v[186:187], v[220:221], 0, s[58:59]
	s_mov_b32 m0, s38
	s_nop 0
	global_load_lds_dwordx4 v[186:187], off
	s_waitcnt vmcnt(8)
	s_waitcnt lgkmcnt(0)
	s_barrier
	s_setprio 1
	s_waitcnt lgkmcnt(0)
	v_mfma_f32_16x16x32_bf16 v[60:63], v[142:145], v[174:177], v[60:63]
	v_mfma_f32_16x16x32_bf16 v[56:59], v[150:153], v[174:177], v[56:59]
	v_mfma_f32_16x16x32_bf16 v[52:55], v[142:145], v[182:185], v[52:55]
	v_mfma_f32_16x16x32_bf16 v[48:51], v[150:153], v[182:185], v[48:51]
	v_mfma_f32_16x16x32_bf16 v[36:39], v[142:145], v[200:203], v[36:39]
	v_mfma_f32_16x16x32_bf16 v[32:35], v[150:153], v[200:203], v[32:35]
	v_mfma_f32_16x16x32_bf16 v[20:23], v[142:145], v[208:211], v[20:23]
	v_mfma_f32_16x16x32_bf16 v[16:19], v[150:153], v[208:211], v[16:19]
	v_mfma_f32_16x16x32_bf16 v[60:63], v[146:149], v[178:181], v[60:63]
	v_mfma_f32_16x16x32_bf16 v[56:59], v[154:157], v[178:181], v[56:59]
	v_mfma_f32_16x16x32_bf16 v[52:55], v[146:149], v[196:199], v[52:55]
	v_mfma_f32_16x16x32_bf16 v[48:51], v[154:157], v[196:199], v[48:51]
	v_mfma_f32_16x16x32_bf16 v[36:39], v[146:149], v[204:207], v[36:39]
	v_mfma_f32_16x16x32_bf16 v[32:35], v[154:157], v[204:207], v[32:35]
	v_mfma_f32_16x16x32_bf16 v[20:23], v[146:149], v[212:215], v[20:23]
	v_mfma_f32_16x16x32_bf16 v[16:19], v[154:157], v[212:215], v[16:19]
	s_setprio 0
	s_setprio 1
	v_mfma_f32_16x16x32_bf16 v[44:47], v[158:161], v[174:177], v[44:47]
	v_mfma_f32_16x16x32_bf16 v[40:43], v[166:169], v[174:177], v[40:43]
	v_mfma_f32_16x16x32_bf16 v[28:31], v[158:161], v[182:185], v[28:31]
	v_mfma_f32_16x16x32_bf16 v[24:27], v[166:169], v[182:185], v[24:27]
	v_mfma_f32_16x16x32_bf16 v[12:15], v[158:161], v[200:203], v[12:15]
	v_mfma_f32_16x16x32_bf16 v[8:11], v[166:169], v[200:203], v[8:11]
	v_mfma_f32_16x16x32_bf16 v[4:7], v[158:161], v[208:211], v[4:7]
	v_mfma_f32_16x16x32_bf16 v[0:3], v[166:169], v[208:211], v[0:3]
	v_mfma_f32_16x16x32_bf16 v[44:47], v[162:165], v[178:181], v[44:47]
	v_mfma_f32_16x16x32_bf16 v[40:43], v[170:173], v[178:181], v[40:43]
	v_mfma_f32_16x16x32_bf16 v[28:31], v[162:165], v[196:199], v[28:31]
	v_mfma_f32_16x16x32_bf16 v[24:27], v[170:173], v[196:199], v[24:27]
	v_mfma_f32_16x16x32_bf16 v[12:15], v[162:165], v[204:207], v[12:15]
	v_mfma_f32_16x16x32_bf16 v[8:11], v[170:173], v[204:207], v[8:11]
	v_mfma_f32_16x16x32_bf16 v[4:7], v[162:165], v[212:215], v[4:7]
	v_mfma_f32_16x16x32_bf16 v[0:3], v[170:173], v[212:215], v[0:3]
	s_setprio 0
	s_barrier
	s_add_i32 s53, s53, 2
	s_add_u32 s47, s47, 0x100
	s_addc_u32 s52, s52, 0
	s_cmpk_gt_u32 s53, 0x55
	s_mov_b64 s[16:17], s[20:21]
	s_cbranch_scc1 .Lpeel_done_8
	s_branch .LBB0_1350
.Ltrip0_strict_8:
	s_add_u32 s20, s16, 0x100
	s_addc_u32 s21, s17, 0
	s_add_i32 s0, 0, 0x10000
	s_cmpk_eq_i32 s53, 0x54
	s_cselect_b32 s25, s13, s21
	s_cselect_b32 s24, s12, s20
	s_cselect_b32 s23, s15, s52
	s_cselect_b32 s22, s14, s47
	s_add_i32 s1, 0, 0x14000
	v_add_u32_e32 v154, s0, v139
	v_add_u32_e32 v170, s1, v139
	ds_read_b128 v[142:145], v154
	ds_read_b128 v[146:149], v154 offset:1024
	ds_read_b128 v[150:153], v154 offset:2048
	ds_read_b128 v[154:157], v154 offset:3072
	ds_read_b128 v[158:161], v170
	ds_read_b128 v[162:165], v170 offset:1024
	ds_read_b128 v[166:169], v170 offset:2048
	ds_read_b128 v[170:173], v170 offset:3072
	v_lshl_add_u64 v[186:187], s[16:17], 0, v[134:135]
	s_add_i32 m0, s29, 0xc000
	ds_read_b128 v[174:177], v141
	ds_read_b128 v[178:181], v141 offset:1024
	ds_read_b128 v[182:185], v141 offset:2048
	ds_read_b128 v[196:199], v141 offset:3072
	ds_read_b128 v[200:203], v141 offset:4096
	ds_read_b128 v[204:207], v141 offset:5120
	ds_read_b128 v[208:211], v141 offset:6144
	ds_read_b128 v[212:215], v141 offset:7168
	global_load_lds_dwordx4 v[186:187], off
	v_lshl_add_u64 v[186:187], s[16:17], 0, v[136:137]
	s_add_i32 m0, s29, 0xe000
	s_nop 0
	global_load_lds_dwordx4 v[186:187], off
	s_waitcnt vmcnt(8)
	s_waitcnt lgkmcnt(0)
	s_barrier
	s_setprio 1
	s_waitcnt lgkmcnt(0)
	v_mfma_f32_16x16x32_bf16 v[124:127], v[142:145], v[174:177], 0
	v_mfma_f32_16x16x32_bf16 v[120:123], v[150:153], v[174:177], 0
	v_mfma_f32_16x16x32_bf16 v[116:119], v[142:145], v[182:185], 0
	v_mfma_f32_16x16x32_bf16 v[112:115], v[150:153], v[182:185], 0
	v_mfma_f32_16x16x32_bf16 v[100:103], v[142:145], v[200:203], 0
	v_mfma_f32_16x16x32_bf16 v[96:99], v[150:153], v[200:203], 0
	v_mfma_f32_16x16x32_bf16 v[84:87], v[142:145], v[208:211], 0
	v_mfma_f32_16x16x32_bf16 v[80:83], v[150:153], v[208:211], 0
	v_mfma_f32_16x16x32_bf16 v[124:127], v[146:149], v[178:181], v[124:127]
	v_mfma_f32_16x16x32_bf16 v[120:123], v[154:157], v[178:181], v[120:123]
	v_mfma_f32_16x16x32_bf16 v[116:119], v[146:149], v[196:199], v[116:119]
	v_mfma_f32_16x16x32_bf16 v[112:115], v[154:157], v[196:199], v[112:115]
	v_mfma_f32_16x16x32_bf16 v[100:103], v[146:149], v[204:207], v[100:103]
	v_mfma_f32_16x16x32_bf16 v[96:99], v[154:157], v[204:207], v[96:99]
	v_mfma_f32_16x16x32_bf16 v[84:87], v[146:149], v[212:215], v[84:87]
	v_mfma_f32_16x16x32_bf16 v[80:83], v[154:157], v[212:215], v[80:83]
	s_setprio 0
	s_setprio 1
	v_mfma_f32_16x16x32_bf16 v[108:111], v[158:161], v[174:177], 0
	v_mfma_f32_16x16x32_bf16 v[104:107], v[166:169], v[174:177], 0
	v_mfma_f32_16x16x32_bf16 v[92:95], v[158:161], v[182:185], 0
	v_mfma_f32_16x16x32_bf16 v[88:91], v[166:169], v[182:185], 0
	v_mfma_f32_16x16x32_bf16 v[76:79], v[158:161], v[200:203], 0
	v_mfma_f32_16x16x32_bf16 v[72:75], v[166:169], v[200:203], 0
	v_mfma_f32_16x16x32_bf16 v[68:71], v[158:161], v[208:211], 0
	v_mfma_f32_16x16x32_bf16 v[64:67], v[166:169], v[208:211], 0
	v_mfma_f32_16x16x32_bf16 v[108:111], v[162:165], v[178:181], v[108:111]
	v_mfma_f32_16x16x32_bf16 v[104:107], v[170:173], v[178:181], v[104:107]
	v_mfma_f32_16x16x32_bf16 v[92:95], v[162:165], v[196:199], v[92:95]
	v_mfma_f32_16x16x32_bf16 v[88:91], v[170:173], v[196:199], v[88:91]
	v_mfma_f32_16x16x32_bf16 v[76:79], v[162:165], v[204:207], v[76:79]
	v_mfma_f32_16x16x32_bf16 v[72:75], v[170:173], v[204:207], v[72:75]
	v_mfma_f32_16x16x32_bf16 v[68:71], v[162:165], v[212:215], v[68:71]
	v_mfma_f32_16x16x32_bf16 v[64:67], v[170:173], v[212:215], v[64:67]
	s_setprio 0
	s_barrier
	s_add_i32 s0, s0, s28
	v_lshl_add_u64 v[186:187], s[22:23], 0, v[190:191]
	s_mov_b32 m0, s0
	ds_read_b128 v[174:177], v141 offset:16384
	ds_read_b128 v[178:181], v141 offset:17408
	ds_read_b128 v[182:185], v141 offset:18432
	ds_read_b128 v[196:199], v141 offset:19456
	ds_read_b128 v[200:203], v141 offset:20480
	ds_read_b128 v[204:207], v141 offset:21504
	ds_read_b128 v[208:211], v141 offset:22528
	ds_read_b128 v[212:215], v141 offset:23552
	global_load_lds_dwordx4 v[186:187], off
	s_add_i32 m0, s0, 0x2000
	s_add_u32 s16, s22, 0x160000
	v_lshl_add_u64 v[216:217], s[22:23], 0, v[132:133]
	s_addc_u32 s17, s23, 0
	s_add_i32 s0, s1, s28
	global_load_lds_dwordx4 v[216:217], off
	v_lshl_add_u64 v[218:219], s[16:17], 0, v[190:191]
	s_mov_b32 m0, s0
	v_lshl_add_u64 v[220:221], s[24:25], 0, v[130:131]
	global_load_lds_dwordx4 v[218:219], off
	v_lshl_add_u64 v[218:219], s[16:17], 0, v[132:133]
	s_add_i32 m0, s0, 0x2000
	s_nop 0
	global_load_lds_dwordx4 v[218:219], off
	v_lshl_add_u64 v[218:219], s[24:25], 0, v[128:129]
	s_mov_b32 m0, s29
	s_nop 0
	global_load_lds_dwordx4 v[218:219], off
	s_mov_b32 m0, s30
	s_nop 0
	global_load_lds_dwordx4 v[220:221], off
	s_waitcnt vmcnt(8)
	s_waitcnt lgkmcnt(0)
	s_barrier
	s_setprio 1
	s_waitcnt lgkmcnt(0)
	v_mfma_f32_16x16x32_bf16 v[60:63], v[142:145], v[174:177], 0
	v_mfma_f32_16x16x32_bf16 v[56:59], v[150:153], v[174:177], 0
	v_mfma_f32_16x16x32_bf16 v[52:55], v[142:145], v[182:185], 0
	v_mfma_f32_16x16x32_bf16 v[48:51], v[150:153], v[182:185], 0
	v_mfma_f32_16x16x32_bf16 v[36:39], v[142:145], v[200:203], 0
	v_mfma_f32_16x16x32_bf16 v[32:35], v[150:153], v[200:203], 0
	v_mfma_f32_16x16x32_bf16 v[20:23], v[142:145], v[208:211], 0
	v_mfma_f32_16x16x32_bf16 v[16:19], v[150:153], v[208:211], 0
	v_mfma_f32_16x16x32_bf16 v[60:63], v[146:149], v[178:181], v[60:63]
	v_mfma_f32_16x16x32_bf16 v[56:59], v[154:157], v[178:181], v[56:59]
	v_mfma_f32_16x16x32_bf16 v[52:55], v[146:149], v[196:199], v[52:55]
	v_mfma_f32_16x16x32_bf16 v[48:51], v[154:157], v[196:199], v[48:51]
	v_mfma_f32_16x16x32_bf16 v[36:39], v[146:149], v[204:207], v[36:39]
	v_mfma_f32_16x16x32_bf16 v[32:35], v[154:157], v[204:207], v[32:35]
	v_mfma_f32_16x16x32_bf16 v[20:23], v[146:149], v[212:215], v[20:23]
	v_mfma_f32_16x16x32_bf16 v[16:19], v[154:157], v[212:215], v[16:19]
	s_setprio 0
	s_setprio 1
	v_mfma_f32_16x16x32_bf16 v[44:47], v[158:161], v[174:177], 0
	v_mfma_f32_16x16x32_bf16 v[40:43], v[166:169], v[174:177], 0
	v_mfma_f32_16x16x32_bf16 v[28:31], v[158:161], v[182:185], 0
	v_mfma_f32_16x16x32_bf16 v[24:27], v[166:169], v[182:185], 0
	v_mfma_f32_16x16x32_bf16 v[12:15], v[158:161], v[200:203], 0
	v_mfma_f32_16x16x32_bf16 v[8:11], v[166:169], v[200:203], 0
	v_mfma_f32_16x16x32_bf16 v[4:7], v[158:161], v[208:211], 0
	v_mfma_f32_16x16x32_bf16 v[0:3], v[166:169], v[208:211], 0
	v_mfma_f32_16x16x32_bf16 v[44:47], v[162:165], v[178:181], v[44:47]
	v_mfma_f32_16x16x32_bf16 v[40:43], v[170:173], v[178:181], v[40:43]
	v_mfma_f32_16x16x32_bf16 v[28:31], v[162:165], v[196:199], v[28:31]
	v_mfma_f32_16x16x32_bf16 v[24:27], v[170:173], v[196:199], v[24:27]
	v_mfma_f32_16x16x32_bf16 v[12:15], v[162:165], v[204:207], v[12:15]
	v_mfma_f32_16x16x32_bf16 v[8:11], v[170:173], v[204:207], v[8:11]
	v_mfma_f32_16x16x32_bf16 v[4:7], v[162:165], v[212:215], v[4:7]
	v_mfma_f32_16x16x32_bf16 v[0:3], v[170:173], v[212:215], v[0:3]
	s_setprio 0
	s_barrier
	s_add_i32 s0, 0, 0x18000
	s_add_i32 s1, 0, 0x1c000
	v_add_u32_e32 v154, s0, v139
	v_add_u32_e32 v170, s1, v139
	ds_read_b128 v[142:145], v154
	ds_read_b128 v[146:149], v154 offset:1024
	ds_read_b128 v[150:153], v154 offset:2048
	ds_read_b128 v[154:157], v154 offset:3072
	ds_read_b128 v[158:161], v170
	ds_read_b128 v[162:165], v170 offset:1024
	ds_read_b128 v[166:169], v170 offset:2048
	ds_read_b128 v[170:173], v170 offset:3072
	s_add_u32 s16, s24, 0x160000
	s_addc_u32 s17, s25, 0
	s_mov_b32 m0, s31
	v_lshl_add_u64 v[222:223], s[16:17], 0, v[128:129]
	ds_read_b128 v[174:177], v141 offset:32768
	ds_read_b128 v[178:181], v141 offset:33792
	ds_read_b128 v[182:185], v141 offset:34816
	ds_read_b128 v[196:199], v141 offset:35840
	ds_read_b128 v[200:203], v141 offset:36864
	ds_read_b128 v[204:207], v141 offset:37888
	ds_read_b128 v[208:211], v141 offset:38912
	ds_read_b128 v[212:215], v141 offset:39936
	global_load_lds_dwordx4 v[222:223], off
	v_lshl_add_u64 v[222:223], s[16:17], 0, v[130:131]
	s_mov_b32 m0, s33
	s_nop 0
	global_load_lds_dwordx4 v[222:223], off
	s_waitcnt vmcnt(8)
	s_waitcnt lgkmcnt(0)
	s_barrier
	s_setprio 1
	s_waitcnt lgkmcnt(0)
	v_mfma_f32_16x16x32_bf16 v[124:127], v[142:145], v[174:177], v[124:127]
	v_mfma_f32_16x16x32_bf16 v[120:123], v[150:153], v[174:177], v[120:123]
	v_mfma_f32_16x16x32_bf16 v[116:119], v[142:145], v[182:185], v[116:119]
	v_mfma_f32_16x16x32_bf16 v[112:115], v[150:153], v[182:185], v[112:115]
	v_mfma_f32_16x16x32_bf16 v[100:103], v[142:145], v[200:203], v[100:103]
	v_mfma_f32_16x16x32_bf16 v[96:99], v[150:153], v[200:203], v[96:99]
	v_mfma_f32_16x16x32_bf16 v[84:87], v[142:145], v[208:211], v[84:87]
	v_mfma_f32_16x16x32_bf16 v[80:83], v[150:153], v[208:211], v[80:83]
	v_mfma_f32_16x16x32_bf16 v[124:127], v[146:149], v[178:181], v[124:127]
	v_mfma_f32_16x16x32_bf16 v[120:123], v[154:157], v[178:181], v[120:123]
	v_mfma_f32_16x16x32_bf16 v[116:119], v[146:149], v[196:199], v[116:119]
	v_mfma_f32_16x16x32_bf16 v[112:115], v[154:157], v[196:199], v[112:115]
	v_mfma_f32_16x16x32_bf16 v[100:103], v[146:149], v[204:207], v[100:103]
	v_mfma_f32_16x16x32_bf16 v[96:99], v[154:157], v[204:207], v[96:99]
	v_mfma_f32_16x16x32_bf16 v[84:87], v[146:149], v[212:215], v[84:87]
	v_mfma_f32_16x16x32_bf16 v[80:83], v[154:157], v[212:215], v[80:83]
	s_setprio 0
	s_setprio 1
	v_mfma_f32_16x16x32_bf16 v[108:111], v[158:161], v[174:177], v[108:111]
	v_mfma_f32_16x16x32_bf16 v[104:107], v[166:169], v[174:177], v[104:107]
	v_mfma_f32_16x16x32_bf16 v[92:95], v[158:161], v[182:185], v[92:95]
	v_mfma_f32_16x16x32_bf16 v[88:91], v[166:169], v[182:185], v[88:91]
	v_mfma_f32_16x16x32_bf16 v[76:79], v[158:161], v[200:203], v[76:79]
	v_mfma_f32_16x16x32_bf16 v[72:75], v[166:169], v[200:203], v[72:75]
	v_mfma_f32_16x16x32_bf16 v[68:71], v[158:161], v[208:211], v[68:71]
	v_mfma_f32_16x16x32_bf16 v[64:67], v[166:169], v[208:211], v[64:67]
	v_mfma_f32_16x16x32_bf16 v[108:111], v[162:165], v[178:181], v[108:111]
	v_mfma_f32_16x16x32_bf16 v[104:107], v[170:173], v[178:181], v[104:107]
	v_mfma_f32_16x16x32_bf16 v[92:95], v[162:165], v[196:199], v[92:95]
	v_mfma_f32_16x16x32_bf16 v[88:91], v[170:173], v[196:199], v[88:91]
	v_mfma_f32_16x16x32_bf16 v[76:79], v[162:165], v[204:207], v[76:79]
	v_mfma_f32_16x16x32_bf16 v[72:75], v[170:173], v[204:207], v[72:75]
	v_mfma_f32_16x16x32_bf16 v[68:71], v[162:165], v[212:215], v[68:71]
	v_mfma_f32_16x16x32_bf16 v[64:67], v[170:173], v[212:215], v[64:67]
	s_setprio 0
	s_barrier
	s_add_i32 s0, s0, s28
	v_lshl_add_u64 v[186:187], v[186:187], 0, s[58:59]
	s_mov_b32 m0, s0
	ds_read_b128 v[174:177], v141 offset:49152
	ds_read_b128 v[178:181], v141 offset:50176
	ds_read_b128 v[182:185], v141 offset:51200
	ds_read_b128 v[196:199], v141 offset:52224
	ds_read_b128 v[200:203], v141 offset:53248
	ds_read_b128 v[204:207], v141 offset:54272
	ds_read_b128 v[208:211], v141 offset:55296
	ds_read_b128 v[212:215], v141 offset:56320
	global_load_lds_dwordx4 v[186:187], off
	s_add_i32 m0, s0, 0x2000
	s_add_u32 s16, s22, 0x160080
	v_lshl_add_u64 v[186:187], v[216:217], 0, s[58:59]
	s_addc_u32 s17, s23, 0
	s_add_i32 s0, s1, s28
	global_load_lds_dwordx4 v[186:187], off
	v_lshl_add_u64 v[186:187], s[16:17], 0, v[190:191]
	s_mov_b32 m0, s0
	s_nop 0
	global_load_lds_dwordx4 v[186:187], off
	v_lshl_add_u64 v[186:187], s[16:17], 0, v[132:133]
	s_add_i32 m0, s0, 0x2000
	s_nop 0
	global_load_lds_dwordx4 v[186:187], off
	v_lshl_add_u64 v[186:187], v[218:219], 0, s[58:59]
	s_mov_b32 m0, s37
	s_nop 0
	global_load_lds_dwordx4 v[186:187], off
	v_lshl_add_u64 v[186:187], v[220:221], 0, s[58:59]
	s_mov_b32 m0, s38
	s_nop 0
	global_load_lds_dwordx4 v[186:187], off
	s_waitcnt vmcnt(8)
	s_waitcnt lgkmcnt(0)
	s_barrier
	s_setprio 1
	s_waitcnt lgkmcnt(0)
	v_mfma_f32_16x16x32_bf16 v[60:63], v[142:145], v[174:177], v[60:63]
	v_mfma_f32_16x16x32_bf16 v[56:59], v[150:153], v[174:177], v[56:59]
	v_mfma_f32_16x16x32_bf16 v[52:55], v[142:145], v[182:185], v[52:55]
	v_mfma_f32_16x16x32_bf16 v[48:51], v[150:153], v[182:185], v[48:51]
	v_mfma_f32_16x16x32_bf16 v[36:39], v[142:145], v[200:203], v[36:39]
	v_mfma_f32_16x16x32_bf16 v[32:35], v[150:153], v[200:203], v[32:35]
	v_mfma_f32_16x16x32_bf16 v[20:23], v[142:145], v[208:211], v[20:23]
	v_mfma_f32_16x16x32_bf16 v[16:19], v[150:153], v[208:211], v[16:19]
	v_mfma_f32_16x16x32_bf16 v[60:63], v[146:149], v[178:181], v[60:63]
	v_mfma_f32_16x16x32_bf16 v[56:59], v[154:157], v[178:181], v[56:59]
	v_mfma_f32_16x16x32_bf16 v[52:55], v[146:149], v[196:199], v[52:55]
	v_mfma_f32_16x16x32_bf16 v[48:51], v[154:157], v[196:199], v[48:51]
	v_mfma_f32_16x16x32_bf16 v[36:39], v[146:149], v[204:207], v[36:39]
	v_mfma_f32_16x16x32_bf16 v[32:35], v[154:157], v[204:207], v[32:35]
	v_mfma_f32_16x16x32_bf16 v[20:23], v[146:149], v[212:215], v[20:23]
	v_mfma_f32_16x16x32_bf16 v[16:19], v[154:157], v[212:215], v[16:19]
	s_setprio 0
	s_setprio 1
	v_mfma_f32_16x16x32_bf16 v[44:47], v[158:161], v[174:177], v[44:47]
	v_mfma_f32_16x16x32_bf16 v[40:43], v[166:169], v[174:177], v[40:43]
	v_mfma_f32_16x16x32_bf16 v[28:31], v[158:161], v[182:185], v[28:31]
	v_mfma_f32_16x16x32_bf16 v[24:27], v[166:169], v[182:185], v[24:27]
	v_mfma_f32_16x16x32_bf16 v[12:15], v[158:161], v[200:203], v[12:15]
	v_mfma_f32_16x16x32_bf16 v[8:11], v[166:169], v[200:203], v[8:11]
	v_mfma_f32_16x16x32_bf16 v[4:7], v[158:161], v[208:211], v[4:7]
	v_mfma_f32_16x16x32_bf16 v[0:3], v[166:169], v[208:211], v[0:3]
	v_mfma_f32_16x16x32_bf16 v[44:47], v[162:165], v[178:181], v[44:47]
	v_mfma_f32_16x16x32_bf16 v[40:43], v[170:173], v[178:181], v[40:43]
	v_mfma_f32_16x16x32_bf16 v[28:31], v[162:165], v[196:199], v[28:31]
	v_mfma_f32_16x16x32_bf16 v[24:27], v[170:173], v[196:199], v[24:27]
	v_mfma_f32_16x16x32_bf16 v[12:15], v[162:165], v[204:207], v[12:15]
	v_mfma_f32_16x16x32_bf16 v[8:11], v[170:173], v[204:207], v[8:11]
	v_mfma_f32_16x16x32_bf16 v[4:7], v[162:165], v[212:215], v[4:7]
	v_mfma_f32_16x16x32_bf16 v[0:3], v[170:173], v[212:215], v[0:3]
	s_setprio 0
	s_barrier
	s_add_i32 s53, s53, 2
	s_add_u32 s47, s47, 0x100
	s_addc_u32 s52, s52, 0
	s_cmpk_gt_u32 s53, 0x55
	s_mov_b64 s[16:17], s[20:21]
	s_cbranch_scc1 .Lpeel_done_8

.Lpeel_done_8:
	s_and_b64 vcc, exec, s[8:9]
	s_cbranch_vccz .LBB0_1353
	s_barrier
